# plus units after an epilogue run K-tile 0 without the two counted vmcnt waits (epilogue already drained the prefetch; avoids waiting on the epilogue stores for two segments)
# speedup vs baseline: 1.0004x; 1.0001x over previous
; #define LAS __attribute__((address_space(3)))
;     __device__ __forceinline__ const float* in(int i) const { return (const float*)(const __attribute__((address_space(1))) float*)get(i); }
;     __device__ __forceinline__ float* out() const { return (float*)(__attribute__((address_space(1))) float*)get(34); }
;     __device__ __forceinline__ unsigned char* ws() const { return (unsigned char*)(__attribute__((address_space(1))) unsigned char*)get(35); }
; __global__ void __launch_bounds__(512, 2) mega_fwd(Args args) {
;     extern __shared__ __attribute__((aligned(16))) unsigned char lds[];
;     LAS unsigned char* ldsL = (LAS unsigned char*)lds;
;     const int Ggemm = (int)gridDim.x, Gthin = Ggemm < THIN_GRID ? Ggemm : THIN_GRID;
;     const int bid0 = blockIdx.x, G0 = gridDim.x, wave_s = __builtin_amdgcn_readfirstlane((int)threadIdx.x >> 6);
;     volatile LAS unsigned* MISC = (volatile LAS unsigned*)(ldsL + MISC_OFF);
;     PA a; a.tab = MISC + 64;
;     ...
;     if (threadIdx.x < 64) MISC[threadIdx.x] = 0u;
;     ...
;     if (threadIdx.x == 64) {
; #pragma unroll
;         for (int i = 0; i < 34; ++i) { const unsigned long long v = (unsigned long long)args.in[i]; a.tab[2 * i] = (unsigned)v; a.tab[2 * i + 1] = (unsigned)(v >> 32); }
;         { const unsigned long long v = (unsigned long long)args.out; a.tab[68] = (unsigned)v; a.tab[69] = (unsigned)(v >> 32); }
;         { const unsigned long long v = (unsigned long long)args.ws; a.tab[70] = (unsigned)v; a.tab[71] = (unsigned)(v >> 32); }
;     }
_Z8mega_fwd4Args:
	s_mov_b32 s100, 0
	s_mov_b32 s101, 0
	s_load_dword s87, s[0:1], 0x128
	s_add_u32 s82, s0, 0x128
	s_mov_b32 s81, s2
	s_addc_u32 s83, s1, 0
	v_readfirstlane_b32 s20, v0
	v_cmp_gt_u32_e32 vcc, 64, v0
	s_and_saveexec_b64 s[2:3], vcc
	v_lshl_add_u32 v1, v0, 2, 0
	v_add_u32_e32 v1, 0x20000, v1
	v_mov_b32_e32 v2, 0
	ds_write_b32 v1, v2
	s_or_b64 exec, exec, s[2:3]
	v_cmp_eq_u32_e32 vcc, 64, v0
	s_and_saveexec_b64 s[2:3], vcc
	s_cbranch_execz .LBB0_4
	s_load_dwordx8 s[12:19], s[0:1], 0x0
	s_load_dwordx8 s[4:11], s[0:1], 0x20
	s_add_i32 s21, 0, 0x20100
	s_add_i32 s22, 0, 0x20104
	v_mov_b32_e32 v1, s21
	s_waitcnt lgkmcnt(0)
	v_mov_b32_e32 v2, s12
	ds_write_b32 v1, v2
	v_mov_b32_e32 v1, s22
	v_mov_b32_e32 v2, s13
	s_add_i32 s12, 0, 0x20108
	ds_write_b32 v1, v2
	v_mov_b32_e32 v1, s12
	v_mov_b32_e32 v2, s14
	s_add_i32 s12, 0, 0x2010c
	ds_write_b32 v1, v2
	v_mov_b32_e32 v1, s12
	v_mov_b32_e32 v2, s15
	s_add_i32 s12, 0, 0x20110
	ds_write_b32 v1, v2
	v_mov_b32_e32 v1, s12
	v_mov_b32_e32 v2, s16
	s_add_i32 s12, 0, 0x20114
	ds_write_b32 v1, v2
	v_mov_b32_e32 v1, s12
	v_mov_b32_e32 v2, s17
	s_add_i32 s12, 0, 0x20118
	ds_write_b32 v1, v2
	v_mov_b32_e32 v1, s12
	v_mov_b32_e32 v2, s18
	s_add_i32 s12, 0, 0x2011c
	ds_write_b32 v1, v2
	v_mov_b32_e32 v1, s12
	v_mov_b32_e32 v2, s19
	s_add_i32 s12, 0, 0x20120
	ds_write_b32 v1, v2
	v_mov_b32_e32 v1, s12
	v_mov_b32_e32 v2, s4
	s_add_i32 s4, 0, 0x20124
	ds_write_b32 v1, v2
	v_mov_b32_e32 v1, s4
	v_mov_b32_e32 v2, s5
	s_add_i32 s4, 0, 0x20128
	ds_write_b32 v1, v2
	v_mov_b32_e32 v1, s4
	v_mov_b32_e32 v2, s6
	s_add_i32 s4, 0, 0x2012c
	ds_write_b32 v1, v2
	v_mov_b32_e32 v1, s4
	v_mov_b32_e32 v2, s7
	s_add_i32 s4, 0, 0x20130
	ds_write_b32 v1, v2
	v_mov_b32_e32 v1, s4
	v_mov_b32_e32 v2, s8
	s_add_i32 s4, 0, 0x20134
	ds_write_b32 v1, v2
	v_mov_b32_e32 v1, s4
	v_mov_b32_e32 v2, s9
	s_add_i32 s4, 0, 0x20138
	ds_write_b32 v1, v2
	v_mov_b32_e32 v1, s4
	v_mov_b32_e32 v2, s10
	s_add_i32 s4, 0, 0x2013c
	ds_write_b32 v1, v2
	v_mov_b32_e32 v1, s4
	s_load_dwordx2 s[4:5], s[0:1], 0x40
	v_mov_b32_e32 v2, s11
	ds_write_b32 v1, v2
	s_add_i32 s6, 0, 0x20140
	v_mov_b32_e32 v1, s6
	s_load_dwordx2 s[6:7], s[0:1], 0x48
	s_load_dwordx2 s[8:9], s[0:1], 0x50
	s_load_dwordx2 s[10:11], s[0:1], 0x58
	s_waitcnt lgkmcnt(0)
	v_mov_b32_e32 v2, s4
	s_add_i32 s4, 0, 0x20144
	ds_write_b32 v1, v2
	v_mov_b32_e32 v1, s4
	v_mov_b32_e32 v2, s5
	s_add_i32 s4, 0, 0x20148
	ds_write_b32 v1, v2
	v_mov_b32_e32 v1, s4
	v_mov_b32_e32 v2, s6
	s_add_i32 s4, 0, 0x2014c
	ds_write_b32 v1, v2
	v_mov_b32_e32 v1, s4
	v_mov_b32_e32 v2, s7
	s_add_i32 s4, 0, 0x20150
	ds_write_b32 v1, v2
	v_mov_b32_e32 v1, s4
	v_mov_b32_e32 v2, s8
	s_add_i32 s4, 0, 0x20154
	ds_write_b32 v1, v2
	v_mov_b32_e32 v1, s4
	v_mov_b32_e32 v2, s9
	s_add_i32 s4, 0, 0x20158
	ds_write_b32 v1, v2
	v_mov_b32_e32 v1, s4
	v_mov_b32_e32 v2, s10
	s_add_i32 s4, 0, 0x2015c
	ds_write_b32 v1, v2
	v_mov_b32_e32 v1, s4
	s_load_dwordx2 s[4:5], s[0:1], 0x60
	v_mov_b32_e32 v2, s11
	ds_write_b32 v1, v2
	s_add_i32 s6, 0, 0x20160
	v_mov_b32_e32 v1, s6
	s_load_dwordx2 s[6:7], s[0:1], 0x68
	s_load_dwordx2 s[8:9], s[0:1], 0x70
	s_load_dwordx2 s[10:11], s[0:1], 0x78
	s_waitcnt lgkmcnt(0)
	v_mov_b32_e32 v2, s4
	s_add_i32 s4, 0, 0x20164
	ds_write_b32 v1, v2
	v_mov_b32_e32 v1, s4
	v_mov_b32_e32 v2, s5
	s_add_i32 s4, 0, 0x20168
	ds_write_b32 v1, v2
	v_mov_b32_e32 v1, s4
	v_mov_b32_e32 v2, s6
	s_add_i32 s4, 0, 0x2016c
	ds_write_b32 v1, v2
	v_mov_b32_e32 v1, s4
	v_mov_b32_e32 v2, s7
	s_add_i32 s4, 0, 0x20170
	ds_write_b32 v1, v2
	v_mov_b32_e32 v1, s4
	v_mov_b32_e32 v2, s8
	s_add_i32 s4, 0, 0x20174
	ds_write_b32 v1, v2
	v_mov_b32_e32 v1, s4
	v_mov_b32_e32 v2, s9
	s_add_i32 s4, 0, 0x20178
	ds_write_b32 v1, v2
	v_mov_b32_e32 v1, s4
	v_mov_b32_e32 v2, s10
	s_add_i32 s4, 0, 0x2017c
	ds_write_b32 v1, v2
	v_mov_b32_e32 v1, s4
	s_load_dwordx2 s[4:5], s[0:1], 0x80
	v_mov_b32_e32 v2, s11
	ds_write_b32 v1, v2
	s_add_i32 s6, 0, 0x20180
	v_mov_b32_e32 v1, s6
	s_load_dwordx2 s[6:7], s[0:1], 0x88
	s_load_dwordx2 s[8:9], s[0:1], 0x90
	s_load_dwordx2 s[10:11], s[0:1], 0x98
	s_waitcnt lgkmcnt(0)
;     __device__ __forceinline__ const float* in(int i) const { return (const float*)(const __attribute__((address_space(1))) float*)get(i); }
;     __device__ __forceinline__ float* out() const { return (float*)(__attribute__((address_space(1))) float*)get(34); }
;     __device__ __forceinline__ unsigned char* ws() const { return (unsigned char*)(__attribute__((address_space(1))) unsigned char*)get(35); }
; __global__ void __launch_bounds__(512, 2) mega_fwd(Args args) {
;     ...
;     if (threadIdx.x == 64) {
; #pragma unroll
;         for (int i = 0; i < 34; ++i) { const unsigned long long v = (unsigned long long)args.in[i]; a.tab[2 * i] = (unsigned)v; a.tab[2 * i + 1] = (unsigned)(v >> 32); }
;         { const unsigned long long v = (unsigned long long)args.out; a.tab[68] = (unsigned)v; a.tab[69] = (unsigned)(v >> 32); }
;         { const unsigned long long v = (unsigned long long)args.ws; a.tab[70] = (unsigned)v; a.tab[71] = (unsigned)(v >> 32); }
;     }
	v_mov_b32_e32 v2, s4
	s_add_i32 s4, 0, 0x20184
	ds_write_b32 v1, v2
	v_mov_b32_e32 v1, s4
	v_mov_b32_e32 v2, s5
	s_add_i32 s4, 0, 0x20188
	ds_write_b32 v1, v2
	v_mov_b32_e32 v1, s4
	v_mov_b32_e32 v2, s6
	s_add_i32 s4, 0, 0x2018c
	ds_write_b32 v1, v2
	v_mov_b32_e32 v1, s4
	v_mov_b32_e32 v2, s7
	s_add_i32 s4, 0, 0x20190
	ds_write_b32 v1, v2
	v_mov_b32_e32 v1, s4
	v_mov_b32_e32 v2, s8
	s_add_i32 s4, 0, 0x20194
	ds_write_b32 v1, v2
	v_mov_b32_e32 v1, s4
	v_mov_b32_e32 v2, s9
	s_add_i32 s4, 0, 0x20198
	ds_write_b32 v1, v2
	v_mov_b32_e32 v1, s4
	v_mov_b32_e32 v2, s10
	s_add_i32 s4, 0, 0x2019c
	ds_write_b32 v1, v2
	v_mov_b32_e32 v1, s4
	s_load_dwordx2 s[4:5], s[0:1], 0xa0
	v_mov_b32_e32 v2, s11
	ds_write_b32 v1, v2
	s_add_i32 s6, 0, 0x201a0
	v_mov_b32_e32 v1, s6
	s_load_dwordx2 s[6:7], s[0:1], 0xa8
	s_load_dwordx2 s[8:9], s[0:1], 0xb0
	s_load_dwordx2 s[10:11], s[0:1], 0xb8
	s_waitcnt lgkmcnt(0)
	v_mov_b32_e32 v2, s4
	s_add_i32 s4, 0, 0x201a4
	ds_write_b32 v1, v2
	v_mov_b32_e32 v1, s4
	v_mov_b32_e32 v2, s5
	s_add_i32 s4, 0, 0x201a8
	ds_write_b32 v1, v2
	v_mov_b32_e32 v1, s4
	v_mov_b32_e32 v2, s6
	s_add_i32 s4, 0, 0x201ac
	ds_write_b32 v1, v2
	v_mov_b32_e32 v1, s4
	v_mov_b32_e32 v2, s7
	s_add_i32 s4, 0, 0x201b0
	ds_write_b32 v1, v2
	v_mov_b32_e32 v1, s4
	v_mov_b32_e32 v2, s8
	s_add_i32 s4, 0, 0x201b4
	ds_write_b32 v1, v2
	v_mov_b32_e32 v1, s4
	v_mov_b32_e32 v2, s9
	s_add_i32 s4, 0, 0x201b8
	ds_write_b32 v1, v2
	v_mov_b32_e32 v1, s4
	v_mov_b32_e32 v2, s10
	s_add_i32 s4, 0, 0x201bc
	ds_write_b32 v1, v2
	v_mov_b32_e32 v1, s4
	s_load_dwordx2 s[4:5], s[0:1], 0xc0
	v_mov_b32_e32 v2, s11
	ds_write_b32 v1, v2
	s_add_i32 s6, 0, 0x201c0
	v_mov_b32_e32 v1, s6
	s_load_dwordx2 s[6:7], s[0:1], 0xc8
	s_load_dwordx2 s[8:9], s[0:1], 0xd0
	s_load_dwordx2 s[10:11], s[0:1], 0xd8
	s_waitcnt lgkmcnt(0)
	v_mov_b32_e32 v2, s4
	s_add_i32 s4, 0, 0x201c4
	ds_write_b32 v1, v2
	v_mov_b32_e32 v1, s4
	v_mov_b32_e32 v2, s5
	s_add_i32 s4, 0, 0x201c8
	ds_write_b32 v1, v2
	v_mov_b32_e32 v1, s4
	v_mov_b32_e32 v2, s6
	s_add_i32 s4, 0, 0x201cc
	ds_write_b32 v1, v2
	v_mov_b32_e32 v1, s4
	v_mov_b32_e32 v2, s7
	s_add_i32 s4, 0, 0x201d0
	ds_write_b32 v1, v2
	v_mov_b32_e32 v1, s4
	v_mov_b32_e32 v2, s8
	s_add_i32 s4, 0, 0x201d4
	ds_write_b32 v1, v2
	v_mov_b32_e32 v1, s4
	v_mov_b32_e32 v2, s9
	s_add_i32 s4, 0, 0x201d8
	ds_write_b32 v1, v2
	v_mov_b32_e32 v1, s4
	v_mov_b32_e32 v2, s10
	s_add_i32 s4, 0, 0x201dc
	ds_write_b32 v1, v2
	v_mov_b32_e32 v1, s4
	s_load_dwordx2 s[4:5], s[0:1], 0xe0
	v_mov_b32_e32 v2, s11
	ds_write_b32 v1, v2
	s_add_i32 s6, 0, 0x201e0
	v_mov_b32_e32 v1, s6
	s_load_dwordx2 s[6:7], s[0:1], 0xe8
	s_load_dwordx2 s[8:9], s[0:1], 0xf0
	s_load_dwordx2 s[10:11], s[0:1], 0xf8
	s_waitcnt lgkmcnt(0)
	v_mov_b32_e32 v2, s4
	s_add_i32 s4, 0, 0x201e4
	ds_write_b32 v1, v2
	v_mov_b32_e32 v1, s4
	v_mov_b32_e32 v2, s5
	s_add_i32 s4, 0, 0x201e8
	ds_write_b32 v1, v2
	v_mov_b32_e32 v1, s4
	v_mov_b32_e32 v2, s6
	s_add_i32 s4, 0, 0x201ec
	ds_write_b32 v1, v2
	v_mov_b32_e32 v1, s4
	v_mov_b32_e32 v2, s7
	s_add_i32 s4, 0, 0x201f0
	ds_write_b32 v1, v2
	v_mov_b32_e32 v1, s4
	v_mov_b32_e32 v2, s8
	s_add_i32 s4, 0, 0x201f4
	ds_write_b32 v1, v2
	v_mov_b32_e32 v1, s4
	v_mov_b32_e32 v2, s9
	s_add_i32 s4, 0, 0x201f8
	ds_write_b32 v1, v2
	v_mov_b32_e32 v1, s4
	v_mov_b32_e32 v2, s10
	s_add_i32 s4, 0, 0x201fc
	ds_write_b32 v1, v2
	v_mov_b32_e32 v1, s4
	s_load_dwordx2 s[4:5], s[0:1], 0x100
	v_mov_b32_e32 v2, s11
	ds_write_b32 v1, v2
	s_add_i32 s6, 0, 0x20200
	v_mov_b32_e32 v1, s6
	s_load_dwordx2 s[6:7], s[0:1], 0x108
	s_load_dwordx2 s[8:9], s[0:1], 0x110
	s_load_dwordx2 s[10:11], s[0:1], 0x118
	s_waitcnt lgkmcnt(0)
	v_mov_b32_e32 v2, s4
	s_add_i32 s0, 0, 0x20204
	ds_write_b32 v1, v2
	v_mov_b32_e32 v1, s0
	v_mov_b32_e32 v2, s5
	s_add_i32 s0, 0, 0x20208
	ds_write_b32 v1, v2
	v_mov_b32_e32 v1, s0
	v_mov_b32_e32 v2, s6
	s_add_i32 s0, 0, 0x2020c
	ds_write_b32 v1, v2
	v_mov_b32_e32 v1, s0
	v_mov_b32_e32 v2, s7
	s_add_i32 s0, 0, 0x20210
	ds_write_b32 v1, v2
	v_mov_b32_e32 v1, s0
	v_mov_b32_e32 v2, s8
	s_add_i32 s0, 0, 0x20214
	ds_write_b32 v1, v2
	v_mov_b32_e32 v1, s0
	v_mov_b32_e32 v2, s9
	s_add_i32 s0, 0, 0x20218
	ds_write_b32 v1, v2
	v_mov_b32_e32 v1, s0
	v_mov_b32_e32 v2, s10
	s_add_i32 s0, 0, 0x2021c
	ds_write_b32 v1, v2
	v_mov_b32_e32 v1, s0
	v_mov_b32_e32 v2, s11
	ds_write_b32 v1, v2

; #define PG8_STAGE(bufoff, gbase, voff) do { _Pragma("unroll") for (int _i = 0; _i < 2; ++_i) \
;         __builtin_amdgcn_global_load_lds((const unsigned*)((const char*)(gbase) + (voff)[_i]), (PG8_LAS unsigned*)(lds + (bufoff) + ldsw + _i * 8192), 16, 0, 0); } while (0)
; #define PG8_LDA(dst, b, h) do { _Pragma("unroll") for (int m = 0; m < 4; ++m) _Pragma("unroll") for (int k = 0; k < 2; ++k) dst[m][k] = *(const PG8_LAS bf16x8*)(lds + PG8_SA(b, h) + aoff + m * 2048 + k * 1024); } while (0)
; #define PG8_LDB(dst, b, h) do { _Pragma("unroll") for (int n = 0; n < 2; ++n) _Pragma("unroll") for (int k = 0; k < 2; ++k) dst[n][k] = *(const PG8_LAS bf16x8*)(lds + PG8_SB(b, h) + boff + n * 2048 + k * 1024); } while (0)
; #define PG8_MMA(ai, bj, At, Bt) do { __builtin_amdgcn_s_setprio(1); _Pragma("unroll") for (int m = 0; m < 4; ++m) _Pragma("unroll") for (int n = 0; n < 2; ++n) _Pragma("unroll") for (int k = 0; k < 2; ++k) \
;         acc[ai][bj][m][n] = __builtin_amdgcn_mfma_f32_16x16x32_bf16(Bt[n][k], At[m][k], acc[ai][bj][m][n], 0, 0, 0); __builtin_amdgcn_s_setprio(0); } while (0)
; #define PG8_WAIT_V(n) asm volatile("s_waitcnt vmcnt(" #n ")" ::: "memory")
; #define PG8_WAIT_L(n) asm volatile("s_waitcnt lgkmcnt(" #n ")" ::: "memory")
; #define PG8_BAR __builtin_amdgcn_s_barrier()
; #define PG8_SCHED __builtin_amdgcn_sched_barrier(0)
; template <class Epi, class Sched, bool ALIGN_EPI = false, bool SP2 = false>
; __device__ __forceinline__ void gemm_phase(PG8_LAS unsigned char* lds, const Gemm g, const Sched& S, const Epi& E, const int tid) {
;     ...
;             if constexpr (SP2) {
;             PG8_LDB(B0, 0, 0); PG8_LDB(B1, 0, 1); PG8_SCHED; PG8_LDA(At, 0, 0); PG8_STAGE(PG8_SA(1, 1), a1 + hstep, voffA);
;             PG8_WAIT_V(8); PG8_WAIT_L(0); PG8_BAR; PG8_MMA(0, 0, At, B0); PG8_MMA(0, 1, At, B1); PG8_BAR; PG8_SCHED;
;             PG8_LDA(At, 0, 1); PG8_STAGE(PG8_SB(0, 0), b2, voffB); PG8_STAGE(PG8_SB(0, 1), b2 + hstep, voffB); PG8_STAGE(PG8_SA(0, 0), a2, voffA);
;             PG8_WAIT_V(8); PG8_WAIT_L(0); PG8_BAR; PG8_MMA(1, 0, At, B0); PG8_MMA(1, 1, At, B1); PG8_BAR; PG8_SCHED;
.Lmy_nobar_341:
	s_cmp_eq_u32 s101, 0
	s_cbranch_scc1 .Lmy_strict_341
	s_add_u32 s12, s10, 0xfff80080
	s_addc_u32 s13, s11, -1
	s_add_i32 s47, 0, 0x10000
	v_add_u32_e32 v28, s47, v197
	s_waitcnt vmcnt(0)
	v_add_u32_e32 v60, s33, v197
	ds_read_b128 v[16:19], v28
	ds_read_b128 v[20:23], v28 offset:1024
	ds_read_b128 v[24:27], v28 offset:2048
	ds_read_b128 v[28:31], v28 offset:3072
	ds_read_b128 v[40:43], v60
	ds_read_b128 v[44:47], v60 offset:1024
	ds_read_b128 v[56:59], v60 offset:2048
	ds_read_b128 v[60:63], v60 offset:3072
	s_cmp_eq_u32 s46, 28
	s_cselect_b32 s43, s1, s13
	s_cselect_b32 s42, s9, s12
	s_cselect_b32 s13, s35, s45
	s_cselect_b32 s12, s37, s44
	v_lshl_add_u64 v[194:195], s[10:11], 0, v[190:191]
	s_add_i32 m0, s63, 0xc000
	ds_read_b128 v[80:83], v240
	ds_read_b128 v[84:87], v240 offset:1024
	ds_read_b128 v[104:107], v240 offset:2048
	ds_read_b128 v[108:111], v240 offset:3072
	ds_read_b128 v[198:201], v240 offset:4096
	ds_read_b128 v[202:205], v240 offset:5120
	ds_read_b128 v[214:217], v240 offset:6144
	ds_read_b128 v[218:221], v240 offset:7168
	global_load_lds_dwordx4 v[194:195], off
	v_lshl_add_u64 v[194:195], s[10:11], 0, v[192:193]
	s_add_i32 m0, s63, 0xe000
	s_nop 0
	global_load_lds_dwordx4 v[194:195], off
	s_waitcnt lgkmcnt(0)
	s_barrier
	s_setprio 1
	s_waitcnt lgkmcnt(0)
	v_mfma_f32_16x16x32_bf16 v[172:175], v[16:19], v[80:83], 0
	v_mfma_f32_16x16x32_bf16 v[168:171], v[24:27], v[80:83], 0
	v_mfma_f32_16x16x32_bf16 v[156:159], v[16:19], v[104:107], 0
	v_mfma_f32_16x16x32_bf16 v[152:155], v[24:27], v[104:107], 0
	v_mfma_f32_16x16x32_bf16 v[140:143], v[16:19], v[198:201], 0
	v_mfma_f32_16x16x32_bf16 v[136:139], v[24:27], v[198:201], 0
	v_mfma_f32_16x16x32_bf16 v[124:127], v[16:19], v[214:217], 0
	v_mfma_f32_16x16x32_bf16 v[120:123], v[24:27], v[214:217], 0
	v_mfma_f32_16x16x32_bf16 v[172:175], v[20:23], v[84:87], v[172:175]
	v_mfma_f32_16x16x32_bf16 v[168:171], v[28:31], v[84:87], v[168:171]
	v_mfma_f32_16x16x32_bf16 v[156:159], v[20:23], v[108:111], v[156:159]
	v_mfma_f32_16x16x32_bf16 v[152:155], v[28:31], v[108:111], v[152:155]
	v_mfma_f32_16x16x32_bf16 v[140:143], v[20:23], v[202:205], v[140:143]
	v_mfma_f32_16x16x32_bf16 v[136:139], v[28:31], v[202:205], v[136:139]
	v_mfma_f32_16x16x32_bf16 v[124:127], v[20:23], v[218:221], v[124:127]
	v_mfma_f32_16x16x32_bf16 v[120:123], v[28:31], v[218:221], v[120:123]
	s_setprio 0
	s_setprio 1
	v_mfma_f32_16x16x32_bf16 v[164:167], v[40:43], v[80:83], 0
	v_mfma_f32_16x16x32_bf16 v[80:83], v[56:59], v[80:83], 0
	v_mfma_f32_16x16x32_bf16 v[164:167], v[44:47], v[84:87], v[164:167]
	v_mfma_f32_16x16x32_bf16 v[80:83], v[60:63], v[84:87], v[80:83]
	v_mfma_f32_16x16x32_bf16 v[84:87], v[40:43], v[104:107], 0
	v_mfma_f32_16x16x32_bf16 v[104:107], v[56:59], v[104:107], 0
	v_mfma_f32_16x16x32_bf16 v[128:131], v[56:59], v[198:201], 0
	v_mfma_f32_16x16x32_bf16 v[116:119], v[40:43], v[214:217], 0
	v_mfma_f32_16x16x32_bf16 v[112:115], v[56:59], v[214:217], 0
	v_mfma_f32_16x16x32_bf16 v[84:87], v[44:47], v[108:111], v[84:87]
	v_mfma_f32_16x16x32_bf16 v[104:107], v[60:63], v[108:111], v[104:107]
	v_mfma_f32_16x16x32_bf16 v[108:111], v[40:43], v[198:201], 0
	v_mfma_f32_16x16x32_bf16 v[128:131], v[60:63], v[202:205], v[128:131]
	v_mfma_f32_16x16x32_bf16 v[116:119], v[44:47], v[218:221], v[116:119]
	v_mfma_f32_16x16x32_bf16 v[112:115], v[60:63], v[218:221], v[112:115]
	v_mfma_f32_16x16x32_bf16 v[108:111], v[44:47], v[202:205], v[108:111]
	s_setprio 0
	s_barrier
	s_add_i32 s47, s47, s62
	v_lshl_add_u64 v[194:195], s[12:13], 0, v[178:179]
	s_mov_b32 m0, s47
	ds_read_b128 v[132:135], v240 offset:16384
	ds_read_b128 v[144:147], v240 offset:17408
	ds_read_b128 v[148:151], v240 offset:18432
	ds_read_b128 v[160:163], v240 offset:19456
	ds_read_b128 v[198:201], v240 offset:20480
	ds_read_b128 v[202:205], v240 offset:21504
	ds_read_b128 v[214:217], v240 offset:22528
	ds_read_b128 v[218:221], v240 offset:23552
	global_load_lds_dwordx4 v[194:195], off
	s_add_i32 m0, s47, 0x2000
	s_add_u32 s48, s12, 0x80000
	v_lshl_add_u64 v[206:207], s[12:13], 0, v[182:183]
	s_addc_u32 s49, s13, 0
	s_add_i32 s47, s33, s62
	global_load_lds_dwordx4 v[206:207], off
	v_lshl_add_u64 v[210:211], s[48:49], 0, v[178:179]
	s_mov_b32 m0, s47
	v_lshl_add_u64 v[234:235], s[42:43], 0, v[180:181]
	global_load_lds_dwordx4 v[210:211], off
	v_lshl_add_u64 v[210:211], s[48:49], 0, v[182:183]
	s_add_i32 m0, s47, 0x2000
	s_nop 0
	global_load_lds_dwordx4 v[210:211], off
	v_lshl_add_u64 v[210:211], s[42:43], 0, v[176:177]
	s_mov_b32 m0, s63
	s_nop 0
	global_load_lds_dwordx4 v[210:211], off
	s_mov_b32 m0, s64
	s_nop 0
	global_load_lds_dwordx4 v[234:235], off
	s_waitcnt lgkmcnt(0)
	s_barrier
	s_setprio 1
	s_waitcnt lgkmcnt(0)
	v_mfma_f32_16x16x32_bf16 v[100:103], v[16:19], v[132:135], 0
	v_mfma_f32_16x16x32_bf16 v[96:99], v[24:27], v[132:135], 0
	v_mfma_f32_16x16x32_bf16 v[76:79], v[16:19], v[148:151], 0
	v_mfma_f32_16x16x32_bf16 v[72:75], v[24:27], v[148:151], 0
	v_mfma_f32_16x16x32_bf16 v[52:55], v[16:19], v[198:201], 0
	v_mfma_f32_16x16x32_bf16 v[48:51], v[24:27], v[198:201], 0
	v_mfma_f32_16x16x32_bf16 v[12:15], v[16:19], v[214:217], 0
	v_mfma_f32_16x16x32_bf16 v[8:11], v[24:27], v[214:217], 0
	v_mfma_f32_16x16x32_bf16 v[100:103], v[20:23], v[144:147], v[100:103]
	v_mfma_f32_16x16x32_bf16 v[96:99], v[28:31], v[144:147], v[96:99]
	v_mfma_f32_16x16x32_bf16 v[76:79], v[20:23], v[160:163], v[76:79]
	v_mfma_f32_16x16x32_bf16 v[72:75], v[28:31], v[160:163], v[72:75]
	v_mfma_f32_16x16x32_bf16 v[52:55], v[20:23], v[202:205], v[52:55]
	v_mfma_f32_16x16x32_bf16 v[48:51], v[28:31], v[202:205], v[48:51]
	v_mfma_f32_16x16x32_bf16 v[12:15], v[20:23], v[218:221], v[12:15]
	v_mfma_f32_16x16x32_bf16 v[8:11], v[28:31], v[218:221], v[8:11]
	s_setprio 0
	s_setprio 1
	v_mfma_f32_16x16x32_bf16 v[36:39], v[40:43], v[198:201], 0
	v_mfma_f32_16x16x32_bf16 v[32:35], v[56:59], v[198:201], 0
	v_mfma_f32_16x16x32_bf16 v[4:7], v[40:43], v[214:217], 0
	v_mfma_f32_16x16x32_bf16 v[0:3], v[56:59], v[214:217], 0
	v_mfma_f32_16x16x32_bf16 v[16:19], v[40:43], v[132:135], 0
	v_mfma_f32_16x16x32_bf16 v[20:23], v[56:59], v[132:135], 0
	v_mfma_f32_16x16x32_bf16 v[24:27], v[40:43], v[148:151], 0
	v_mfma_f32_16x16x32_bf16 v[28:31], v[56:59], v[148:151], 0
	v_mfma_f32_16x16x32_bf16 v[36:39], v[44:47], v[202:205], v[36:39]
	v_mfma_f32_16x16x32_bf16 v[32:35], v[60:63], v[202:205], v[32:35]
	v_mfma_f32_16x16x32_bf16 v[4:7], v[44:47], v[218:221], v[4:7]
	v_mfma_f32_16x16x32_bf16 v[0:3], v[60:63], v[218:221], v[0:3]
	v_mfma_f32_16x16x32_bf16 v[16:19], v[44:47], v[144:147], v[16:19]
	v_mfma_f32_16x16x32_bf16 v[20:23], v[60:63], v[144:147], v[20:23]
	v_mfma_f32_16x16x32_bf16 v[24:27], v[44:47], v[160:163], v[24:27]
	v_mfma_f32_16x16x32_bf16 v[28:31], v[60:63], v[160:163], v[28:31]
	s_setprio 0
	s_barrier
	s_mov_b32 s101, 0
	s_branch .Lmy_mid_341

; #define PG8_BAR __builtin_amdgcn_s_barrier()
; template <class Epi, class Sched, bool ALIGN_EPI = false, bool SP2 = false>
; __device__ __forceinline__ void gemm_phase(PG8_LAS unsigned char* lds, const Gemm g, const Sched& S, const Epi& E, const int tid) {
;     ...
;         if (!has_next) break;
; #pragma unroll
;         for (int a = 0; a < 2; ++a)
; #pragma unroll
;             for (int b = 0; b < 2; ++b)
; #pragma unroll
;                 for (int m = 0; m < 4; ++m)
; #pragma unroll
;                     for (int n = 0; n < 2; ++n) acc[a][b][m][n] = (f32x4){0.f, 0.f, 0.f, 0.f};
;         cur = nxt; cA = nA; cB = nB; ++ui;
;         if constexpr (ALIGN_EPI) { if (wr == 1) PG8_BAR; }
.LBB0_703:
	s_mov_b32 s101, 1
	s_andn2_b64 vcc, exec, s[14:15]
	s_cbranch_vccnz .LBB0_332
	s_mov_b32 s100, 1
	s_branch .LBB0_332

; #define PG8_STAGE(bufoff, gbase, voff) do { _Pragma("unroll") for (int _i = 0; _i < 2; ++_i) \
;         __builtin_amdgcn_global_load_lds((const unsigned*)((const char*)(gbase) + (voff)[_i]), (PG8_LAS unsigned*)(lds + (bufoff) + ldsw + _i * 8192), 16, 0, 0); } while (0)
; #define PG8_LDA(dst, b, h) do { _Pragma("unroll") for (int m = 0; m < 4; ++m) _Pragma("unroll") for (int k = 0; k < 2; ++k) dst[m][k] = *(const PG8_LAS bf16x8*)(lds + PG8_SA(b, h) + aoff + m * 2048 + k * 1024); } while (0)
; #define PG8_LDB(dst, b, h) do { _Pragma("unroll") for (int n = 0; n < 2; ++n) _Pragma("unroll") for (int k = 0; k < 2; ++k) dst[n][k] = *(const PG8_LAS bf16x8*)(lds + PG8_SB(b, h) + boff + n * 2048 + k * 1024); } while (0)
; #define PG8_MMA(ai, bj, At, Bt) do { __builtin_amdgcn_s_setprio(1); _Pragma("unroll") for (int m = 0; m < 4; ++m) _Pragma("unroll") for (int n = 0; n < 2; ++n) _Pragma("unroll") for (int k = 0; k < 2; ++k) \
;         acc[ai][bj][m][n] = __builtin_amdgcn_mfma_f32_16x16x32_bf16(Bt[n][k], At[m][k], acc[ai][bj][m][n], 0, 0, 0); __builtin_amdgcn_s_setprio(0); } while (0)
; #define PG8_WAIT_V(n) asm volatile("s_waitcnt vmcnt(" #n ")" ::: "memory")
; #define PG8_WAIT_L(n) asm volatile("s_waitcnt lgkmcnt(" #n ")" ::: "memory")
; #define PG8_BAR __builtin_amdgcn_s_barrier()
; #define PG8_SCHED __builtin_amdgcn_sched_barrier(0)
; template <class Epi, class Sched, bool ALIGN_EPI = false, bool SP2 = false>
; __device__ __forceinline__ void gemm_phase(PG8_LAS unsigned char* lds, const Gemm g, const Sched& S, const Epi& E, const int tid) {
;     ...
;             if constexpr (SP2) {
;             PG8_LDB(B0, 0, 0); PG8_LDB(B1, 0, 1); PG8_SCHED; PG8_LDA(At, 0, 0); PG8_STAGE(PG8_SA(1, 1), a1 + hstep, voffA);
;             PG8_WAIT_V(8); PG8_WAIT_L(0); PG8_BAR; PG8_MMA(0, 0, At, B0); PG8_MMA(0, 1, At, B1); PG8_BAR; PG8_SCHED;
;             PG8_LDA(At, 0, 1); PG8_STAGE(PG8_SB(0, 0), b2, voffB); PG8_STAGE(PG8_SB(0, 1), b2 + hstep, voffB); PG8_STAGE(PG8_SA(0, 0), a2, voffA);
;             PG8_WAIT_V(8); PG8_WAIT_L(0); PG8_BAR; PG8_MMA(1, 0, At, B0); PG8_MMA(1, 1, At, B1); PG8_BAR; PG8_SCHED;
.Lmy_nobar_768:
	s_cmp_eq_u32 s101, 0
	s_cbranch_scc1 .Lmy_strict_768
	s_add_u32 s26, s24, 0xfff80080
	s_addc_u32 s27, s25, -1
	s_add_i32 s52, 0, 0x10000
	v_add_u32_e32 v68, s52, v157
	v_add_u32_e32 v154, s33, v157
	ds_read_b128 v[48:51], v68
	ds_read_b128 v[52:55], v68 offset:1024
	ds_read_b128 v[64:67], v68 offset:2048
	ds_read_b128 v[68:71], v68 offset:3072
	ds_read_b128 v[162:165], v154
	ds_read_b128 v[166:169], v154 offset:1024
	ds_read_b128 v[170:173], v154 offset:2048
	ds_read_b128 v[174:177], v154 offset:3072
	s_cmp_eq_u32 s51, 28
	s_cselect_b32 s29, s15, s27
	s_cselect_b32 s28, s21, s26
	s_cselect_b32 s27, s11, s50
	s_cselect_b32 s26, s48, s49
	v_lshl_add_u64 v[206:207], s[24:25], 0, v[150:151]
	s_add_i32 m0, s23, 0xc000
	ds_read_b128 v[178:181], v161
	ds_read_b128 v[182:185], v161 offset:1024
	ds_read_b128 v[186:189], v161 offset:2048
	ds_read_b128 v[190:193], v161 offset:3072
	ds_read_b128 v[194:197], v161 offset:4096
	ds_read_b128 v[198:201], v161 offset:5120
	ds_read_b128 v[202:205], v161 offset:6144
	ds_read_b128 v[214:217], v161 offset:7168
	global_load_lds_dwordx4 v[206:207], off
	v_lshl_add_u64 v[206:207], s[24:25], 0, v[152:153]
	s_add_i32 m0, s23, 0xe000
	s_nop 0
	global_load_lds_dwordx4 v[206:207], off
	s_waitcnt lgkmcnt(0)
	s_barrier
	s_setprio 1
	s_waitcnt lgkmcnt(0)
	v_mfma_f32_16x16x32_bf16 v[140:143], v[48:51], v[178:181], 0
	v_mfma_f32_16x16x32_bf16 v[136:139], v[64:67], v[178:181], 0
	v_mfma_f32_16x16x32_bf16 v[124:127], v[48:51], v[186:189], 0
	v_mfma_f32_16x16x32_bf16 v[120:123], v[64:67], v[186:189], 0
	v_mfma_f32_16x16x32_bf16 v[108:111], v[48:51], v[194:197], 0
	v_mfma_f32_16x16x32_bf16 v[104:107], v[64:67], v[194:197], 0
	v_mfma_f32_16x16x32_bf16 v[92:95], v[48:51], v[202:205], 0
	v_mfma_f32_16x16x32_bf16 v[88:91], v[64:67], v[202:205], 0
	v_mfma_f32_16x16x32_bf16 v[140:143], v[52:55], v[182:185], v[140:143]
	v_mfma_f32_16x16x32_bf16 v[136:139], v[68:71], v[182:185], v[136:139]
	v_mfma_f32_16x16x32_bf16 v[124:127], v[52:55], v[190:193], v[124:127]
	v_mfma_f32_16x16x32_bf16 v[120:123], v[68:71], v[190:193], v[120:123]
	v_mfma_f32_16x16x32_bf16 v[108:111], v[52:55], v[198:201], v[108:111]
	v_mfma_f32_16x16x32_bf16 v[104:107], v[68:71], v[198:201], v[104:107]
	v_mfma_f32_16x16x32_bf16 v[92:95], v[52:55], v[214:217], v[92:95]
	v_mfma_f32_16x16x32_bf16 v[88:91], v[68:71], v[214:217], v[88:91]
	s_setprio 0
	s_setprio 1
	v_mfma_f32_16x16x32_bf16 v[132:135], v[162:165], v[178:181], 0
	v_mfma_f32_16x16x32_bf16 v[128:131], v[170:173], v[178:181], 0
	v_mfma_f32_16x16x32_bf16 v[116:119], v[162:165], v[186:189], 0
	v_mfma_f32_16x16x32_bf16 v[112:115], v[170:173], v[186:189], 0
	v_mfma_f32_16x16x32_bf16 v[100:103], v[162:165], v[194:197], 0
	v_mfma_f32_16x16x32_bf16 v[96:99], v[170:173], v[194:197], 0
	v_mfma_f32_16x16x32_bf16 v[84:87], v[162:165], v[202:205], 0
	v_mfma_f32_16x16x32_bf16 v[80:83], v[170:173], v[202:205], 0
	v_mfma_f32_16x16x32_bf16 v[132:135], v[166:169], v[182:185], v[132:135]
	v_mfma_f32_16x16x32_bf16 v[128:131], v[174:177], v[182:185], v[128:131]
	v_mfma_f32_16x16x32_bf16 v[116:119], v[166:169], v[190:193], v[116:119]
	v_mfma_f32_16x16x32_bf16 v[112:115], v[174:177], v[190:193], v[112:115]
	v_mfma_f32_16x16x32_bf16 v[100:103], v[166:169], v[198:201], v[100:103]
	v_mfma_f32_16x16x32_bf16 v[96:99], v[174:177], v[198:201], v[96:99]
	v_mfma_f32_16x16x32_bf16 v[84:87], v[166:169], v[214:217], v[84:87]
	v_mfma_f32_16x16x32_bf16 v[80:83], v[174:177], v[214:217], v[80:83]
	s_setprio 0
	s_barrier
	s_add_i32 s52, s52, s38
	v_lshl_add_u64 v[206:207], s[26:27], 0, v[208:209]
	s_mov_b32 m0, s52
	ds_read_b128 v[178:181], v161 offset:16384
	ds_read_b128 v[182:185], v161 offset:17408
	ds_read_b128 v[186:189], v161 offset:18432
	ds_read_b128 v[190:193], v161 offset:19456
	ds_read_b128 v[194:197], v161 offset:20480
	ds_read_b128 v[198:201], v161 offset:21504
	ds_read_b128 v[202:205], v161 offset:22528
	ds_read_b128 v[214:217], v161 offset:23552
	global_load_lds_dwordx4 v[206:207], off
	s_add_i32 m0, s52, 0x2000
	s_add_u32 s52, s26, 0x80000
	v_lshl_add_u64 v[210:211], s[26:27], 0, v[144:145]
	s_addc_u32 s53, s27, 0
	s_add_i32 s54, s33, s38
	global_load_lds_dwordx4 v[210:211], off
	v_lshl_add_u64 v[218:219], s[52:53], 0, v[208:209]
	s_mov_b32 m0, s54
	v_lshl_add_u64 v[220:221], s[28:29], 0, v[146:147]
	global_load_lds_dwordx4 v[218:219], off
	v_lshl_add_u64 v[218:219], s[52:53], 0, v[144:145]
	s_add_i32 m0, s54, 0x2000
	s_nop 0
	global_load_lds_dwordx4 v[218:219], off
	v_lshl_add_u64 v[218:219], s[28:29], 0, v[148:149]
	s_mov_b32 m0, s23
	s_nop 0
	global_load_lds_dwordx4 v[218:219], off
	s_mov_b32 m0, s39
	s_nop 0
	global_load_lds_dwordx4 v[220:221], off
	s_waitcnt lgkmcnt(0)
	s_barrier
	s_setprio 1
	s_waitcnt lgkmcnt(0)
	v_mfma_f32_16x16x32_bf16 v[76:79], v[48:51], v[178:181], 0
	v_mfma_f32_16x16x32_bf16 v[72:75], v[64:67], v[178:181], 0
	v_mfma_f32_16x16x32_bf16 v[44:47], v[48:51], v[186:189], 0
	v_mfma_f32_16x16x32_bf16 v[40:43], v[64:67], v[186:189], 0
	v_mfma_f32_16x16x32_bf16 v[28:31], v[48:51], v[194:197], 0
	v_mfma_f32_16x16x32_bf16 v[24:27], v[64:67], v[194:197], 0
	v_mfma_f32_16x16x32_bf16 v[12:15], v[48:51], v[202:205], 0
	v_mfma_f32_16x16x32_bf16 v[8:11], v[64:67], v[202:205], 0
	v_mfma_f32_16x16x32_bf16 v[76:79], v[52:55], v[182:185], v[76:79]
	v_mfma_f32_16x16x32_bf16 v[72:75], v[68:71], v[182:185], v[72:75]
	v_mfma_f32_16x16x32_bf16 v[44:47], v[52:55], v[190:193], v[44:47]
	v_mfma_f32_16x16x32_bf16 v[40:43], v[68:71], v[190:193], v[40:43]
	v_mfma_f32_16x16x32_bf16 v[28:31], v[52:55], v[198:201], v[28:31]
	v_mfma_f32_16x16x32_bf16 v[24:27], v[68:71], v[198:201], v[24:27]
	v_mfma_f32_16x16x32_bf16 v[12:15], v[52:55], v[214:217], v[12:15]
	v_mfma_f32_16x16x32_bf16 v[8:11], v[68:71], v[214:217], v[8:11]
	s_setprio 0
	s_setprio 1
	v_mfma_f32_16x16x32_bf16 v[36:39], v[162:165], v[186:189], 0
	v_mfma_f32_16x16x32_bf16 v[32:35], v[170:173], v[186:189], 0
	v_mfma_f32_16x16x32_bf16 v[20:23], v[162:165], v[194:197], 0
	v_mfma_f32_16x16x32_bf16 v[16:19], v[170:173], v[194:197], 0
	v_mfma_f32_16x16x32_bf16 v[4:7], v[162:165], v[202:205], 0
	v_mfma_f32_16x16x32_bf16 v[0:3], v[170:173], v[202:205], 0
	v_mfma_f32_16x16x32_bf16 v[48:51], v[162:165], v[178:181], 0
	v_mfma_f32_16x16x32_bf16 v[52:55], v[170:173], v[178:181], 0
	v_mfma_f32_16x16x32_bf16 v[36:39], v[166:169], v[190:193], v[36:39]
	v_mfma_f32_16x16x32_bf16 v[32:35], v[174:177], v[190:193], v[32:35]
	v_mfma_f32_16x16x32_bf16 v[20:23], v[166:169], v[198:201], v[20:23]
	v_mfma_f32_16x16x32_bf16 v[16:19], v[174:177], v[198:201], v[16:19]
	v_mfma_f32_16x16x32_bf16 v[4:7], v[166:169], v[214:217], v[4:7]
	v_mfma_f32_16x16x32_bf16 v[0:3], v[174:177], v[214:217], v[0:3]
	v_mfma_f32_16x16x32_bf16 v[48:51], v[166:169], v[182:185], v[48:51]
	v_mfma_f32_16x16x32_bf16 v[52:55], v[174:177], v[182:185], v[52:55]
	s_setprio 0
	s_barrier
	s_mov_b32 s101, 0
	s_branch .Lmy_mid_768

; __device__ __forceinline__ unsigned pk2(float lo, float hi) { const f32x2 v = {lo, hi}; return __builtin_bit_cast(unsigned, __builtin_convertvector(v, bf16x2_t)); }
; #define EPI_LOOP _Pragma("unroll") for (int ai = 0; ai < 2; ++ai) _Pragma("unroll") for (int m = 0; m < 4; ++m) _Pragma("unroll") for (int bj = 0; bj < 2; ++bj)
; __device__ __forceinline__ float sigmoidf_(float x) { return __builtin_amdgcn_rcpf(1.f + __builtin_amdgcn_exp2f(-x * LOG2E)); }
;     __device__ __forceinline__ void operator()(const f32x4 (&acc)[2][2][4][2], const Unit& un, int wr, int wc, int fr, int fq) const {
;     ...
;         EPI_LOOP { const int row = rbase + ai * 128 + m * 16, col = cw + bj * 128; const float r = rr[ai][m];
;             f32x4 v0 = acc[ai][bj][m][0] * r + s0[bj], v1 = acc[ai][bj][m][1] * r + s1[bj];
;             v0 = (f32x4){sigmoidf_(v0.x), sigmoidf_(v0.y), sigmoidf_(v0.z), sigmoidf_(v0.w)}; v1 = (f32x4){sigmoidf_(v1.x), sigmoidf_(v1.y), sigmoidf_(v1.z), sigmoidf_(v1.w)};
;             u32x4 w; w.x = pk2(v0.x, v0.y); w.y = pk2(v0.z, v0.w); w.z = pk2(v1.x, v1.y); w.w = pk2(v1.z, v1.w);
;             *(u32x4*)(o + (size_t)row * DFF + col) = w; }
.LBB0_771:
	s_mov_b64 s[20:21], 0x240000
	s_waitcnt vmcnt(0)
	v_pk_fma_f32 v[142:143], v[142:143], v[174:175], v[70:71] op_sel_hi:[1,0,1]
	v_pk_fma_f32 v[140:141], v[140:141], v[174:175], v[68:69] op_sel_hi:[1,0,1]
	v_pk_fma_f32 v[138:139], v[138:139], v[174:175], v[66:67] op_sel_hi:[1,0,1]
	v_pk_fma_f32 v[136:137], v[136:137], v[174:175], v[64:65] op_sel_hi:[1,0,1]
	v_mul_f32_e32 v140, 0xbfb8aa3b, v140
	v_mul_f32_e32 v141, 0xbfb8aa3b, v141
	v_mul_f32_e32 v142, 0xbfb8aa3b, v142
	v_mul_f32_e32 v143, 0xbfb8aa3b, v143
	v_mul_f32_e32 v136, 0xbfb8aa3b, v136
	v_mul_f32_e32 v137, 0xbfb8aa3b, v137
	v_mul_f32_e32 v138, 0xbfb8aa3b, v138
	v_mul_f32_e32 v139, 0xbfb8aa3b, v139
	v_exp_f32_e32 v140, v140
	v_exp_f32_e32 v141, v141
	v_exp_f32_e32 v142, v142
	v_exp_f32_e32 v143, v143
	v_exp_f32_e32 v136, v136
	v_exp_f32_e32 v137, v137
	v_exp_f32_e32 v138, v138
	v_exp_f32_e32 v139, v139
	v_add_f32_e32 v140, 1.0, v140
	v_add_f32_e32 v141, 1.0, v141
	v_add_f32_e32 v142, 1.0, v142
	v_add_f32_e32 v143, 1.0, v143
	v_add_f32_e32 v136, 1.0, v136
	v_add_f32_e32 v137, 1.0, v137
	v_add_f32_e32 v138, 1.0, v138
	v_add_f32_e32 v139, 1.0, v139
	v_pk_fma_f32 v[128:129], v[128:129], v[174:175], v[48:49] op_sel_hi:[1,0,1]
	v_rcp_f32_e32 v140, v140
	v_rcp_f32_e32 v141, v141
	v_rcp_f32_e32 v142, v142
	v_rcp_f32_e32 v143, v143
	v_rcp_f32_e32 v136, v136
	v_rcp_f32_e32 v137, v137
	v_rcp_f32_e32 v138, v138
	v_rcp_f32_e32 v139, v139
	v_mul_f32_e32 v128, 0xbfb8aa3b, v128
	v_exp_f32_e32 v128, v128
	v_cvt_pk_bf16_f32 v140, v140, v141
	v_cvt_pk_bf16_f32 v141, v142, v143
	v_cvt_pk_bf16_f32 v142, v136, v137
	v_cvt_pk_bf16_f32 v143, v138, v139
	v_lshl_add_u64 v[136:137], s[4:5], 0, v[178:179]
	v_lshlrev_b64 v[138:139], 1, v[176:177]
	v_lshl_add_u64 v[136:137], v[136:137], 0, v[138:139]
	v_add_f32_e32 v128, 1.0, v128
	global_store_dwordx4 v[136:137], v[140:143], off
	v_pk_fma_f32 v[130:131], v[130:131], v[174:175], v[50:51] op_sel_hi:[1,0,1]
	v_pk_fma_f32 v[134:135], v[134:135], v[174:175], v[54:55] op_sel_hi:[1,0,1]
	v_rcp_f32_e32 v140, v128
	v_mul_f32_e32 v128, 0xbfb8aa3b, v129
	v_exp_f32_e32 v128, v128
	v_pk_fma_f32 v[132:133], v[132:133], v[174:175], v[52:53] op_sel_hi:[1,0,1]
	v_mul_f32_e32 v134, 0xbfb8aa3b, v134
	v_mul_f32_e32 v132, 0xbfb8aa3b, v132
	v_add_f32_e32 v128, 1.0, v128
	v_rcp_f32_e32 v141, v128
	v_mul_f32_e32 v128, 0xbfb8aa3b, v130
	v_exp_f32_e32 v128, v128
	v_mul_f32_e32 v133, 0xbfb8aa3b, v133
	v_mul_f32_e32 v135, 0xbfb8aa3b, v135
	v_exp_f32_e32 v132, v132
	v_add_f32_e32 v128, 1.0, v128
	v_rcp_f32_e32 v142, v128
	v_mul_f32_e32 v128, 0xbfb8aa3b, v131
	v_exp_f32_e32 v133, v133
	v_exp_f32_e32 v134, v134
	v_exp_f32_e32 v135, v135
	v_exp_f32_e32 v128, v128
	v_pk_fma_f32 v[120:121], v[120:121], v[170:171], v[64:65] op_sel_hi:[1,0,1]
	v_add_f32_e32 v132, 1.0, v132
	v_add_f32_e32 v133, 1.0, v133
	v_add_f32_e32 v134, 1.0, v134
	v_add_f32_e32 v135, 1.0, v135
	v_add_f32_e32 v128, 1.0, v128
	v_mul_f32_e32 v120, 0xbfb8aa3b, v120
	v_rcp_f32_e32 v132, v132
	v_rcp_f32_e32 v133, v133
	v_rcp_f32_e32 v134, v134
	v_rcp_f32_e32 v135, v135
	v_rcp_f32_e32 v131, v128
	v_exp_f32_e32 v120, v120
	v_cvt_pk_bf16_f32 v128, v132, v133
	v_cvt_pk_bf16_f32 v129, v134, v135
	v_cvt_pk_bf16_f32 v130, v140, v141
	v_cvt_pk_bf16_f32 v131, v142, v131
	v_add_f32_e32 v120, 1.0, v120
	global_store_dwordx4 v[136:137], v[128:131], off offset:256
	v_pk_fma_f32 v[122:123], v[122:123], v[170:171], v[66:67] op_sel_hi:[1,0,1]
	v_pk_fma_f32 v[124:125], v[124:125], v[170:171], v[68:69] op_sel_hi:[1,0,1]
	v_rcp_f32_e32 v130, v120
	v_mul_f32_e32 v120, 0xbfb8aa3b, v121
	v_exp_f32_e32 v120, v120
	v_pk_fma_f32 v[126:127], v[126:127], v[170:171], v[70:71] op_sel_hi:[1,0,1]
	v_mul_f32_e32 v124, 0xbfb8aa3b, v124
	v_mul_f32_e32 v125, 0xbfb8aa3b, v125
	v_add_f32_e32 v120, 1.0, v120
	v_rcp_f32_e32 v131, v120
	v_mul_f32_e32 v120, 0xbfb8aa3b, v122
	v_exp_f32_e32 v120, v120
	v_exp_f32_e32 v124, v124
	v_exp_f32_e32 v125, v125
	v_mul_f32_e32 v126, 0xbfb8aa3b, v126
	v_add_f32_e32 v120, 1.0, v120
	v_mul_f32_e32 v127, 0xbfb8aa3b, v127
	v_rcp_f32_e32 v132, v120
	v_mul_f32_e32 v120, 0xbfb8aa3b, v123
	v_exp_f32_e32 v126, v126
	v_exp_f32_e32 v127, v127
	v_exp_f32_e32 v120, v120
	v_add_f32_e32 v124, 1.0, v124
	v_add_f32_e32 v125, 1.0, v125
	v_pk_fma_f32 v[112:113], v[112:113], v[170:171], v[48:49] op_sel_hi:[1,0,1]
	v_rcp_f32_e32 v124, v124
	v_rcp_f32_e32 v125, v125
	v_add_f32_e32 v126, 1.0, v126
	v_add_f32_e32 v127, 1.0, v127
	v_add_f32_e32 v120, 1.0, v120
	v_mul_f32_e32 v112, 0xbfb8aa3b, v112
	v_rcp_f32_e32 v126, v126
	v_rcp_f32_e32 v127, v127
	v_rcp_f32_e32 v123, v120
	v_exp_f32_e32 v112, v112
	v_lshlrev_b64 v[128:129], 14, v[172:173]
	v_cvt_pk_bf16_f32 v120, v124, v125
	v_lshl_add_u64 v[124:125], s[4:5], 0, v[128:129]
	v_cvt_pk_bf16_f32 v121, v126, v127
	v_cvt_pk_bf16_f32 v122, v130, v131
	v_cvt_pk_bf16_f32 v123, v132, v123
	v_lshl_add_u64 v[124:125], v[124:125], 0, v[138:139]
	v_add_f32_e32 v112, 1.0, v112
	global_store_dwordx4 v[124:125], v[120:123], off
	v_pk_fma_f32 v[114:115], v[114:115], v[170:171], v[50:51] op_sel_hi:[1,0,1]
	v_pk_fma_f32 v[118:119], v[118:119], v[170:171], v[54:55] op_sel_hi:[1,0,1]
	v_rcp_f32_e32 v120, v112
	v_mul_f32_e32 v112, 0xbfb8aa3b, v113
	v_exp_f32_e32 v112, v112
	v_pk_fma_f32 v[116:117], v[116:117], v[170:171], v[52:53] op_sel_hi:[1,0,1]
	v_mul_f32_e32 v118, 0xbfb8aa3b, v118
	v_mul_f32_e32 v116, 0xbfb8aa3b, v116
	v_add_f32_e32 v112, 1.0, v112
	v_rcp_f32_e32 v121, v112
	v_mul_f32_e32 v112, 0xbfb8aa3b, v114
	v_exp_f32_e32 v112, v112
	v_mul_f32_e32 v117, 0xbfb8aa3b, v117
	v_mul_f32_e32 v119, 0xbfb8aa3b, v119
	v_exp_f32_e32 v116, v116
	v_add_f32_e32 v112, 1.0, v112
	v_rcp_f32_e32 v122, v112
; __device__ __forceinline__ unsigned pk2(float lo, float hi) { const f32x2 v = {lo, hi}; return __builtin_bit_cast(unsigned, __builtin_convertvector(v, bf16x2_t)); }
; __device__ __forceinline__ float sigmoidf_(float x) { return __builtin_amdgcn_rcpf(1.f + __builtin_amdgcn_exp2f(-x * LOG2E)); }
; #define EPI_LOOP _Pragma("unroll") for (int ai = 0; ai < 2; ++ai) _Pragma("unroll") for (int m = 0; m < 4; ++m) _Pragma("unroll") for (int bj = 0; bj < 2; ++bj)
;     __device__ __forceinline__ void operator()(const f32x4 (&acc)[2][2][4][2], const Unit& un, int wr, int wc, int fr, int fq) const {
;     ...
;         EPI_LOOP { const int row = rbase + ai * 128 + m * 16, col = cw + bj * 128; const float r = rr[ai][m];
;             f32x4 v0 = acc[ai][bj][m][0] * r + s0[bj], v1 = acc[ai][bj][m][1] * r + s1[bj];
;             v0 = (f32x4){sigmoidf_(v0.x), sigmoidf_(v0.y), sigmoidf_(v0.z), sigmoidf_(v0.w)}; v1 = (f32x4){sigmoidf_(v1.x), sigmoidf_(v1.y), sigmoidf_(v1.z), sigmoidf_(v1.w)};
;             u32x4 w; w.x = pk2(v0.x, v0.y); w.y = pk2(v0.z, v0.w); w.z = pk2(v1.x, v1.y); w.w = pk2(v1.z, v1.w);
;             *(u32x4*)(o + (size_t)row * DFF + col) = w; }
	v_mul_f32_e32 v112, 0xbfb8aa3b, v115
	v_exp_f32_e32 v117, v117
	v_exp_f32_e32 v118, v118
	v_exp_f32_e32 v119, v119
	v_exp_f32_e32 v112, v112
	v_pk_fma_f32 v[104:105], v[104:105], v[166:167], v[64:65] op_sel_hi:[1,0,1]
	v_add_f32_e32 v116, 1.0, v116
	v_add_f32_e32 v117, 1.0, v117
	v_add_f32_e32 v118, 1.0, v118
	v_add_f32_e32 v119, 1.0, v119
	v_add_f32_e32 v112, 1.0, v112
	v_mul_f32_e32 v104, 0xbfb8aa3b, v104
	v_rcp_f32_e32 v116, v116
	v_rcp_f32_e32 v117, v117
	v_rcp_f32_e32 v118, v118
	v_rcp_f32_e32 v119, v119
	v_rcp_f32_e32 v115, v112
	v_exp_f32_e32 v104, v104
	v_cvt_pk_bf16_f32 v112, v116, v117
	v_cvt_pk_bf16_f32 v113, v118, v119
	v_cvt_pk_bf16_f32 v114, v120, v121
	v_cvt_pk_bf16_f32 v115, v122, v115
	v_add_f32_e32 v104, 1.0, v104
	global_store_dwordx4 v[124:125], v[112:115], off offset:256
	v_pk_fma_f32 v[106:107], v[106:107], v[166:167], v[66:67] op_sel_hi:[1,0,1]
	v_pk_fma_f32 v[108:109], v[108:109], v[166:167], v[68:69] op_sel_hi:[1,0,1]
	v_rcp_f32_e32 v114, v104
	v_mul_f32_e32 v104, 0xbfb8aa3b, v105
	v_exp_f32_e32 v104, v104
	v_pk_fma_f32 v[110:111], v[110:111], v[166:167], v[70:71] op_sel_hi:[1,0,1]
	v_mul_f32_e32 v108, 0xbfb8aa3b, v108
	v_mul_f32_e32 v109, 0xbfb8aa3b, v109
	v_add_f32_e32 v104, 1.0, v104
	v_rcp_f32_e32 v115, v104
	v_mul_f32_e32 v104, 0xbfb8aa3b, v106
	v_exp_f32_e32 v104, v104
	v_exp_f32_e32 v108, v108
	v_exp_f32_e32 v109, v109
	v_mul_f32_e32 v110, 0xbfb8aa3b, v110
	v_add_f32_e32 v104, 1.0, v104
	v_mul_f32_e32 v111, 0xbfb8aa3b, v111
	v_rcp_f32_e32 v116, v104
	v_mul_f32_e32 v104, 0xbfb8aa3b, v107
	v_exp_f32_e32 v110, v110
	v_exp_f32_e32 v111, v111
	v_exp_f32_e32 v104, v104
	v_add_f32_e32 v108, 1.0, v108
	v_add_f32_e32 v109, 1.0, v109
	v_pk_fma_f32 v[96:97], v[96:97], v[166:167], v[48:49] op_sel_hi:[1,0,1]
	v_rcp_f32_e32 v108, v108
	v_rcp_f32_e32 v109, v109
	v_add_f32_e32 v110, 1.0, v110
	v_add_f32_e32 v111, 1.0, v111
	v_add_f32_e32 v104, 1.0, v104
	v_mul_f32_e32 v96, 0xbfb8aa3b, v96
	v_rcp_f32_e32 v110, v110
	v_rcp_f32_e32 v111, v111
	v_rcp_f32_e32 v107, v104
	v_exp_f32_e32 v96, v96
	v_lshlrev_b64 v[112:113], 14, v[168:169]
	v_cvt_pk_bf16_f32 v104, v108, v109
	v_lshl_add_u64 v[108:109], s[4:5], 0, v[112:113]
	v_cvt_pk_bf16_f32 v105, v110, v111
	v_cvt_pk_bf16_f32 v106, v114, v115
	v_cvt_pk_bf16_f32 v107, v116, v107
	v_lshl_add_u64 v[108:109], v[108:109], 0, v[138:139]
	v_add_f32_e32 v96, 1.0, v96
	global_store_dwordx4 v[108:109], v[104:107], off
	v_pk_fma_f32 v[98:99], v[98:99], v[166:167], v[50:51] op_sel_hi:[1,0,1]
	v_pk_fma_f32 v[102:103], v[102:103], v[166:167], v[54:55] op_sel_hi:[1,0,1]
	v_rcp_f32_e32 v104, v96
	v_mul_f32_e32 v96, 0xbfb8aa3b, v97
	v_exp_f32_e32 v96, v96
	v_pk_fma_f32 v[100:101], v[100:101], v[166:167], v[52:53] op_sel_hi:[1,0,1]
	v_mul_f32_e32 v102, 0xbfb8aa3b, v102
	v_mul_f32_e32 v100, 0xbfb8aa3b, v100
	v_add_f32_e32 v96, 1.0, v96
	v_rcp_f32_e32 v105, v96
	v_mul_f32_e32 v96, 0xbfb8aa3b, v98
	v_exp_f32_e32 v96, v96
	v_mul_f32_e32 v101, 0xbfb8aa3b, v101
	v_mul_f32_e32 v103, 0xbfb8aa3b, v103
	v_exp_f32_e32 v100, v100
	v_add_f32_e32 v96, 1.0, v96
	v_rcp_f32_e32 v106, v96
	v_mul_f32_e32 v96, 0xbfb8aa3b, v99
	v_exp_f32_e32 v101, v101
	v_exp_f32_e32 v102, v102
	v_exp_f32_e32 v103, v103
	v_exp_f32_e32 v96, v96
	v_pk_fma_f32 v[88:89], v[88:89], v[162:163], v[64:65] op_sel_hi:[1,0,1]
	v_add_f32_e32 v100, 1.0, v100
	v_add_f32_e32 v101, 1.0, v101
	v_add_f32_e32 v102, 1.0, v102
	v_add_f32_e32 v103, 1.0, v103
	v_add_f32_e32 v96, 1.0, v96
	v_mul_f32_e32 v88, 0xbfb8aa3b, v88
	v_rcp_f32_e32 v100, v100
	v_rcp_f32_e32 v101, v101
	v_rcp_f32_e32 v102, v102
	v_rcp_f32_e32 v103, v103
	v_rcp_f32_e32 v99, v96
	v_exp_f32_e32 v88, v88
	v_cvt_pk_bf16_f32 v96, v100, v101
	v_cvt_pk_bf16_f32 v97, v102, v103
	v_cvt_pk_bf16_f32 v98, v104, v105
	v_cvt_pk_bf16_f32 v99, v106, v99
	v_add_f32_e32 v88, 1.0, v88
	global_store_dwordx4 v[108:109], v[96:99], off offset:256
	v_pk_fma_f32 v[90:91], v[90:91], v[162:163], v[66:67] op_sel_hi:[1,0,1]
	v_pk_fma_f32 v[92:93], v[92:93], v[162:163], v[68:69] op_sel_hi:[1,0,1]
	v_rcp_f32_e32 v98, v88
	v_mul_f32_e32 v88, 0xbfb8aa3b, v89
	v_exp_f32_e32 v88, v88
	v_pk_fma_f32 v[94:95], v[94:95], v[162:163], v[70:71] op_sel_hi:[1,0,1]
	v_mul_f32_e32 v92, 0xbfb8aa3b, v92
	v_mul_f32_e32 v93, 0xbfb8aa3b, v93
	v_add_f32_e32 v88, 1.0, v88
	v_rcp_f32_e32 v99, v88
	v_mul_f32_e32 v88, 0xbfb8aa3b, v90
	v_exp_f32_e32 v88, v88
	v_exp_f32_e32 v92, v92
	v_exp_f32_e32 v93, v93
	v_mul_f32_e32 v94, 0xbfb8aa3b, v94
	v_add_f32_e32 v88, 1.0, v88
	v_mul_f32_e32 v95, 0xbfb8aa3b, v95
	v_rcp_f32_e32 v100, v88
	v_mul_f32_e32 v88, 0xbfb8aa3b, v91
	v_exp_f32_e32 v94, v94
	v_exp_f32_e32 v95, v95
	v_exp_f32_e32 v88, v88
	v_add_f32_e32 v92, 1.0, v92
	v_add_f32_e32 v93, 1.0, v93
	v_pk_fma_f32 v[80:81], v[80:81], v[162:163], v[48:49] op_sel_hi:[1,0,1]
	v_rcp_f32_e32 v92, v92
	v_rcp_f32_e32 v93, v93
	v_add_f32_e32 v94, 1.0, v94
	v_add_f32_e32 v95, 1.0, v95
	v_add_f32_e32 v88, 1.0, v88
	v_mul_f32_e32 v80, 0xbfb8aa3b, v80
	v_rcp_f32_e32 v94, v94
	v_rcp_f32_e32 v95, v95
	v_rcp_f32_e32 v91, v88
	v_exp_f32_e32 v80, v80
	v_lshlrev_b64 v[96:97], 14, v[164:165]
	v_cvt_pk_bf16_f32 v88, v92, v93
	v_lshl_add_u64 v[92:93], s[4:5], 0, v[96:97]
	v_cvt_pk_bf16_f32 v89, v94, v95
	v_cvt_pk_bf16_f32 v90, v98, v99
	v_cvt_pk_bf16_f32 v91, v100, v91
	v_lshl_add_u64 v[92:93], v[92:93], 0, v[138:139]
	v_add_f32_e32 v80, 1.0, v80
	global_store_dwordx4 v[92:93], v[88:91], off
	v_pk_fma_f32 v[82:83], v[82:83], v[162:163], v[50:51] op_sel_hi:[1,0,1]
	v_pk_fma_f32 v[86:87], v[86:87], v[162:163], v[54:55] op_sel_hi:[1,0,1]
	v_rcp_f32_e32 v88, v80
	v_mul_f32_e32 v80, 0xbfb8aa3b, v81
	v_exp_f32_e32 v80, v80
	v_pk_fma_f32 v[84:85], v[84:85], v[162:163], v[52:53] op_sel_hi:[1,0,1]
; __device__ __forceinline__ unsigned pk2(float lo, float hi) { const f32x2 v = {lo, hi}; return __builtin_bit_cast(unsigned, __builtin_convertvector(v, bf16x2_t)); }
; __device__ __forceinline__ float sigmoidf_(float x) { return __builtin_amdgcn_rcpf(1.f + __builtin_amdgcn_exp2f(-x * LOG2E)); }
; #define EPI_LOOP _Pragma("unroll") for (int ai = 0; ai < 2; ++ai) _Pragma("unroll") for (int m = 0; m < 4; ++m) _Pragma("unroll") for (int bj = 0; bj < 2; ++bj)
;     __device__ __forceinline__ void operator()(const f32x4 (&acc)[2][2][4][2], const Unit& un, int wr, int wc, int fr, int fq) const {
;     ...
;         EPI_LOOP { const int row = rbase + ai * 128 + m * 16, col = cw + bj * 128; const float r = rr[ai][m];
;             f32x4 v0 = acc[ai][bj][m][0] * r + s0[bj], v1 = acc[ai][bj][m][1] * r + s1[bj];
;             v0 = (f32x4){sigmoidf_(v0.x), sigmoidf_(v0.y), sigmoidf_(v0.z), sigmoidf_(v0.w)}; v1 = (f32x4){sigmoidf_(v1.x), sigmoidf_(v1.y), sigmoidf_(v1.z), sigmoidf_(v1.w)};
;             u32x4 w; w.x = pk2(v0.x, v0.y); w.y = pk2(v0.z, v0.w); w.z = pk2(v1.x, v1.y); w.w = pk2(v1.z, v1.w);
;             *(u32x4*)(o + (size_t)row * DFF + col) = w; }
	v_mul_f32_e32 v86, 0xbfb8aa3b, v86
	v_mul_f32_e32 v84, 0xbfb8aa3b, v84
	v_add_f32_e32 v80, 1.0, v80
	v_rcp_f32_e32 v89, v80
	v_mul_f32_e32 v80, 0xbfb8aa3b, v82
	v_exp_f32_e32 v80, v80
	v_mul_f32_e32 v85, 0xbfb8aa3b, v85
	v_mul_f32_e32 v87, 0xbfb8aa3b, v87
	v_exp_f32_e32 v84, v84
	v_add_f32_e32 v80, 1.0, v80
	v_rcp_f32_e32 v90, v80
	v_mul_f32_e32 v80, 0xbfb8aa3b, v83
	v_exp_f32_e32 v85, v85
	v_exp_f32_e32 v86, v86
	v_exp_f32_e32 v87, v87
	v_exp_f32_e32 v80, v80
	v_pk_fma_f32 v[72:73], v[72:73], v[160:161], v[64:65] op_sel_hi:[1,0,1]
	v_add_f32_e32 v84, 1.0, v84
	v_add_f32_e32 v85, 1.0, v85
	v_add_f32_e32 v86, 1.0, v86
	v_add_f32_e32 v87, 1.0, v87
	v_add_f32_e32 v80, 1.0, v80
	v_mul_f32_e32 v72, 0xbfb8aa3b, v72
	v_rcp_f32_e32 v84, v84
	v_rcp_f32_e32 v85, v85
	v_rcp_f32_e32 v86, v86
	v_rcp_f32_e32 v87, v87
	v_rcp_f32_e32 v83, v80
	v_exp_f32_e32 v72, v72
	v_cvt_pk_bf16_f32 v80, v84, v85
	v_cvt_pk_bf16_f32 v81, v86, v87
	v_cvt_pk_bf16_f32 v82, v88, v89
	v_cvt_pk_bf16_f32 v83, v90, v83
	v_add_f32_e32 v72, 1.0, v72
	global_store_dwordx4 v[92:93], v[80:83], off offset:256
	v_pk_fma_f32 v[74:75], v[74:75], v[160:161], v[66:67] op_sel_hi:[1,0,1]
	v_pk_fma_f32 v[78:79], v[78:79], v[160:161], v[70:71] op_sel_hi:[1,0,1]
	v_rcp_f32_e32 v80, v72
	v_mul_f32_e32 v72, 0xbfb8aa3b, v73
	v_exp_f32_e32 v72, v72
	v_pk_fma_f32 v[76:77], v[76:77], v[160:161], v[68:69] op_sel_hi:[1,0,1]
	v_mul_f32_e32 v78, 0xbfb8aa3b, v78
	v_mul_f32_e32 v79, 0xbfb8aa3b, v79
	v_add_f32_e32 v72, 1.0, v72
	v_rcp_f32_e32 v81, v72
	v_mul_f32_e32 v72, 0xbfb8aa3b, v74
	v_exp_f32_e32 v72, v72
	v_mul_f32_e32 v76, 0xbfb8aa3b, v76
	v_mul_f32_e32 v77, 0xbfb8aa3b, v77
	v_exp_f32_e32 v78, v78
	v_add_f32_e32 v72, 1.0, v72
	v_exp_f32_e32 v79, v79
	v_rcp_f32_e32 v82, v72
	v_mul_f32_e32 v72, 0xbfb8aa3b, v75
	v_exp_f32_e32 v76, v76
	v_exp_f32_e32 v77, v77
	v_exp_f32_e32 v72, v72
	v_add_f32_e32 v78, 1.0, v78
	v_add_f32_e32 v79, 1.0, v79
	v_pk_fma_f32 v[56:57], v[56:57], v[160:161], v[48:49] op_sel_hi:[1,0,1]
	v_add_f32_e32 v76, 1.0, v76
	v_add_f32_e32 v77, 1.0, v77
	v_rcp_f32_e32 v78, v78
	v_rcp_f32_e32 v79, v79
	v_add_f32_e32 v72, 1.0, v72
	v_mul_f32_e32 v56, 0xbfb8aa3b, v56
	v_rcp_f32_e32 v76, v76
	v_rcp_f32_e32 v77, v77
	v_rcp_f32_e32 v75, v72
	v_exp_f32_e32 v56, v56
	v_cvt_pk_bf16_f32 v73, v78, v79
	v_add_co_u32_e32 v78, vcc, s78, v136
	v_cvt_pk_bf16_f32 v72, v76, v77
	v_cvt_pk_bf16_f32 v74, v80, v81
	v_cvt_pk_bf16_f32 v75, v82, v75
	v_addc_co_u32_e32 v79, vcc, 0, v137, vcc
	v_add_f32_e32 v56, 1.0, v56
	global_store_dwordx4 v[78:79], v[72:75], off
	v_pk_fma_f32 v[58:59], v[58:59], v[160:161], v[50:51] op_sel_hi:[1,0,1]
	v_pk_fma_f32 v[62:63], v[62:63], v[160:161], v[54:55] op_sel_hi:[1,0,1]
	v_rcp_f32_e32 v72, v56
	v_mul_f32_e32 v56, 0xbfb8aa3b, v57
	v_exp_f32_e32 v56, v56
	v_pk_fma_f32 v[60:61], v[60:61], v[160:161], v[52:53] op_sel_hi:[1,0,1]
	v_mul_f32_e32 v62, 0xbfb8aa3b, v62
	v_mul_f32_e32 v60, 0xbfb8aa3b, v60
	v_add_f32_e32 v56, 1.0, v56
	v_rcp_f32_e32 v73, v56
	v_mul_f32_e32 v56, 0xbfb8aa3b, v58
	v_exp_f32_e32 v56, v56
	v_mul_f32_e32 v61, 0xbfb8aa3b, v61
	v_mul_f32_e32 v63, 0xbfb8aa3b, v63
	v_exp_f32_e32 v60, v60
	v_add_f32_e32 v56, 1.0, v56
	v_rcp_f32_e32 v74, v56
	v_mul_f32_e32 v56, 0xbfb8aa3b, v59
	v_exp_f32_e32 v61, v61
	v_exp_f32_e32 v62, v62
	v_exp_f32_e32 v63, v63
	v_exp_f32_e32 v56, v56
	v_pk_fma_f32 v[40:41], v[40:41], v[158:159], v[64:65] op_sel_hi:[1,0,1]
	v_add_f32_e32 v60, 1.0, v60
	v_add_f32_e32 v61, 1.0, v61
	v_add_f32_e32 v62, 1.0, v62
	v_add_f32_e32 v63, 1.0, v63
	v_add_f32_e32 v56, 1.0, v56
	v_mul_f32_e32 v40, 0xbfb8aa3b, v40
	v_rcp_f32_e32 v60, v60
	v_rcp_f32_e32 v61, v61
	v_rcp_f32_e32 v62, v62
	v_rcp_f32_e32 v63, v63
	v_rcp_f32_e32 v59, v56
	v_exp_f32_e32 v40, v40
	v_lshl_add_u64 v[76:77], v[136:137], 0, s[56:57]
	v_cvt_pk_bf16_f32 v56, v60, v61
	v_cvt_pk_bf16_f32 v57, v62, v63
	v_cvt_pk_bf16_f32 v58, v72, v73
	v_cvt_pk_bf16_f32 v59, v74, v59
	v_add_f32_e32 v40, 1.0, v40
	global_store_dwordx4 v[76:77], v[56:59], off offset:256
	v_pk_fma_f32 v[42:43], v[42:43], v[158:159], v[66:67] op_sel_hi:[1,0,1]
	v_pk_fma_f32 v[46:47], v[46:47], v[158:159], v[70:71] op_sel_hi:[1,0,1]
	v_rcp_f32_e32 v56, v40
	v_mul_f32_e32 v40, 0xbfb8aa3b, v41
	v_exp_f32_e32 v40, v40
	v_pk_fma_f32 v[44:45], v[44:45], v[158:159], v[68:69] op_sel_hi:[1,0,1]
	v_mul_f32_e32 v46, 0xbfb8aa3b, v46
	v_mul_f32_e32 v47, 0xbfb8aa3b, v47
	v_add_f32_e32 v40, 1.0, v40
	v_rcp_f32_e32 v57, v40
	v_mul_f32_e32 v40, 0xbfb8aa3b, v42
	v_exp_f32_e32 v40, v40
	v_mul_f32_e32 v44, 0xbfb8aa3b, v44
	v_mul_f32_e32 v45, 0xbfb8aa3b, v45
	v_exp_f32_e32 v46, v46
	v_add_f32_e32 v40, 1.0, v40
	v_exp_f32_e32 v47, v47
	v_rcp_f32_e32 v58, v40
	v_mul_f32_e32 v40, 0xbfb8aa3b, v43
	v_exp_f32_e32 v44, v44
	v_exp_f32_e32 v45, v45
	v_exp_f32_e32 v40, v40
	v_add_f32_e32 v46, 1.0, v46
	v_add_f32_e32 v47, 1.0, v47
	v_pk_fma_f32 v[32:33], v[32:33], v[158:159], v[48:49] op_sel_hi:[1,0,1]
	v_add_f32_e32 v44, 1.0, v44
	v_add_f32_e32 v45, 1.0, v45
	v_rcp_f32_e32 v46, v46
	v_rcp_f32_e32 v47, v47
	v_add_f32_e32 v40, 1.0, v40
	v_mul_f32_e32 v32, 0xbfb8aa3b, v32
	v_rcp_f32_e32 v44, v44
	v_rcp_f32_e32 v45, v45
	v_rcp_f32_e32 v43, v40
	v_exp_f32_e32 v32, v32
	v_cvt_pk_bf16_f32 v41, v46, v47
	v_add_co_u32_e32 v46, vcc, s74, v136
	v_cvt_pk_bf16_f32 v40, v44, v45
	v_cvt_pk_bf16_f32 v42, v56, v57
	v_cvt_pk_bf16_f32 v43, v58, v43
	v_addc_co_u32_e32 v47, vcc, 0, v137, vcc
	v_add_f32_e32 v32, 1.0, v32
	global_store_dwordx4 v[46:47], v[40:43], off
	v_pk_fma_f32 v[34:35], v[34:35], v[158:159], v[50:51] op_sel_hi:[1,0,1]
	v_pk_fma_f32 v[38:39], v[38:39], v[158:159], v[54:55] op_sel_hi:[1,0,1]
	v_rcp_f32_e32 v40, v32
	v_mul_f32_e32 v32, 0xbfb8aa3b, v33
; #define PG8_BAR __builtin_amdgcn_s_barrier()
; __device__ __forceinline__ unsigned pk2(float lo, float hi) { const f32x2 v = {lo, hi}; return __builtin_bit_cast(unsigned, __builtin_convertvector(v, bf16x2_t)); }
; __device__ __forceinline__ float sigmoidf_(float x) { return __builtin_amdgcn_rcpf(1.f + __builtin_amdgcn_exp2f(-x * LOG2E)); }
; #define EPI_LOOP _Pragma("unroll") for (int ai = 0; ai < 2; ++ai) _Pragma("unroll") for (int m = 0; m < 4; ++m) _Pragma("unroll") for (int bj = 0; bj < 2; ++bj)
; template <class Epi, class Sched, bool ALIGN_EPI = false, bool SP2 = false>
; __device__ __forceinline__ void gemm_phase(PG8_LAS unsigned char* lds, const Gemm g, const Sched& S, const Epi& E, const int tid) {
;     ...
;         if (!has_next) break;
; #pragma unroll
;         for (int a = 0; a < 2; ++a)
; #pragma unroll
;             for (int b = 0; b < 2; ++b)
; #pragma unroll
;                 for (int m = 0; m < 4; ++m)
; #pragma unroll
;                     for (int n = 0; n < 2; ++n) acc[a][b][m][n] = (f32x4){0.f, 0.f, 0.f, 0.f};
;         cur = nxt; cA = nA; cB = nB; ++ui;
;         if constexpr (ALIGN_EPI) { if (wr == 1) PG8_BAR; }
;     __device__ __forceinline__ void operator()(const f32x4 (&acc)[2][2][4][2], const Unit& un, int wr, int wc, int fr, int fq) const {
;     ...
;         EPI_LOOP { const int row = rbase + ai * 128 + m * 16, col = cw + bj * 128; const float r = rr[ai][m];
;             f32x4 v0 = acc[ai][bj][m][0] * r + s0[bj], v1 = acc[ai][bj][m][1] * r + s1[bj];
;             v0 = (f32x4){sigmoidf_(v0.x), sigmoidf_(v0.y), sigmoidf_(v0.z), sigmoidf_(v0.w)}; v1 = (f32x4){sigmoidf_(v1.x), sigmoidf_(v1.y), sigmoidf_(v1.z), sigmoidf_(v1.w)};
;             u32x4 w; w.x = pk2(v0.x, v0.y); w.y = pk2(v0.z, v0.w); w.z = pk2(v1.x, v1.y); w.w = pk2(v1.z, v1.w);
;             *(u32x4*)(o + (size_t)row * DFF + col) = w; }
	v_exp_f32_e32 v32, v32
	v_pk_fma_f32 v[36:37], v[36:37], v[158:159], v[52:53] op_sel_hi:[1,0,1]
	v_mul_f32_e32 v38, 0xbfb8aa3b, v38
	v_mul_f32_e32 v36, 0xbfb8aa3b, v36
	v_add_f32_e32 v32, 1.0, v32
	v_rcp_f32_e32 v41, v32
	v_mul_f32_e32 v32, 0xbfb8aa3b, v34
	v_exp_f32_e32 v32, v32
	v_mul_f32_e32 v37, 0xbfb8aa3b, v37
	v_mul_f32_e32 v39, 0xbfb8aa3b, v39
	v_exp_f32_e32 v36, v36
	v_add_f32_e32 v32, 1.0, v32
	v_rcp_f32_e32 v42, v32
	v_mul_f32_e32 v32, 0xbfb8aa3b, v35
	v_exp_f32_e32 v37, v37
	v_exp_f32_e32 v38, v38
	v_exp_f32_e32 v39, v39
	v_exp_f32_e32 v32, v32
	v_pk_fma_f32 v[24:25], v[24:25], v[156:157], v[64:65] op_sel_hi:[1,0,1]
	v_add_f32_e32 v36, 1.0, v36
	v_add_f32_e32 v37, 1.0, v37
	v_add_f32_e32 v38, 1.0, v38
	v_add_f32_e32 v39, 1.0, v39
	v_add_f32_e32 v32, 1.0, v32
	v_mul_f32_e32 v24, 0xbfb8aa3b, v24
	v_rcp_f32_e32 v36, v36
	v_rcp_f32_e32 v37, v37
	v_rcp_f32_e32 v38, v38
	v_rcp_f32_e32 v39, v39
	v_rcp_f32_e32 v35, v32
	v_exp_f32_e32 v24, v24
	v_lshl_add_u64 v[44:45], v[136:137], 0, s[20:21]
	v_cvt_pk_bf16_f32 v32, v36, v37
	v_cvt_pk_bf16_f32 v33, v38, v39
	v_cvt_pk_bf16_f32 v34, v40, v41
	v_cvt_pk_bf16_f32 v35, v42, v35
	v_add_f32_e32 v24, 1.0, v24
	global_store_dwordx4 v[44:45], v[32:35], off offset:256
	v_pk_fma_f32 v[26:27], v[26:27], v[156:157], v[66:67] op_sel_hi:[1,0,1]
	v_pk_fma_f32 v[30:31], v[30:31], v[156:157], v[70:71] op_sel_hi:[1,0,1]
	v_rcp_f32_e32 v32, v24
	v_mul_f32_e32 v24, 0xbfb8aa3b, v25
	v_exp_f32_e32 v24, v24
	v_pk_fma_f32 v[28:29], v[28:29], v[156:157], v[68:69] op_sel_hi:[1,0,1]
	v_mul_f32_e32 v30, 0xbfb8aa3b, v30
	v_mul_f32_e32 v31, 0xbfb8aa3b, v31
	v_add_f32_e32 v24, 1.0, v24
	v_rcp_f32_e32 v33, v24
	v_mul_f32_e32 v24, 0xbfb8aa3b, v26
	v_exp_f32_e32 v24, v24
	v_mul_f32_e32 v28, 0xbfb8aa3b, v28
	v_mul_f32_e32 v29, 0xbfb8aa3b, v29
	v_exp_f32_e32 v30, v30
	v_add_f32_e32 v24, 1.0, v24
	v_exp_f32_e32 v31, v31
	v_rcp_f32_e32 v34, v24
	v_mul_f32_e32 v24, 0xbfb8aa3b, v27
	v_exp_f32_e32 v28, v28
	v_exp_f32_e32 v29, v29
	v_exp_f32_e32 v24, v24
	v_add_f32_e32 v30, 1.0, v30
	v_add_f32_e32 v31, 1.0, v31
	v_pk_fma_f32 v[16:17], v[16:17], v[156:157], v[48:49] op_sel_hi:[1,0,1]
	v_add_f32_e32 v28, 1.0, v28
	v_add_f32_e32 v29, 1.0, v29
	v_rcp_f32_e32 v30, v30
	v_rcp_f32_e32 v31, v31
	v_add_f32_e32 v24, 1.0, v24
	v_mul_f32_e32 v16, 0xbfb8aa3b, v16
	v_rcp_f32_e32 v28, v28
	v_rcp_f32_e32 v29, v29
	v_rcp_f32_e32 v27, v24
	v_exp_f32_e32 v16, v16
	v_cvt_pk_bf16_f32 v25, v30, v31
	v_add_co_u32_e32 v30, vcc, s71, v136
	v_cvt_pk_bf16_f32 v24, v28, v29
	v_cvt_pk_bf16_f32 v26, v32, v33
	v_cvt_pk_bf16_f32 v27, v34, v27
	v_addc_co_u32_e32 v31, vcc, 0, v137, vcc
	v_add_f32_e32 v16, 1.0, v16
	global_store_dwordx4 v[30:31], v[24:27], off
	v_pk_fma_f32 v[18:19], v[18:19], v[156:157], v[50:51] op_sel_hi:[1,0,1]
	v_pk_fma_f32 v[22:23], v[22:23], v[156:157], v[54:55] op_sel_hi:[1,0,1]
	v_rcp_f32_e32 v24, v16
	v_mul_f32_e32 v16, 0xbfb8aa3b, v17
	v_exp_f32_e32 v16, v16
	v_pk_fma_f32 v[20:21], v[20:21], v[156:157], v[52:53] op_sel_hi:[1,0,1]
	v_mul_f32_e32 v22, 0xbfb8aa3b, v22
	v_mul_f32_e32 v20, 0xbfb8aa3b, v20
	v_add_f32_e32 v16, 1.0, v16
	v_rcp_f32_e32 v25, v16
	v_mul_f32_e32 v16, 0xbfb8aa3b, v18
	v_exp_f32_e32 v16, v16
	v_mul_f32_e32 v21, 0xbfb8aa3b, v21
	v_mul_f32_e32 v23, 0xbfb8aa3b, v23
	v_exp_f32_e32 v20, v20
	v_add_f32_e32 v16, 1.0, v16
	v_rcp_f32_e32 v26, v16
	v_mul_f32_e32 v16, 0xbfb8aa3b, v19
	v_exp_f32_e32 v21, v21
	v_exp_f32_e32 v22, v22
	v_exp_f32_e32 v23, v23
	v_exp_f32_e32 v16, v16
	v_pk_fma_f32 v[8:9], v[8:9], v[154:155], v[64:65] op_sel_hi:[1,0,1]
	v_add_f32_e32 v20, 1.0, v20
	v_add_f32_e32 v21, 1.0, v21
	v_add_f32_e32 v22, 1.0, v22
	v_add_f32_e32 v23, 1.0, v23
	v_add_f32_e32 v16, 1.0, v16
	v_mul_f32_e32 v8, 0xbfb8aa3b, v8
	v_rcp_f32_e32 v20, v20
	v_rcp_f32_e32 v21, v21
	v_rcp_f32_e32 v22, v22
	v_rcp_f32_e32 v23, v23
	v_rcp_f32_e32 v19, v16
	v_exp_f32_e32 v8, v8
	s_mov_b64 s[20:21], 0x280000
	v_lshl_add_u64 v[28:29], v[136:137], 0, s[20:21]
	v_cvt_pk_bf16_f32 v16, v20, v21
	v_cvt_pk_bf16_f32 v17, v22, v23
	v_cvt_pk_bf16_f32 v18, v24, v25
	v_cvt_pk_bf16_f32 v19, v26, v19
	v_add_f32_e32 v8, 1.0, v8
	global_store_dwordx4 v[28:29], v[16:19], off offset:256
	v_pk_fma_f32 v[10:11], v[10:11], v[154:155], v[66:67] op_sel_hi:[1,0,1]
	v_pk_fma_f32 v[14:15], v[14:15], v[154:155], v[70:71] op_sel_hi:[1,0,1]
	v_rcp_f32_e32 v16, v8
	v_mul_f32_e32 v8, 0xbfb8aa3b, v9
	v_exp_f32_e32 v8, v8
	v_pk_fma_f32 v[12:13], v[12:13], v[154:155], v[68:69] op_sel_hi:[1,0,1]
	v_mul_f32_e32 v14, 0xbfb8aa3b, v14
	v_mul_f32_e32 v15, 0xbfb8aa3b, v15
	v_add_f32_e32 v8, 1.0, v8
	v_rcp_f32_e32 v17, v8
	v_mul_f32_e32 v8, 0xbfb8aa3b, v10
	v_exp_f32_e32 v8, v8
	v_mul_f32_e32 v12, 0xbfb8aa3b, v12
	v_mul_f32_e32 v13, 0xbfb8aa3b, v13
	v_exp_f32_e32 v14, v14
	v_add_f32_e32 v8, 1.0, v8
	v_exp_f32_e32 v15, v15
	v_rcp_f32_e32 v18, v8
	v_mul_f32_e32 v8, 0xbfb8aa3b, v11
	v_exp_f32_e32 v12, v12
	v_exp_f32_e32 v13, v13
	v_exp_f32_e32 v8, v8
	v_add_f32_e32 v14, 1.0, v14
	v_add_f32_e32 v15, 1.0, v15
	v_pk_fma_f32 v[0:1], v[0:1], v[154:155], v[48:49] op_sel_hi:[1,0,1]
	v_add_f32_e32 v12, 1.0, v12
	v_add_f32_e32 v13, 1.0, v13
	v_rcp_f32_e32 v14, v14
	v_rcp_f32_e32 v15, v15
	v_add_f32_e32 v8, 1.0, v8
	v_mul_f32_e32 v0, 0xbfb8aa3b, v0
	v_rcp_f32_e32 v12, v12
	v_rcp_f32_e32 v13, v13
	v_rcp_f32_e32 v11, v8
	v_exp_f32_e32 v0, v0
	v_cvt_pk_bf16_f32 v9, v14, v15
	v_add_co_u32_e32 v14, vcc, s72, v136
	v_cvt_pk_bf16_f32 v8, v12, v13
	v_cvt_pk_bf16_f32 v10, v16, v17
	v_cvt_pk_bf16_f32 v11, v18, v11
	v_addc_co_u32_e32 v15, vcc, 0, v137, vcc
	v_add_f32_e32 v0, 1.0, v0
	global_store_dwordx4 v[14:15], v[8:11], off
	v_pk_fma_f32 v[2:3], v[2:3], v[154:155], v[50:51] op_sel_hi:[1,0,1]
	v_pk_fma_f32 v[6:7], v[6:7], v[154:155], v[54:55] op_sel_hi:[1,0,1]
	v_rcp_f32_e32 v8, v0
	v_mul_f32_e32 v0, 0xbfb8aa3b, v1
	v_exp_f32_e32 v0, v0
	v_pk_fma_f32 v[4:5], v[4:5], v[154:155], v[52:53] op_sel_hi:[1,0,1]
	v_mul_f32_e32 v6, 0xbfb8aa3b, v6
	v_mul_f32_e32 v4, 0xbfb8aa3b, v4
	v_add_f32_e32 v0, 1.0, v0
	v_rcp_f32_e32 v9, v0
	v_mul_f32_e32 v0, 0xbfb8aa3b, v2
	v_exp_f32_e32 v0, v0
	v_mul_f32_e32 v5, 0xbfb8aa3b, v5
	v_mul_f32_e32 v7, 0xbfb8aa3b, v7
	v_exp_f32_e32 v4, v4
	v_add_f32_e32 v0, 1.0, v0
	v_rcp_f32_e32 v10, v0
	v_mul_f32_e32 v0, 0xbfb8aa3b, v3
	v_exp_f32_e32 v5, v5
	v_exp_f32_e32 v6, v6
	v_exp_f32_e32 v7, v7
	v_exp_f32_e32 v0, v0
	v_add_f32_e32 v4, 1.0, v4
	v_add_f32_e32 v5, 1.0, v5
	v_add_f32_e32 v6, 1.0, v6
	v_add_f32_e32 v7, 1.0, v7
	v_add_f32_e32 v0, 1.0, v0
	v_rcp_f32_e32 v4, v4
	v_rcp_f32_e32 v5, v5
	v_rcp_f32_e32 v6, v6
	v_rcp_f32_e32 v7, v7
	v_rcp_f32_e32 v3, v0
	s_mov_b64 s[20:21], 0x2c0000
	v_lshl_add_u64 v[12:13], v[136:137], 0, s[20:21]
	v_cvt_pk_bf16_f32 v0, v4, v5
	v_cvt_pk_bf16_f32 v1, v6, v7
	v_cvt_pk_bf16_f32 v2, v8, v9
	v_cvt_pk_bf16_f32 v3, v10, v3
	s_mov_b64 s[20:21], -1
	s_andn2_b64 vcc, exec, s[12:13]
	global_store_dwordx4 v[12:13], v[0:3], off offset:256
	s_cbranch_vccnz .LBB0_764
	s_mov_b32 s101, 1
	s_andn2_b64 vcc, exec, s[0:1]
	s_cbranch_vccnz .LBB0_763
	s_mov_b32 s100, 1
	s_branch .LBB0_763

; #define PG8_STAGE(bufoff, gbase, voff) do { _Pragma("unroll") for (int _i = 0; _i < 2; ++_i) \
;         __builtin_amdgcn_global_load_lds((const unsigned*)((const char*)(gbase) + (voff)[_i]), (PG8_LAS unsigned*)(lds + (bufoff) + ldsw + _i * 8192), 16, 0, 0); } while (0)
; #define PG8_LDA(dst, b, h) do { _Pragma("unroll") for (int m = 0; m < 4; ++m) _Pragma("unroll") for (int k = 0; k < 2; ++k) dst[m][k] = *(const PG8_LAS bf16x8*)(lds + PG8_SA(b, h) + aoff + m * 2048 + k * 1024); } while (0)
; #define PG8_LDB(dst, b, h) do { _Pragma("unroll") for (int n = 0; n < 2; ++n) _Pragma("unroll") for (int k = 0; k < 2; ++k) dst[n][k] = *(const PG8_LAS bf16x8*)(lds + PG8_SB(b, h) + boff + n * 2048 + k * 1024); } while (0)
; #define PG8_MMA(ai, bj, At, Bt) do { __builtin_amdgcn_s_setprio(1); _Pragma("unroll") for (int m = 0; m < 4; ++m) _Pragma("unroll") for (int n = 0; n < 2; ++n) _Pragma("unroll") for (int k = 0; k < 2; ++k) \
;         acc[ai][bj][m][n] = __builtin_amdgcn_mfma_f32_16x16x32_bf16(Bt[n][k], At[m][k], acc[ai][bj][m][n], 0, 0, 0); __builtin_amdgcn_s_setprio(0); } while (0)
; #define PG8_WAIT_V(n) asm volatile("s_waitcnt vmcnt(" #n ")" ::: "memory")
; #define PG8_WAIT_L(n) asm volatile("s_waitcnt lgkmcnt(" #n ")" ::: "memory")
; #define PG8_BAR __builtin_amdgcn_s_barrier()
; #define PG8_SCHED __builtin_amdgcn_sched_barrier(0)
; template <class Epi, class Sched, bool ALIGN_EPI = false, bool SP2 = false>
; __device__ __forceinline__ void gemm_phase(PG8_LAS unsigned char* lds, const Gemm g, const Sched& S, const Epi& E, const int tid) {
;     ...
;             PG8_LDB(B0, 0, 0); PG8_LDB(B1, 0, 1); PG8_SCHED; PG8_LDA(At, 0, 0); PG8_STAGE(PG8_SA(1, 1), a1 + hstep, voffA);
;             PG8_WAIT_V(8); PG8_WAIT_L(0); PG8_BAR; PG8_MMA(0, 0, At, B0); PG8_MMA(0, 1, At, B1); PG8_BAR; PG8_SCHED;
;             PG8_LDA(At, 0, 1); PG8_STAGE(PG8_SB(0, 0), b2, voffB); PG8_STAGE(PG8_SB(0, 1), b2 + hstep, voffB); PG8_STAGE(PG8_SA(0, 0), a2, voffA);
;             PG8_WAIT_V(8); PG8_WAIT_L(0); PG8_BAR; PG8_MMA(1, 0, At, B0); PG8_MMA(1, 1, At, B1); PG8_BAR; PG8_SCHED;
.Lmy_nobar_1047:
	s_cmp_eq_u32 s101, 0
	s_cbranch_scc1 .Lmy_strict_1047
	s_add_u32 s26, s24, 0xfff80080
	s_addc_u32 s27, s25, -1
	s_add_i32 s51, 0, 0x10000
	v_add_u32_e32 v68, s51, v157
	v_add_u32_e32 v154, s33, v157
	ds_read_b128 v[48:51], v68
	ds_read_b128 v[52:55], v68 offset:1024
	ds_read_b128 v[64:67], v68 offset:2048
	ds_read_b128 v[68:71], v68 offset:3072
	ds_read_b128 v[162:165], v154
	ds_read_b128 v[166:169], v154 offset:1024
	ds_read_b128 v[170:173], v154 offset:2048
	ds_read_b128 v[174:177], v154 offset:3072
	s_cmp_eq_u32 s50, 28
	s_cselect_b32 s29, s15, s27
	s_cselect_b32 s28, s21, s26
	s_cselect_b32 s27, s11, s49
	s_cselect_b32 s26, s47, s48
	v_lshl_add_u64 v[206:207], s[24:25], 0, v[150:151]
	s_add_i32 m0, s23, 0xc000
	ds_read_b128 v[178:181], v161
	ds_read_b128 v[182:185], v161 offset:1024
	ds_read_b128 v[186:189], v161 offset:2048
	ds_read_b128 v[190:193], v161 offset:3072
	ds_read_b128 v[194:197], v161 offset:4096
	ds_read_b128 v[198:201], v161 offset:5120
	ds_read_b128 v[202:205], v161 offset:6144
	ds_read_b128 v[214:217], v161 offset:7168
	global_load_lds_dwordx4 v[206:207], off
	v_lshl_add_u64 v[206:207], s[24:25], 0, v[152:153]
	s_add_i32 m0, s23, 0xe000
	s_nop 0
	global_load_lds_dwordx4 v[206:207], off
	s_waitcnt lgkmcnt(0)
	s_barrier
	s_setprio 1
	s_waitcnt lgkmcnt(0)
	v_mfma_f32_16x16x32_bf16 v[140:143], v[48:51], v[178:181], 0
	v_mfma_f32_16x16x32_bf16 v[136:139], v[64:67], v[178:181], 0
	v_mfma_f32_16x16x32_bf16 v[124:127], v[48:51], v[186:189], 0
	v_mfma_f32_16x16x32_bf16 v[120:123], v[64:67], v[186:189], 0
	v_mfma_f32_16x16x32_bf16 v[108:111], v[48:51], v[194:197], 0
	v_mfma_f32_16x16x32_bf16 v[104:107], v[64:67], v[194:197], 0
	v_mfma_f32_16x16x32_bf16 v[92:95], v[48:51], v[202:205], 0
	v_mfma_f32_16x16x32_bf16 v[88:91], v[64:67], v[202:205], 0
	v_mfma_f32_16x16x32_bf16 v[140:143], v[52:55], v[182:185], v[140:143]
	v_mfma_f32_16x16x32_bf16 v[136:139], v[68:71], v[182:185], v[136:139]
	v_mfma_f32_16x16x32_bf16 v[124:127], v[52:55], v[190:193], v[124:127]
	v_mfma_f32_16x16x32_bf16 v[120:123], v[68:71], v[190:193], v[120:123]
	v_mfma_f32_16x16x32_bf16 v[108:111], v[52:55], v[198:201], v[108:111]
	v_mfma_f32_16x16x32_bf16 v[104:107], v[68:71], v[198:201], v[104:107]
	v_mfma_f32_16x16x32_bf16 v[92:95], v[52:55], v[214:217], v[92:95]
	v_mfma_f32_16x16x32_bf16 v[88:91], v[68:71], v[214:217], v[88:91]
	s_setprio 0
	s_setprio 1
	v_mfma_f32_16x16x32_bf16 v[132:135], v[162:165], v[178:181], 0
	v_mfma_f32_16x16x32_bf16 v[128:131], v[170:173], v[178:181], 0
	v_mfma_f32_16x16x32_bf16 v[116:119], v[162:165], v[186:189], 0
	v_mfma_f32_16x16x32_bf16 v[112:115], v[170:173], v[186:189], 0
	v_mfma_f32_16x16x32_bf16 v[100:103], v[162:165], v[194:197], 0
	v_mfma_f32_16x16x32_bf16 v[96:99], v[170:173], v[194:197], 0
	v_mfma_f32_16x16x32_bf16 v[84:87], v[162:165], v[202:205], 0
	v_mfma_f32_16x16x32_bf16 v[80:83], v[170:173], v[202:205], 0
	v_mfma_f32_16x16x32_bf16 v[132:135], v[166:169], v[182:185], v[132:135]
	v_mfma_f32_16x16x32_bf16 v[128:131], v[174:177], v[182:185], v[128:131]
	v_mfma_f32_16x16x32_bf16 v[116:119], v[166:169], v[190:193], v[116:119]
	v_mfma_f32_16x16x32_bf16 v[112:115], v[174:177], v[190:193], v[112:115]
	v_mfma_f32_16x16x32_bf16 v[100:103], v[166:169], v[198:201], v[100:103]
	v_mfma_f32_16x16x32_bf16 v[96:99], v[174:177], v[198:201], v[96:99]
	v_mfma_f32_16x16x32_bf16 v[84:87], v[166:169], v[214:217], v[84:87]
	v_mfma_f32_16x16x32_bf16 v[80:83], v[174:177], v[214:217], v[80:83]
	s_setprio 0
	s_barrier
	s_add_i32 s51, s51, s38
	v_lshl_add_u64 v[206:207], s[26:27], 0, v[208:209]
	s_mov_b32 m0, s51
	ds_read_b128 v[178:181], v161 offset:16384
	ds_read_b128 v[182:185], v161 offset:17408
	ds_read_b128 v[186:189], v161 offset:18432
	ds_read_b128 v[190:193], v161 offset:19456
	ds_read_b128 v[194:197], v161 offset:20480
	ds_read_b128 v[198:201], v161 offset:21504
	ds_read_b128 v[202:205], v161 offset:22528
	ds_read_b128 v[214:217], v161 offset:23552
	global_load_lds_dwordx4 v[206:207], off
	s_add_i32 m0, s51, 0x2000
	s_add_u32 s52, s26, 0x80000
	v_lshl_add_u64 v[210:211], s[26:27], 0, v[144:145]
	s_addc_u32 s53, s27, 0
	s_add_i32 s51, s33, s38
	global_load_lds_dwordx4 v[210:211], off
	v_lshl_add_u64 v[218:219], s[52:53], 0, v[208:209]
	s_mov_b32 m0, s51
	v_lshl_add_u64 v[220:221], s[28:29], 0, v[146:147]
	global_load_lds_dwordx4 v[218:219], off
	v_lshl_add_u64 v[218:219], s[52:53], 0, v[144:145]
	s_add_i32 m0, s51, 0x2000
	s_nop 0
	global_load_lds_dwordx4 v[218:219], off
	v_lshl_add_u64 v[218:219], s[28:29], 0, v[148:149]
	s_mov_b32 m0, s23
	s_nop 0
	global_load_lds_dwordx4 v[218:219], off
	s_mov_b32 m0, s39
	s_nop 0
	global_load_lds_dwordx4 v[220:221], off
	s_waitcnt lgkmcnt(0)
	s_barrier
	s_setprio 1
	s_waitcnt lgkmcnt(0)
	v_mfma_f32_16x16x32_bf16 v[76:79], v[48:51], v[178:181], 0
	v_mfma_f32_16x16x32_bf16 v[72:75], v[64:67], v[178:181], 0
	v_mfma_f32_16x16x32_bf16 v[44:47], v[48:51], v[186:189], 0
	v_mfma_f32_16x16x32_bf16 v[40:43], v[64:67], v[186:189], 0
	v_mfma_f32_16x16x32_bf16 v[28:31], v[48:51], v[194:197], 0
	v_mfma_f32_16x16x32_bf16 v[24:27], v[64:67], v[194:197], 0
	v_mfma_f32_16x16x32_bf16 v[12:15], v[48:51], v[202:205], 0
	v_mfma_f32_16x16x32_bf16 v[8:11], v[64:67], v[202:205], 0
	v_mfma_f32_16x16x32_bf16 v[76:79], v[52:55], v[182:185], v[76:79]
	v_mfma_f32_16x16x32_bf16 v[72:75], v[68:71], v[182:185], v[72:75]
	v_mfma_f32_16x16x32_bf16 v[44:47], v[52:55], v[190:193], v[44:47]
	v_mfma_f32_16x16x32_bf16 v[40:43], v[68:71], v[190:193], v[40:43]
	v_mfma_f32_16x16x32_bf16 v[28:31], v[52:55], v[198:201], v[28:31]
	v_mfma_f32_16x16x32_bf16 v[24:27], v[68:71], v[198:201], v[24:27]
	v_mfma_f32_16x16x32_bf16 v[12:15], v[52:55], v[214:217], v[12:15]
	v_mfma_f32_16x16x32_bf16 v[8:11], v[68:71], v[214:217], v[8:11]
	s_setprio 0
	s_setprio 1
	v_mfma_f32_16x16x32_bf16 v[36:39], v[162:165], v[186:189], 0
	v_mfma_f32_16x16x32_bf16 v[32:35], v[170:173], v[186:189], 0
	v_mfma_f32_16x16x32_bf16 v[20:23], v[162:165], v[194:197], 0
	v_mfma_f32_16x16x32_bf16 v[16:19], v[170:173], v[194:197], 0
	v_mfma_f32_16x16x32_bf16 v[4:7], v[162:165], v[202:205], 0
	v_mfma_f32_16x16x32_bf16 v[0:3], v[170:173], v[202:205], 0
	v_mfma_f32_16x16x32_bf16 v[48:51], v[162:165], v[178:181], 0
	v_mfma_f32_16x16x32_bf16 v[52:55], v[170:173], v[178:181], 0
	v_mfma_f32_16x16x32_bf16 v[36:39], v[166:169], v[190:193], v[36:39]
	v_mfma_f32_16x16x32_bf16 v[32:35], v[174:177], v[190:193], v[32:35]
	v_mfma_f32_16x16x32_bf16 v[20:23], v[166:169], v[198:201], v[20:23]
	v_mfma_f32_16x16x32_bf16 v[16:19], v[174:177], v[198:201], v[16:19]
	v_mfma_f32_16x16x32_bf16 v[4:7], v[166:169], v[214:217], v[4:7]
	v_mfma_f32_16x16x32_bf16 v[0:3], v[174:177], v[214:217], v[0:3]
	v_mfma_f32_16x16x32_bf16 v[48:51], v[166:169], v[182:185], v[48:51]
	v_mfma_f32_16x16x32_bf16 v[52:55], v[174:177], v[182:185], v[52:55]
	s_setprio 0
	s_barrier
	s_mov_b32 s101, 0
	s_branch .Lmy_mid_1047

; #define PG8_STAGE(bufoff, gbase, voff) do { _Pragma("unroll") for (int _i = 0; _i < 2; ++_i) \
;         __builtin_amdgcn_global_load_lds((const unsigned*)((const char*)(gbase) + (voff)[_i]), (PG8_LAS unsigned*)(lds + (bufoff) + ldsw + _i * 8192), 16, 0, 0); } while (0)
; #define PG8_LDA(dst, b, h) do { _Pragma("unroll") for (int m = 0; m < 4; ++m) _Pragma("unroll") for (int k = 0; k < 2; ++k) dst[m][k] = *(const PG8_LAS bf16x8*)(lds + PG8_SA(b, h) + aoff + m * 2048 + k * 1024); } while (0)
; #define PG8_LDB(dst, b, h) do { _Pragma("unroll") for (int n = 0; n < 2; ++n) _Pragma("unroll") for (int k = 0; k < 2; ++k) dst[n][k] = *(const PG8_LAS bf16x8*)(lds + PG8_SB(b, h) + boff + n * 2048 + k * 1024); } while (0)
; #define PG8_MMA(ai, bj, At, Bt) do { __builtin_amdgcn_s_setprio(1); _Pragma("unroll") for (int m = 0; m < 4; ++m) _Pragma("unroll") for (int n = 0; n < 2; ++n) _Pragma("unroll") for (int k = 0; k < 2; ++k) \
;         acc[ai][bj][m][n] = __builtin_amdgcn_mfma_f32_16x16x32_bf16(Bt[n][k], At[m][k], acc[ai][bj][m][n], 0, 0, 0); __builtin_amdgcn_s_setprio(0); } while (0)
; #define PG8_WAIT_V(n) asm volatile("s_waitcnt vmcnt(" #n ")" ::: "memory")
; #define PG8_WAIT_L(n) asm volatile("s_waitcnt lgkmcnt(" #n ")" ::: "memory")
; #define PG8_BAR __builtin_amdgcn_s_barrier()
; #define PG8_SCHED __builtin_amdgcn_sched_barrier(0)
; template <class Epi, class Sched, bool ALIGN_EPI = false, bool SP2 = false>
; __device__ __forceinline__ void gemm_phase(PG8_LAS unsigned char* lds, const Gemm g, const Sched& S, const Epi& E, const int tid) {
;     ...
;             PG8_LDB(B0, 0, 0); PG8_LDB(B1, 0, 1); PG8_SCHED; PG8_LDA(At, 0, 0); PG8_STAGE(PG8_SA(1, 1), a1 + hstep, voffA);
;             PG8_WAIT_V(8); PG8_WAIT_L(0); PG8_BAR; PG8_MMA(0, 0, At, B0); PG8_MMA(0, 1, At, B1); PG8_BAR; PG8_SCHED;
;             PG8_LDA(At, 0, 1); PG8_STAGE(PG8_SB(0, 0), b2, voffB); PG8_STAGE(PG8_SB(0, 1), b2 + hstep, voffB); PG8_STAGE(PG8_SA(0, 0), a2, voffA);
;             PG8_WAIT_V(8); PG8_WAIT_L(0); PG8_BAR; PG8_MMA(1, 0, At, B0); PG8_MMA(1, 1, At, B1); PG8_BAR; PG8_SCHED;
.Lmy_nobar_1128:
	s_cmp_eq_u32 s101, 0
	s_cbranch_scc1 .Lmy_strict_1128
	s_add_u32 s24, s4, 0xfffe0080
	s_addc_u32 s25, s5, -1
	s_add_i32 s50, 0, 0x10000
	v_add_u32_e32 v140, s50, v211
	v_add_u32_e32 v156, s33, v211
	ds_read_b128 v[128:131], v140
	ds_read_b128 v[132:135], v140 offset:1024
	ds_read_b128 v[136:139], v140 offset:2048
	ds_read_b128 v[140:143], v140 offset:3072
	ds_read_b128 v[144:147], v156
	ds_read_b128 v[148:151], v156 offset:1024
	ds_read_b128 v[152:155], v156 offset:2048
	ds_read_b128 v[156:159], v156 offset:3072
	s_cmp_eq_u32 s49, 4
	s_cselect_b32 s27, s17, s25
	s_cselect_b32 s26, s16, s24
	s_cselect_b32 s25, s13, s23
	s_cselect_b32 s24, s15, s21
	v_lshl_add_u64 v[192:193], s[4:5], 0, v[200:201]
	s_add_i32 m0, s37, 0xc000
	ds_read_b128 v[160:163], v225
	ds_read_b128 v[164:167], v225 offset:1024
	ds_read_b128 v[168:171], v225 offset:2048
	ds_read_b128 v[172:175], v225 offset:3072
	ds_read_b128 v[176:179], v225 offset:4096
	ds_read_b128 v[180:183], v225 offset:5120
	ds_read_b128 v[184:187], v225 offset:6144
	ds_read_b128 v[188:191], v225 offset:7168
	global_load_lds_dwordx4 v[192:193], off
	v_lshl_add_u64 v[192:193], s[4:5], 0, v[202:203]
	s_add_i32 m0, s37, 0xe000
	s_nop 0
	global_load_lds_dwordx4 v[192:193], off
	s_waitcnt lgkmcnt(0)
	s_barrier
	s_setprio 1
	s_waitcnt lgkmcnt(0)
	v_mfma_f32_16x16x32_bf16 v[124:127], v[128:131], v[160:163], 0
	v_mfma_f32_16x16x32_bf16 v[120:123], v[136:139], v[160:163], 0
	v_mfma_f32_16x16x32_bf16 v[108:111], v[128:131], v[168:171], 0
	v_mfma_f32_16x16x32_bf16 v[104:107], v[136:139], v[168:171], 0
	v_mfma_f32_16x16x32_bf16 v[100:103], v[128:131], v[176:179], 0
	v_mfma_f32_16x16x32_bf16 v[96:99], v[136:139], v[176:179], 0
	v_mfma_f32_16x16x32_bf16 v[92:95], v[128:131], v[184:187], 0
	v_mfma_f32_16x16x32_bf16 v[88:91], v[136:139], v[184:187], 0
	v_mfma_f32_16x16x32_bf16 v[124:127], v[132:135], v[164:167], v[124:127]
	v_mfma_f32_16x16x32_bf16 v[120:123], v[140:143], v[164:167], v[120:123]
	v_mfma_f32_16x16x32_bf16 v[108:111], v[132:135], v[172:175], v[108:111]
	v_mfma_f32_16x16x32_bf16 v[104:107], v[140:143], v[172:175], v[104:107]
	v_mfma_f32_16x16x32_bf16 v[100:103], v[132:135], v[180:183], v[100:103]
	v_mfma_f32_16x16x32_bf16 v[96:99], v[140:143], v[180:183], v[96:99]
	v_mfma_f32_16x16x32_bf16 v[92:95], v[132:135], v[188:191], v[92:95]
	v_mfma_f32_16x16x32_bf16 v[88:91], v[140:143], v[188:191], v[88:91]
	s_setprio 0
	s_setprio 1
	v_mfma_f32_16x16x32_bf16 v[116:119], v[144:147], v[160:163], 0
	v_mfma_f32_16x16x32_bf16 v[112:115], v[152:155], v[160:163], 0
	v_mfma_f32_16x16x32_bf16 v[84:87], v[144:147], v[168:171], 0
	v_mfma_f32_16x16x32_bf16 v[80:83], v[152:155], v[168:171], 0
	v_mfma_f32_16x16x32_bf16 v[76:79], v[144:147], v[176:179], 0
	v_mfma_f32_16x16x32_bf16 v[72:75], v[152:155], v[176:179], 0
	v_mfma_f32_16x16x32_bf16 v[68:71], v[144:147], v[184:187], 0
	v_mfma_f32_16x16x32_bf16 v[64:67], v[152:155], v[184:187], 0
	v_mfma_f32_16x16x32_bf16 v[116:119], v[148:151], v[164:167], v[116:119]
	v_mfma_f32_16x16x32_bf16 v[112:115], v[156:159], v[164:167], v[112:115]
	v_mfma_f32_16x16x32_bf16 v[84:87], v[148:151], v[172:175], v[84:87]
	v_mfma_f32_16x16x32_bf16 v[80:83], v[156:159], v[172:175], v[80:83]
	v_mfma_f32_16x16x32_bf16 v[76:79], v[148:151], v[180:183], v[76:79]
	v_mfma_f32_16x16x32_bf16 v[72:75], v[156:159], v[180:183], v[72:75]
	v_mfma_f32_16x16x32_bf16 v[68:71], v[148:151], v[188:191], v[68:71]
	v_mfma_f32_16x16x32_bf16 v[64:67], v[156:159], v[188:191], v[64:67]
	s_setprio 0
	s_barrier
	s_add_i32 s50, s50, s36
	v_lshl_add_u64 v[192:193], s[24:25], 0, v[208:209]
	s_mov_b32 m0, s50
	ds_read_b128 v[160:163], v225 offset:16384
	ds_read_b128 v[164:167], v225 offset:17408
	ds_read_b128 v[168:171], v225 offset:18432
	ds_read_b128 v[172:175], v225 offset:19456
	ds_read_b128 v[176:179], v225 offset:20480
	ds_read_b128 v[180:183], v225 offset:21504
	ds_read_b128 v[184:187], v225 offset:22528
	ds_read_b128 v[188:191], v225 offset:23552
	global_load_lds_dwordx4 v[192:193], off
	s_add_i32 m0, s50, 0x2000
	s_add_u32 s50, s24, 0x20000
	v_lshl_add_u64 v[204:205], s[24:25], 0, v[198:199]
	s_addc_u32 s51, s25, 0
	s_add_i32 s52, s33, s36
	global_load_lds_dwordx4 v[204:205], off
	v_lshl_add_u64 v[206:207], s[50:51], 0, v[208:209]
	s_mov_b32 m0, s52
	v_lshl_add_u64 v[214:215], s[26:27], 0, v[196:197]
	global_load_lds_dwordx4 v[206:207], off
	v_lshl_add_u64 v[206:207], s[50:51], 0, v[198:199]
	s_add_i32 m0, s52, 0x2000
	s_nop 0
	global_load_lds_dwordx4 v[206:207], off
	v_lshl_add_u64 v[206:207], s[26:27], 0, v[194:195]
	s_mov_b32 m0, s37
	s_nop 0
	global_load_lds_dwordx4 v[206:207], off
	s_mov_b32 m0, s38
	s_nop 0
	global_load_lds_dwordx4 v[214:215], off
	s_waitcnt lgkmcnt(0)
	s_barrier
	s_setprio 1
	s_waitcnt lgkmcnt(0)
	v_mfma_f32_16x16x32_bf16 v[60:63], v[128:131], v[160:163], 0
	v_mfma_f32_16x16x32_bf16 v[56:59], v[136:139], v[160:163], 0
	v_mfma_f32_16x16x32_bf16 v[44:47], v[128:131], v[168:171], 0
	v_mfma_f32_16x16x32_bf16 v[40:43], v[136:139], v[168:171], 0
	v_mfma_f32_16x16x32_bf16 v[28:31], v[128:131], v[176:179], 0
	v_mfma_f32_16x16x32_bf16 v[24:27], v[136:139], v[176:179], 0
	v_mfma_f32_16x16x32_bf16 v[12:15], v[128:131], v[184:187], 0
	v_mfma_f32_16x16x32_bf16 v[8:11], v[136:139], v[184:187], 0
	v_mfma_f32_16x16x32_bf16 v[60:63], v[132:135], v[164:167], v[60:63]
	v_mfma_f32_16x16x32_bf16 v[56:59], v[140:143], v[164:167], v[56:59]
	v_mfma_f32_16x16x32_bf16 v[44:47], v[132:135], v[172:175], v[44:47]
	v_mfma_f32_16x16x32_bf16 v[40:43], v[140:143], v[172:175], v[40:43]
	v_mfma_f32_16x16x32_bf16 v[28:31], v[132:135], v[180:183], v[28:31]
	v_mfma_f32_16x16x32_bf16 v[24:27], v[140:143], v[180:183], v[24:27]
	v_mfma_f32_16x16x32_bf16 v[12:15], v[132:135], v[188:191], v[12:15]
	v_mfma_f32_16x16x32_bf16 v[8:11], v[140:143], v[188:191], v[8:11]
	s_setprio 0
	s_setprio 1
	v_mfma_f32_16x16x32_bf16 v[52:55], v[144:147], v[160:163], 0
	v_mfma_f32_16x16x32_bf16 v[48:51], v[152:155], v[160:163], 0
	v_mfma_f32_16x16x32_bf16 v[36:39], v[144:147], v[168:171], 0
	v_mfma_f32_16x16x32_bf16 v[32:35], v[152:155], v[168:171], 0
	v_mfma_f32_16x16x32_bf16 v[20:23], v[144:147], v[176:179], 0
	v_mfma_f32_16x16x32_bf16 v[16:19], v[152:155], v[176:179], 0
	v_mfma_f32_16x16x32_bf16 v[4:7], v[144:147], v[184:187], 0
	v_mfma_f32_16x16x32_bf16 v[0:3], v[152:155], v[184:187], 0
	v_mfma_f32_16x16x32_bf16 v[52:55], v[148:151], v[164:167], v[52:55]
	v_mfma_f32_16x16x32_bf16 v[48:51], v[156:159], v[164:167], v[48:51]
	v_mfma_f32_16x16x32_bf16 v[36:39], v[148:151], v[172:175], v[36:39]
	v_mfma_f32_16x16x32_bf16 v[32:35], v[156:159], v[172:175], v[32:35]
	v_mfma_f32_16x16x32_bf16 v[20:23], v[148:151], v[180:183], v[20:23]
	v_mfma_f32_16x16x32_bf16 v[16:19], v[156:159], v[180:183], v[16:19]
	v_mfma_f32_16x16x32_bf16 v[4:7], v[148:151], v[188:191], v[4:7]
	v_mfma_f32_16x16x32_bf16 v[0:3], v[156:159], v[188:191], v[0:3]
	s_setprio 0
	s_barrier
	s_mov_b32 s101, 0
	s_branch .Lmy_mid_1128

; __device__ __forceinline__ unsigned pk2(float lo, float hi) { const f32x2 v = {lo, hi}; return __builtin_bit_cast(unsigned, __builtin_convertvector(v, bf16x2_t)); }
;     __device__ __forceinline__ void operator()(const f32x4 (&acc)[2][2][4][2], const Unit& un, int wr, int wc, int fr, int fq) const {
;     ...
;                 for (int bj = 0; bj < 2; ++bj) { const int row = rbase + ai * 128 + m * 16, col = cw + bj * 128; ga_[m][bj] = *(const u32x4*)(gate + (size_t)row * DFF + kb * D + col);
;                     pa_[m][bj] = kb > 0 ? *(const u32x4*)(mg + (size_t)row * D + col) : (u32x4){0u, 0u, 0u, 0u}; }
; #pragma unroll
;             for (int m = 0; m < 4; ++m)
; #pragma unroll
;                 for (int bj = 0; bj < 2; ++bj) { const int row = rbase + ai * 128 + m * 16, col = cw + bj * 128; const f32x4 v0 = acc[ai][bj][m][0], v1 = acc[ai][bj][m][1]; const u32x4 gw = ga_[m][bj], pm = pa_[m][bj];
;                     const f32x4 r0 = (f32x4){bflo(gw.x) * v0.x, bfhi(gw.x) * v0.y, bflo(gw.y) * v0.z, bfhi(gw.y) * v0.w} + (f32x4){bflo(pm.x), bfhi(pm.x), bflo(pm.y), bfhi(pm.y)};
;                     const f32x4 r1 = (f32x4){bflo(gw.z) * v1.x, bfhi(gw.z) * v1.y, bflo(gw.w) * v1.z, bfhi(gw.w) * v1.w} + (f32x4){bflo(pm.z), bfhi(pm.z), bflo(pm.w), bfhi(pm.w)};
;                     u32x4 w; w.x = pk2(r0.x, r0.y); w.y = pk2(r0.z, r0.w); w.z = pk2(r1.x, r1.y); w.w = pk2(r1.z, r1.w); *(u32x4*)(mg + (size_t)row * D + col) = w; } }
.LBB0_1165:
	s_waitcnt vmcnt(10)
	v_lshlrev_b32_e32 v138, 16, v100
	v_and_b32_e32 v139, 0xffff0000, v100
	v_lshlrev_b32_e32 v100, 16, v101
	v_and_b32_e32 v101, 0xffff0000, v101
	s_waitcnt vmcnt(7)
	v_lshlrev_b32_e32 v140, 16, v128
	v_and_b32_e32 v141, 0xffff0000, v128
	v_lshlrev_b32_e32 v128, 16, v129
	v_and_b32_e32 v129, 0xffff0000, v129
	v_pk_fma_f32 v[62:63], v[62:63], v[100:101], v[128:129]
	v_lshlrev_b32_e32 v100, 16, v102
	v_and_b32_e32 v101, 0xffff0000, v102
	v_lshlrev_b32_e32 v102, 16, v103
	v_and_b32_e32 v103, 0xffff0000, v103
	v_lshlrev_b32_e32 v128, 16, v130
	v_and_b32_e32 v129, 0xffff0000, v130
	v_lshlrev_b32_e32 v130, 16, v131
	v_and_b32_e32 v131, 0xffff0000, v131
	v_pk_fma_f32 v[60:61], v[60:61], v[138:139], v[140:141]
	v_pk_fma_f32 v[102:103], v[58:59], v[102:103], v[130:131]
	v_pk_fma_f32 v[58:59], v[56:57], v[100:101], v[128:129]
	v_cvt_pk_bf16_f32 v56, v60, v61
	v_cvt_pk_bf16_f32 v57, v62, v63
	v_cvt_pk_bf16_f32 v58, v58, v59
	v_cvt_pk_bf16_f32 v59, v102, v103
	v_lshl_add_u64 v[60:61], v[136:137], 0, v[124:125]
	global_store_dwordx4 v[60:61], v[56:59], off
	s_waitcnt vmcnt(7)
	v_lshlrev_b32_e32 v62, 16, v116
	v_and_b32_e32 v63, 0xffff0000, v116
	v_lshlrev_b32_e32 v56, 16, v120
	v_and_b32_e32 v57, 0xffff0000, v120
	v_lshlrev_b32_e32 v58, 16, v121
	v_and_b32_e32 v59, 0xffff0000, v121
	v_lshlrev_b32_e32 v100, 16, v117
	v_and_b32_e32 v101, 0xffff0000, v117
	v_pk_fma_f32 v[54:55], v[54:55], v[58:59], v[100:101]
	v_pk_fma_f32 v[52:53], v[52:53], v[56:57], v[62:63]
	v_lshlrev_b32_e32 v56, 16, v122
	v_and_b32_e32 v57, 0xffff0000, v122
	v_lshlrev_b32_e32 v58, 16, v123
	v_and_b32_e32 v59, 0xffff0000, v123
	v_lshlrev_b32_e32 v62, 16, v118
	v_and_b32_e32 v63, 0xffff0000, v118
	v_lshlrev_b32_e32 v100, 16, v119
	v_and_b32_e32 v101, 0xffff0000, v119
	v_pk_fma_f32 v[58:59], v[50:51], v[58:59], v[100:101]
	v_pk_fma_f32 v[50:51], v[48:49], v[56:57], v[62:63]
	v_cvt_pk_bf16_f32 v48, v52, v53
	v_cvt_pk_bf16_f32 v49, v54, v55
	v_cvt_pk_bf16_f32 v50, v50, v51
	v_cvt_pk_bf16_f32 v51, v58, v59
	global_store_dwordx4 v[60:61], v[48:51], off offset:256
	s_waitcnt vmcnt(7)
	v_lshlrev_b32_e32 v52, 16, v96
	v_and_b32_e32 v53, 0xffff0000, v96
	v_lshlrev_b32_e32 v48, 16, v112
	v_and_b32_e32 v49, 0xffff0000, v112
	v_lshlrev_b32_e32 v50, 16, v113
	v_and_b32_e32 v51, 0xffff0000, v113
	v_lshlrev_b32_e32 v54, 16, v97
	v_and_b32_e32 v55, 0xffff0000, v97
	v_pk_fma_f32 v[46:47], v[46:47], v[50:51], v[54:55]
	v_pk_fma_f32 v[44:45], v[44:45], v[48:49], v[52:53]
	v_lshlrev_b32_e32 v48, 16, v114
	v_and_b32_e32 v49, 0xffff0000, v114
	v_lshlrev_b32_e32 v50, 16, v115
	v_and_b32_e32 v51, 0xffff0000, v115
	v_lshlrev_b32_e32 v52, 16, v98
	v_and_b32_e32 v53, 0xffff0000, v98
	v_lshlrev_b32_e32 v54, 16, v99
	v_and_b32_e32 v55, 0xffff0000, v99
	v_pk_fma_f32 v[50:51], v[42:43], v[50:51], v[54:55]
	v_pk_fma_f32 v[42:43], v[40:41], v[48:49], v[52:53]
	v_cvt_pk_bf16_f32 v40, v44, v45
	v_cvt_pk_bf16_f32 v41, v46, v47
	v_cvt_pk_bf16_f32 v42, v42, v43
	v_cvt_pk_bf16_f32 v43, v50, v51
	v_lshl_add_u64 v[44:45], v[134:135], 0, v[124:125]
	global_store_dwordx4 v[44:45], v[40:43], off
	s_waitcnt vmcnt(7)
	v_lshlrev_b32_e32 v46, 16, v104
	v_and_b32_e32 v47, 0xffff0000, v104
	v_lshlrev_b32_e32 v40, 16, v108
	v_and_b32_e32 v41, 0xffff0000, v108
	v_lshlrev_b32_e32 v42, 16, v109
	v_and_b32_e32 v43, 0xffff0000, v109
	v_lshlrev_b32_e32 v48, 16, v105
	v_and_b32_e32 v49, 0xffff0000, v105
	v_pk_fma_f32 v[38:39], v[38:39], v[42:43], v[48:49]
	v_pk_fma_f32 v[36:37], v[36:37], v[40:41], v[46:47]
	v_lshlrev_b32_e32 v40, 16, v110
	v_and_b32_e32 v41, 0xffff0000, v110
	v_lshlrev_b32_e32 v42, 16, v111
	v_and_b32_e32 v43, 0xffff0000, v111
	v_lshlrev_b32_e32 v46, 16, v106
	v_and_b32_e32 v47, 0xffff0000, v106
	v_lshlrev_b32_e32 v48, 16, v107
	v_and_b32_e32 v49, 0xffff0000, v107
	v_pk_fma_f32 v[42:43], v[34:35], v[42:43], v[48:49]
	v_pk_fma_f32 v[34:35], v[32:33], v[40:41], v[46:47]
	v_cvt_pk_bf16_f32 v32, v36, v37
	v_cvt_pk_bf16_f32 v33, v38, v39
	v_cvt_pk_bf16_f32 v34, v34, v35
	v_cvt_pk_bf16_f32 v35, v42, v43
	global_store_dwordx4 v[44:45], v[32:35], off offset:256
	s_waitcnt vmcnt(7)
; __device__ __forceinline__ unsigned pk2(float lo, float hi) { const f32x2 v = {lo, hi}; return __builtin_bit_cast(unsigned, __builtin_convertvector(v, bf16x2_t)); }
; template <class Epi, class Sched, bool ALIGN_EPI = false, bool SP2 = false>
; __device__ __forceinline__ void gemm_phase(PG8_LAS unsigned char* lds, const Gemm g, const Sched& S, const Epi& E, const int tid) {
;     ...
;         if constexpr (!Epi::AFTER_DRAIN) { E(acc, cur, wr, wc, fr, fq); S.done(cur); }
;         if (!has_next) break;
; #pragma unroll
;         for (int a = 0; a < 2; ++a)
; #pragma unroll
;             for (int b = 0; b < 2; ++b)
; #pragma unroll
;                 for (int m = 0; m < 4; ++m)
; #pragma unroll
;                     for (int n = 0; n < 2; ++n) acc[a][b][m][n] = (f32x4){0.f, 0.f, 0.f, 0.f};
;         cur = nxt; cA = nA; cB = nB; ++ui;
;     __device__ __forceinline__ void operator()(const f32x4 (&acc)[2][2][4][2], const Unit& un, int wr, int wc, int fr, int fq) const {
;     ...
;             for (int m = 0; m < 4; ++m)
; #pragma unroll
;                 for (int bj = 0; bj < 2; ++bj) { const int row = rbase + ai * 128 + m * 16, col = cw + bj * 128; const f32x4 v0 = acc[ai][bj][m][0], v1 = acc[ai][bj][m][1]; const u32x4 gw = ga_[m][bj], pm = pa_[m][bj];
;                     const f32x4 r0 = (f32x4){bflo(gw.x) * v0.x, bfhi(gw.x) * v0.y, bflo(gw.y) * v0.z, bfhi(gw.y) * v0.w} + (f32x4){bflo(pm.x), bfhi(pm.x), bflo(pm.y), bfhi(pm.y)};
;                     const f32x4 r1 = (f32x4){bflo(gw.z) * v1.x, bfhi(gw.z) * v1.y, bflo(gw.w) * v1.z, bfhi(gw.w) * v1.w} + (f32x4){bflo(pm.z), bfhi(pm.z), bflo(pm.w), bfhi(pm.w)};
;                     u32x4 w; w.x = pk2(r0.x, r0.y); w.y = pk2(r0.z, r0.w); w.z = pk2(r1.x, r1.y); w.w = pk2(r1.z, r1.w); *(u32x4*)(mg + (size_t)row * D + col) = w; } }
	v_lshlrev_b32_e32 v36, 16, v80
	v_and_b32_e32 v37, 0xffff0000, v80
	v_lshlrev_b32_e32 v32, 16, v92
	v_and_b32_e32 v33, 0xffff0000, v92
	v_lshlrev_b32_e32 v34, 16, v93
	v_and_b32_e32 v35, 0xffff0000, v93
	v_lshlrev_b32_e32 v38, 16, v81
	v_and_b32_e32 v39, 0xffff0000, v81
	v_pk_fma_f32 v[30:31], v[30:31], v[34:35], v[38:39]
	v_pk_fma_f32 v[28:29], v[28:29], v[32:33], v[36:37]
	v_lshlrev_b32_e32 v32, 16, v94
	v_and_b32_e32 v33, 0xffff0000, v94
	v_lshlrev_b32_e32 v34, 16, v95
	v_and_b32_e32 v35, 0xffff0000, v95
	v_lshlrev_b32_e32 v36, 16, v82
	v_and_b32_e32 v37, 0xffff0000, v82
	v_lshlrev_b32_e32 v38, 16, v83
	v_and_b32_e32 v39, 0xffff0000, v83
	v_pk_fma_f32 v[34:35], v[26:27], v[34:35], v[38:39]
	v_pk_fma_f32 v[26:27], v[24:25], v[32:33], v[36:37]
	v_cvt_pk_bf16_f32 v24, v28, v29
	v_cvt_pk_bf16_f32 v25, v30, v31
	v_cvt_pk_bf16_f32 v26, v26, v27
	v_cvt_pk_bf16_f32 v27, v34, v35
	v_lshl_add_u64 v[28:29], v[132:133], 0, v[124:125]
	global_store_dwordx4 v[28:29], v[24:27], off
	s_waitcnt vmcnt(7)
	v_lshlrev_b32_e32 v30, 16, v84
	v_and_b32_e32 v31, 0xffff0000, v84
	v_lshlrev_b32_e32 v24, 16, v88
	v_and_b32_e32 v25, 0xffff0000, v88
	v_lshlrev_b32_e32 v26, 16, v89
	v_and_b32_e32 v27, 0xffff0000, v89
	v_lshlrev_b32_e32 v32, 16, v85
	v_and_b32_e32 v33, 0xffff0000, v85
	v_pk_fma_f32 v[22:23], v[22:23], v[26:27], v[32:33]
	v_pk_fma_f32 v[20:21], v[20:21], v[24:25], v[30:31]
	v_lshlrev_b32_e32 v24, 16, v90
	v_and_b32_e32 v25, 0xffff0000, v90
	v_lshlrev_b32_e32 v26, 16, v91
	v_and_b32_e32 v27, 0xffff0000, v91
	v_lshlrev_b32_e32 v30, 16, v86
	v_and_b32_e32 v31, 0xffff0000, v86
	v_lshlrev_b32_e32 v32, 16, v87
	v_and_b32_e32 v33, 0xffff0000, v87
	v_pk_fma_f32 v[26:27], v[18:19], v[26:27], v[32:33]
	v_pk_fma_f32 v[18:19], v[16:17], v[24:25], v[30:31]
	v_cvt_pk_bf16_f32 v16, v20, v21
	v_cvt_pk_bf16_f32 v17, v22, v23
	v_cvt_pk_bf16_f32 v18, v18, v19
	v_cvt_pk_bf16_f32 v19, v26, v27
	global_store_dwordx4 v[28:29], v[16:19], off offset:256
	s_waitcnt vmcnt(7)
	v_lshlrev_b32_e32 v20, 16, v64
	v_and_b32_e32 v21, 0xffff0000, v64
	v_lshlrev_b32_e32 v16, 16, v76
	v_and_b32_e32 v17, 0xffff0000, v76
	v_lshlrev_b32_e32 v18, 16, v77
	v_and_b32_e32 v19, 0xffff0000, v77
	v_lshlrev_b32_e32 v22, 16, v65
	v_and_b32_e32 v23, 0xffff0000, v65
	v_pk_fma_f32 v[14:15], v[14:15], v[18:19], v[22:23]
	v_pk_fma_f32 v[12:13], v[12:13], v[16:17], v[20:21]
	v_lshlrev_b32_e32 v16, 16, v78
	v_and_b32_e32 v17, 0xffff0000, v78
	v_lshlrev_b32_e32 v18, 16, v79
	v_and_b32_e32 v19, 0xffff0000, v79
	v_lshlrev_b32_e32 v20, 16, v66
	v_and_b32_e32 v21, 0xffff0000, v66
	v_lshlrev_b32_e32 v22, 16, v67
	v_and_b32_e32 v23, 0xffff0000, v67
	v_pk_fma_f32 v[18:19], v[10:11], v[18:19], v[22:23]
	v_pk_fma_f32 v[10:11], v[8:9], v[16:17], v[20:21]
	v_cvt_pk_bf16_f32 v8, v12, v13
	v_cvt_pk_bf16_f32 v9, v14, v15
	v_cvt_pk_bf16_f32 v10, v10, v11
	v_cvt_pk_bf16_f32 v11, v18, v19
	v_lshl_add_u64 v[12:13], v[126:127], 0, v[124:125]
	global_store_dwordx4 v[12:13], v[8:11], off
	s_waitcnt vmcnt(7)
	v_lshlrev_b32_e32 v14, 16, v68
	v_and_b32_e32 v15, 0xffff0000, v68
	v_lshlrev_b32_e32 v8, 16, v72
	v_and_b32_e32 v9, 0xffff0000, v72
	v_lshlrev_b32_e32 v10, 16, v73
	v_and_b32_e32 v11, 0xffff0000, v73
	v_lshlrev_b32_e32 v16, 16, v69
	v_and_b32_e32 v17, 0xffff0000, v69
	v_pk_fma_f32 v[6:7], v[6:7], v[10:11], v[16:17]
	v_pk_fma_f32 v[4:5], v[4:5], v[8:9], v[14:15]
	v_lshlrev_b32_e32 v8, 16, v74
	v_and_b32_e32 v9, 0xffff0000, v74
	v_lshlrev_b32_e32 v10, 16, v75
	v_and_b32_e32 v11, 0xffff0000, v75
	v_lshlrev_b32_e32 v14, 16, v70
	v_and_b32_e32 v15, 0xffff0000, v70
	v_lshlrev_b32_e32 v16, 16, v71
	v_and_b32_e32 v17, 0xffff0000, v71
	v_pk_fma_f32 v[10:11], v[2:3], v[10:11], v[16:17]
	v_pk_fma_f32 v[2:3], v[0:1], v[8:9], v[14:15]
	v_cvt_pk_bf16_f32 v0, v4, v5
	v_cvt_pk_bf16_f32 v1, v6, v7
	v_cvt_pk_bf16_f32 v2, v2, v3
	v_cvt_pk_bf16_f32 v3, v10, v11
	s_and_b64 vcc, exec, s[0:1]
	s_mov_b64 s[0:1], -1
	global_store_dwordx4 v[12:13], v[0:3], off offset:256
	s_cbranch_vccnz .LBB0_1118
	s_mov_b32 s101, 1
	s_andn2_b64 vcc, exec, s[6:7]
	s_cbranch_vccnz .LBB0_1117
	s_mov_b32 s100, 1
	s_branch .LBB0_1117

; #define PG8_STAGE(bufoff, gbase, voff) do { _Pragma("unroll") for (int _i = 0; _i < 2; ++_i) \
;         __builtin_amdgcn_global_load_lds((const unsigned*)((const char*)(gbase) + (voff)[_i]), (PG8_LAS unsigned*)(lds + (bufoff) + ldsw + _i * 8192), 16, 0, 0); } while (0)
; #define PG8_LDA(dst, b, h) do { _Pragma("unroll") for (int m = 0; m < 4; ++m) _Pragma("unroll") for (int k = 0; k < 2; ++k) dst[m][k] = *(const PG8_LAS bf16x8*)(lds + PG8_SA(b, h) + aoff + m * 2048 + k * 1024); } while (0)
; #define PG8_LDB(dst, b, h) do { _Pragma("unroll") for (int n = 0; n < 2; ++n) _Pragma("unroll") for (int k = 0; k < 2; ++k) dst[n][k] = *(const PG8_LAS bf16x8*)(lds + PG8_SB(b, h) + boff + n * 2048 + k * 1024); } while (0)
; #define PG8_MMA(ai, bj, At, Bt) do { __builtin_amdgcn_s_setprio(1); _Pragma("unroll") for (int m = 0; m < 4; ++m) _Pragma("unroll") for (int n = 0; n < 2; ++n) _Pragma("unroll") for (int k = 0; k < 2; ++k) \
;         acc[ai][bj][m][n] = __builtin_amdgcn_mfma_f32_16x16x32_bf16(Bt[n][k], At[m][k], acc[ai][bj][m][n], 0, 0, 0); __builtin_amdgcn_s_setprio(0); } while (0)
; #define PG8_WAIT_V(n) asm volatile("s_waitcnt vmcnt(" #n ")" ::: "memory")
; #define PG8_WAIT_L(n) asm volatile("s_waitcnt lgkmcnt(" #n ")" ::: "memory")
; #define PG8_BAR __builtin_amdgcn_s_barrier()
; #define PG8_SCHED __builtin_amdgcn_sched_barrier(0)
; template <class Epi, class Sched, bool ALIGN_EPI = false, bool SP2 = false>
; __device__ __forceinline__ void gemm_phase(PG8_LAS unsigned char* lds, const Gemm g, const Sched& S, const Epi& E, const int tid) {
;     ...
;             PG8_LDB(B0, 0, 0); PG8_LDB(B1, 0, 1); PG8_SCHED; PG8_LDA(At, 0, 0); PG8_STAGE(PG8_SA(1, 1), a1 + hstep, voffA);
;             PG8_WAIT_V(8); PG8_WAIT_L(0); PG8_BAR; PG8_MMA(0, 0, At, B0); PG8_MMA(0, 1, At, B1); PG8_BAR; PG8_SCHED;
;             PG8_LDA(At, 0, 1); PG8_STAGE(PG8_SB(0, 0), b2, voffB); PG8_STAGE(PG8_SB(0, 1), b2 + hstep, voffB); PG8_STAGE(PG8_SA(0, 0), a2, voffA);
;             PG8_WAIT_V(8); PG8_WAIT_L(0); PG8_BAR; PG8_MMA(1, 0, At, B0); PG8_MMA(1, 1, At, B1); PG8_BAR; PG8_SCHED;
.Lmy_nobar_1316:
	s_cmp_eq_u32 s101, 0
	s_cbranch_scc1 .Lmy_strict_1316
	s_add_u32 s44, s42, 0xfff80080
	s_addc_u32 s45, s43, -1
	s_add_i32 s74, 0, 0x10000
	v_add_u32_e32 v132, s74, v252
	v_add_u32_e32 v156, s33, v252
	ds_read_b128 v[116:119], v132
	ds_read_b128 v[124:127], v132 offset:1024
	ds_read_b128 v[128:131], v132 offset:2048
	ds_read_b128 v[132:135], v132 offset:3072
	ds_read_b128 v[144:147], v156
	ds_read_b128 v[148:151], v156 offset:1024
	ds_read_b128 v[152:155], v156 offset:2048
	ds_read_b128 v[156:159], v156 offset:3072
	s_cmp_eq_u32 s73, 28
	s_cselect_b32 s47, s31, s45
	s_cselect_b32 s46, s39, s44
	s_cselect_b32 s45, s29, s72
	s_cselect_b32 s44, s41, s71
	v_lshl_add_u64 v[192:193], s[42:43], 0, v[220:221]
	s_add_i32 m0, s55, 0xc000
	ds_read_b128 v[160:163], v210
	ds_read_b128 v[164:167], v210 offset:1024
	ds_read_b128 v[168:171], v210 offset:2048
	ds_read_b128 v[172:175], v210 offset:3072
	ds_read_b128 v[176:179], v210 offset:4096
	ds_read_b128 v[180:183], v210 offset:5120
	ds_read_b128 v[184:187], v210 offset:6144
	ds_read_b128 v[188:191], v210 offset:7168
	global_load_lds_dwordx4 v[192:193], off
	v_lshl_add_u64 v[192:193], s[42:43], 0, v[222:223]
	s_add_i32 m0, s55, 0xe000
	s_nop 0
	global_load_lds_dwordx4 v[192:193], off
	s_waitcnt lgkmcnt(0)
	s_barrier
	s_setprio 1
	s_waitcnt lgkmcnt(0)
	v_mfma_f32_16x16x32_bf16 v[140:143], v[116:119], v[160:163], 0
	v_mfma_f32_16x16x32_bf16 v[136:139], v[128:131], v[160:163], 0
	v_mfma_f32_16x16x32_bf16 v[108:111], v[116:119], v[168:171], 0
	v_mfma_f32_16x16x32_bf16 v[104:107], v[128:131], v[168:171], 0
	v_mfma_f32_16x16x32_bf16 v[92:95], v[116:119], v[176:179], 0
	v_mfma_f32_16x16x32_bf16 v[88:91], v[128:131], v[176:179], 0
	v_mfma_f32_16x16x32_bf16 v[76:79], v[116:119], v[184:187], 0
	v_mfma_f32_16x16x32_bf16 v[72:75], v[128:131], v[184:187], 0
	v_mfma_f32_16x16x32_bf16 v[140:143], v[124:127], v[164:167], v[140:143]
	v_mfma_f32_16x16x32_bf16 v[136:139], v[132:135], v[164:167], v[136:139]
	v_mfma_f32_16x16x32_bf16 v[108:111], v[124:127], v[172:175], v[108:111]
	v_mfma_f32_16x16x32_bf16 v[104:107], v[132:135], v[172:175], v[104:107]
	v_mfma_f32_16x16x32_bf16 v[92:95], v[124:127], v[180:183], v[92:95]
	v_mfma_f32_16x16x32_bf16 v[88:91], v[132:135], v[180:183], v[88:91]
	v_mfma_f32_16x16x32_bf16 v[76:79], v[124:127], v[188:191], v[76:79]
	v_mfma_f32_16x16x32_bf16 v[72:75], v[132:135], v[188:191], v[72:75]
	s_setprio 0
	s_setprio 1
	v_mfma_f32_16x16x32_bf16 v[120:123], v[144:147], v[160:163], 0
	v_mfma_f32_16x16x32_bf16 v[112:115], v[152:155], v[160:163], 0
	v_mfma_f32_16x16x32_bf16 v[100:103], v[144:147], v[168:171], 0
	v_mfma_f32_16x16x32_bf16 v[96:99], v[152:155], v[168:171], 0
	v_mfma_f32_16x16x32_bf16 v[84:87], v[144:147], v[176:179], 0
	v_mfma_f32_16x16x32_bf16 v[80:83], v[152:155], v[176:179], 0
	v_mfma_f32_16x16x32_bf16 v[68:71], v[144:147], v[184:187], 0
	v_mfma_f32_16x16x32_bf16 v[64:67], v[152:155], v[184:187], 0
	v_mfma_f32_16x16x32_bf16 v[120:123], v[148:151], v[164:167], v[120:123]
	v_mfma_f32_16x16x32_bf16 v[112:115], v[156:159], v[164:167], v[112:115]
	v_mfma_f32_16x16x32_bf16 v[100:103], v[148:151], v[172:175], v[100:103]
	v_mfma_f32_16x16x32_bf16 v[96:99], v[156:159], v[172:175], v[96:99]
	v_mfma_f32_16x16x32_bf16 v[84:87], v[148:151], v[180:183], v[84:87]
	v_mfma_f32_16x16x32_bf16 v[80:83], v[156:159], v[180:183], v[80:83]
	v_mfma_f32_16x16x32_bf16 v[68:71], v[148:151], v[188:191], v[68:71]
	v_mfma_f32_16x16x32_bf16 v[64:67], v[156:159], v[188:191], v[64:67]
	s_setprio 0
	s_barrier
	s_add_i32 s74, s74, s54
	v_lshl_add_u64 v[192:193], s[44:45], 0, v[208:209]
	s_mov_b32 m0, s74
	ds_read_b128 v[160:163], v210 offset:16384
	ds_read_b128 v[164:167], v210 offset:17408
	ds_read_b128 v[168:171], v210 offset:18432
	ds_read_b128 v[172:175], v210 offset:19456
	ds_read_b128 v[176:179], v210 offset:20480
	ds_read_b128 v[180:183], v210 offset:21504
	ds_read_b128 v[184:187], v210 offset:22528
	ds_read_b128 v[188:191], v210 offset:23552
	global_load_lds_dwordx4 v[192:193], off
	s_add_i32 m0, s74, 0x2000
	s_add_u32 s74, s44, 0x80000
	v_lshl_add_u64 v[194:195], s[44:45], 0, v[218:219]
	s_addc_u32 s75, s45, 0
	s_add_i32 s76, s33, s54
	global_load_lds_dwordx4 v[194:195], off
	v_lshl_add_u64 v[196:197], s[74:75], 0, v[208:209]
	s_mov_b32 m0, s76
	v_lshl_add_u64 v[198:199], s[46:47], 0, v[216:217]
	global_load_lds_dwordx4 v[196:197], off
	v_lshl_add_u64 v[196:197], s[74:75], 0, v[218:219]
	s_add_i32 m0, s76, 0x2000
	s_nop 0
	global_load_lds_dwordx4 v[196:197], off
	v_lshl_add_u64 v[196:197], s[46:47], 0, v[214:215]
	s_mov_b32 m0, s55
	s_nop 0
	global_load_lds_dwordx4 v[196:197], off
	s_mov_b32 m0, s56
	s_nop 0
	global_load_lds_dwordx4 v[198:199], off
	s_waitcnt lgkmcnt(0)
	s_barrier
	s_setprio 1
	s_waitcnt lgkmcnt(0)
	v_mfma_f32_16x16x32_bf16 v[60:63], v[116:119], v[160:163], 0
	v_mfma_f32_16x16x32_bf16 v[56:59], v[128:131], v[160:163], 0
	v_mfma_f32_16x16x32_bf16 v[44:47], v[116:119], v[168:171], 0
	v_mfma_f32_16x16x32_bf16 v[40:43], v[128:131], v[168:171], 0
	v_mfma_f32_16x16x32_bf16 v[28:31], v[116:119], v[176:179], 0
	v_mfma_f32_16x16x32_bf16 v[24:27], v[128:131], v[176:179], 0
	v_mfma_f32_16x16x32_bf16 v[12:15], v[116:119], v[184:187], 0
	v_mfma_f32_16x16x32_bf16 v[8:11], v[128:131], v[184:187], 0
	v_mfma_f32_16x16x32_bf16 v[60:63], v[124:127], v[164:167], v[60:63]
	v_mfma_f32_16x16x32_bf16 v[56:59], v[132:135], v[164:167], v[56:59]
	v_mfma_f32_16x16x32_bf16 v[44:47], v[124:127], v[172:175], v[44:47]
	v_mfma_f32_16x16x32_bf16 v[40:43], v[132:135], v[172:175], v[40:43]
	v_mfma_f32_16x16x32_bf16 v[28:31], v[124:127], v[180:183], v[28:31]
	v_mfma_f32_16x16x32_bf16 v[24:27], v[132:135], v[180:183], v[24:27]
	v_mfma_f32_16x16x32_bf16 v[12:15], v[124:127], v[188:191], v[12:15]
	v_mfma_f32_16x16x32_bf16 v[8:11], v[132:135], v[188:191], v[8:11]
	s_setprio 0
	s_setprio 1
	v_mfma_f32_16x16x32_bf16 v[52:55], v[144:147], v[160:163], 0
	v_mfma_f32_16x16x32_bf16 v[48:51], v[152:155], v[160:163], 0
	v_mfma_f32_16x16x32_bf16 v[36:39], v[144:147], v[168:171], 0
	v_mfma_f32_16x16x32_bf16 v[32:35], v[152:155], v[168:171], 0
	v_mfma_f32_16x16x32_bf16 v[20:23], v[144:147], v[176:179], 0
	v_mfma_f32_16x16x32_bf16 v[16:19], v[152:155], v[176:179], 0
	v_mfma_f32_16x16x32_bf16 v[4:7], v[144:147], v[184:187], 0
	v_mfma_f32_16x16x32_bf16 v[0:3], v[152:155], v[184:187], 0
	v_mfma_f32_16x16x32_bf16 v[52:55], v[148:151], v[164:167], v[52:55]
	v_mfma_f32_16x16x32_bf16 v[48:51], v[156:159], v[164:167], v[48:51]
	v_mfma_f32_16x16x32_bf16 v[36:39], v[148:151], v[172:175], v[36:39]
	v_mfma_f32_16x16x32_bf16 v[32:35], v[156:159], v[172:175], v[32:35]
	v_mfma_f32_16x16x32_bf16 v[20:23], v[148:151], v[180:183], v[20:23]
	v_mfma_f32_16x16x32_bf16 v[16:19], v[156:159], v[180:183], v[16:19]
	v_mfma_f32_16x16x32_bf16 v[4:7], v[148:151], v[188:191], v[4:7]
	v_mfma_f32_16x16x32_bf16 v[0:3], v[156:159], v[188:191], v[0:3]
	s_setprio 0
	s_barrier
	s_mov_b32 s101, 0
	s_branch .Lmy_mid_1316

; template <class Epi, class Sched, bool ALIGN_EPI = false, bool SP2 = false>
; __device__ __forceinline__ void gemm_phase(PG8_LAS unsigned char* lds, const Gemm g, const Sched& S, const Epi& E, const int tid) {
;     ...
;         if constexpr (!Epi::AFTER_DRAIN) { E(acc, cur, wr, wc, fr, fq); S.done(cur); }
;         if (!has_next) break;
; #pragma unroll
;         for (int a = 0; a < 2; ++a)
; #pragma unroll
;             for (int b = 0; b < 2; ++b)
; #pragma unroll
;                 for (int m = 0; m < 4; ++m)
; #pragma unroll
;                     for (int n = 0; n < 2; ++n) acc[a][b][m][n] = (f32x4){0.f, 0.f, 0.f, 0.f};
;         cur = nxt; cA = nA; cB = nB; ++ui;
;     __device__ __forceinline__ void operator()(const f32x4 (&acc)[2][2][4][2], const Unit& un, int wr, int wc, int fr_, int fq_) const {
;     ...
;             for (int m = 0; m < 4; ++m) { float s = ssq[ai][m]; s += shx<16>(s); s += shx<32>(s);
;                 if (fq == 0) ps[((size_t)(rbase + ai * 128 + m * 16) * 8 + un.pn) * 4 + wc] = s; }
.LBB0_1338:
	s_or_b64 exec, exec, s[40:41]
	s_andn2_b64 vcc, exec, s[0:1]
	s_mov_b64 s[0:1], -1
	s_cbranch_vccnz .LBB0_1308
	s_mov_b32 s101, 1
	s_andn2_b64 vcc, exec, s[16:17]
	s_cbranch_vccnz .LBB0_1307
	s_mov_b32 s100, 1
	s_branch .LBB0_1307

; #define PG8_STAGE(bufoff, gbase, voff) do { _Pragma("unroll") for (int _i = 0; _i < 2; ++_i) \
;         __builtin_amdgcn_global_load_lds((const unsigned*)((const char*)(gbase) + (voff)[_i]), (PG8_LAS unsigned*)(lds + (bufoff) + ldsw + _i * 8192), 16, 0, 0); } while (0)
; #define PG8_LDA(dst, b, h) do { _Pragma("unroll") for (int m = 0; m < 4; ++m) _Pragma("unroll") for (int k = 0; k < 2; ++k) dst[m][k] = *(const PG8_LAS bf16x8*)(lds + PG8_SA(b, h) + aoff + m * 2048 + k * 1024); } while (0)
; #define PG8_LDB(dst, b, h) do { _Pragma("unroll") for (int n = 0; n < 2; ++n) _Pragma("unroll") for (int k = 0; k < 2; ++k) dst[n][k] = *(const PG8_LAS bf16x8*)(lds + PG8_SB(b, h) + boff + n * 2048 + k * 1024); } while (0)
; #define PG8_MMA(ai, bj, At, Bt) do { __builtin_amdgcn_s_setprio(1); _Pragma("unroll") for (int m = 0; m < 4; ++m) _Pragma("unroll") for (int n = 0; n < 2; ++n) _Pragma("unroll") for (int k = 0; k < 2; ++k) \
;         acc[ai][bj][m][n] = __builtin_amdgcn_mfma_f32_16x16x32_bf16(Bt[n][k], At[m][k], acc[ai][bj][m][n], 0, 0, 0); __builtin_amdgcn_s_setprio(0); } while (0)
; #define PG8_WAIT_V(n) asm volatile("s_waitcnt vmcnt(" #n ")" ::: "memory")
; #define PG8_WAIT_L(n) asm volatile("s_waitcnt lgkmcnt(" #n ")" ::: "memory")
; #define PG8_BAR __builtin_amdgcn_s_barrier()
; #define PG8_SCHED __builtin_amdgcn_sched_barrier(0)
; template <class Epi, class Sched, bool ALIGN_EPI = false, bool SP2 = false>
; __device__ __forceinline__ void gemm_phase(PG8_LAS unsigned char* lds, const Gemm g, const Sched& S, const Epi& E, const int tid) {
;     ...
;             PG8_LDB(B0, 0, 0); PG8_LDB(B1, 0, 1); PG8_SCHED; PG8_LDA(At, 0, 0); PG8_STAGE(PG8_SA(1, 1), a1 + hstep, voffA);
;             PG8_WAIT_V(8); PG8_WAIT_L(0); PG8_BAR; PG8_MMA(0, 0, At, B0); PG8_MMA(0, 1, At, B1); PG8_BAR; PG8_SCHED;
;             PG8_LDA(At, 0, 1); PG8_STAGE(PG8_SB(0, 0), b2, voffB); PG8_STAGE(PG8_SB(0, 1), b2 + hstep, voffB); PG8_STAGE(PG8_SA(0, 0), a2, voffA);
;             PG8_WAIT_V(8); PG8_WAIT_L(0); PG8_BAR; PG8_MMA(1, 0, At, B0); PG8_MMA(1, 1, At, B1); PG8_BAR; PG8_SCHED;
.Lmy_nobar_1479:
	s_cmp_eq_u32 s101, 0
	s_cbranch_scc1 .Lmy_strict_1479
	s_add_u32 s30, s28, 0xfff80080
	s_addc_u32 s31, s29, -1
	s_add_i32 s57, 0, 0x10000
	v_add_u32_e32 v124, s57, v157
	v_add_u32_e32 v154, s33, v157
	ds_read_b128 v[112:115], v124
	ds_read_b128 v[116:119], v124 offset:1024
	ds_read_b128 v[120:123], v124 offset:2048
	ds_read_b128 v[124:127], v124 offset:3072
	ds_read_b128 v[162:165], v154
	ds_read_b128 v[166:169], v154 offset:1024
	ds_read_b128 v[170:173], v154 offset:2048
	ds_read_b128 v[174:177], v154 offset:3072
	s_cmp_eq_u32 s56, 28
	s_cselect_b32 s35, s19, s31
	s_cselect_b32 s34, s25, s30
	s_cselect_b32 s31, s17, s55
	s_cselect_b32 s30, s53, s54
	v_lshl_add_u64 v[206:207], s[28:29], 0, v[150:151]
	s_add_i32 m0, s27, 0xc000
	ds_read_b128 v[178:181], v161
	ds_read_b128 v[182:185], v161 offset:1024
	ds_read_b128 v[186:189], v161 offset:2048
	ds_read_b128 v[190:193], v161 offset:3072
	ds_read_b128 v[194:197], v161 offset:4096
	ds_read_b128 v[198:201], v161 offset:5120
	ds_read_b128 v[202:205], v161 offset:6144
	ds_read_b128 v[214:217], v161 offset:7168
	global_load_lds_dwordx4 v[206:207], off
	v_lshl_add_u64 v[206:207], s[28:29], 0, v[152:153]
	s_add_i32 m0, s27, 0xe000
	s_nop 0
	global_load_lds_dwordx4 v[206:207], off
	s_waitcnt lgkmcnt(0)
	s_barrier
	s_setprio 1
	s_waitcnt lgkmcnt(0)
	v_mfma_f32_16x16x32_bf16 v[140:143], v[112:115], v[178:181], 0
	v_mfma_f32_16x16x32_bf16 v[136:139], v[120:123], v[178:181], 0
	v_mfma_f32_16x16x32_bf16 v[108:111], v[112:115], v[186:189], 0
	v_mfma_f32_16x16x32_bf16 v[104:107], v[120:123], v[186:189], 0
	v_mfma_f32_16x16x32_bf16 v[92:95], v[112:115], v[194:197], 0
	v_mfma_f32_16x16x32_bf16 v[88:91], v[120:123], v[194:197], 0
	v_mfma_f32_16x16x32_bf16 v[76:79], v[112:115], v[202:205], 0
	v_mfma_f32_16x16x32_bf16 v[72:75], v[120:123], v[202:205], 0
	v_mfma_f32_16x16x32_bf16 v[140:143], v[116:119], v[182:185], v[140:143]
	v_mfma_f32_16x16x32_bf16 v[136:139], v[124:127], v[182:185], v[136:139]
	v_mfma_f32_16x16x32_bf16 v[108:111], v[116:119], v[190:193], v[108:111]
	v_mfma_f32_16x16x32_bf16 v[104:107], v[124:127], v[190:193], v[104:107]
	v_mfma_f32_16x16x32_bf16 v[92:95], v[116:119], v[198:201], v[92:95]
	v_mfma_f32_16x16x32_bf16 v[88:91], v[124:127], v[198:201], v[88:91]
	v_mfma_f32_16x16x32_bf16 v[76:79], v[116:119], v[214:217], v[76:79]
	v_mfma_f32_16x16x32_bf16 v[72:75], v[124:127], v[214:217], v[72:75]
	s_setprio 0
	s_setprio 1
	v_mfma_f32_16x16x32_bf16 v[132:135], v[162:165], v[178:181], 0
	v_mfma_f32_16x16x32_bf16 v[128:131], v[170:173], v[178:181], 0
	v_mfma_f32_16x16x32_bf16 v[100:103], v[162:165], v[186:189], 0
	v_mfma_f32_16x16x32_bf16 v[96:99], v[170:173], v[186:189], 0
	v_mfma_f32_16x16x32_bf16 v[84:87], v[162:165], v[194:197], 0
	v_mfma_f32_16x16x32_bf16 v[80:83], v[170:173], v[194:197], 0
	v_mfma_f32_16x16x32_bf16 v[68:71], v[162:165], v[202:205], 0
	v_mfma_f32_16x16x32_bf16 v[64:67], v[170:173], v[202:205], 0
	v_mfma_f32_16x16x32_bf16 v[132:135], v[166:169], v[182:185], v[132:135]
	v_mfma_f32_16x16x32_bf16 v[128:131], v[174:177], v[182:185], v[128:131]
	v_mfma_f32_16x16x32_bf16 v[100:103], v[166:169], v[190:193], v[100:103]
	v_mfma_f32_16x16x32_bf16 v[96:99], v[174:177], v[190:193], v[96:99]
	v_mfma_f32_16x16x32_bf16 v[84:87], v[166:169], v[198:201], v[84:87]
	v_mfma_f32_16x16x32_bf16 v[80:83], v[174:177], v[198:201], v[80:83]
	v_mfma_f32_16x16x32_bf16 v[68:71], v[166:169], v[214:217], v[68:71]
	v_mfma_f32_16x16x32_bf16 v[64:67], v[174:177], v[214:217], v[64:67]
	s_setprio 0
	s_barrier
	s_add_i32 s57, s57, s42
	v_lshl_add_u64 v[206:207], s[30:31], 0, v[208:209]
	s_mov_b32 m0, s57
	ds_read_b128 v[178:181], v161 offset:16384
	ds_read_b128 v[182:185], v161 offset:17408
	ds_read_b128 v[186:189], v161 offset:18432
	ds_read_b128 v[190:193], v161 offset:19456
	ds_read_b128 v[194:197], v161 offset:20480
	ds_read_b128 v[198:201], v161 offset:21504
	ds_read_b128 v[202:205], v161 offset:22528
	ds_read_b128 v[214:217], v161 offset:23552
	global_load_lds_dwordx4 v[206:207], off
	s_add_i32 m0, s57, 0x2000
	s_add_u32 s58, s30, 0x80000
	v_lshl_add_u64 v[210:211], s[30:31], 0, v[144:145]
	s_addc_u32 s59, s31, 0
	s_add_i32 s57, s33, s42
	global_load_lds_dwordx4 v[210:211], off
	v_lshl_add_u64 v[212:213], s[58:59], 0, v[208:209]
	s_mov_b32 m0, s57
	v_lshl_add_u64 v[218:219], s[34:35], 0, v[146:147]
	global_load_lds_dwordx4 v[212:213], off
	v_lshl_add_u64 v[212:213], s[58:59], 0, v[144:145]
	s_add_i32 m0, s57, 0x2000
	s_nop 0
	global_load_lds_dwordx4 v[212:213], off
	v_lshl_add_u64 v[212:213], s[34:35], 0, v[148:149]
	s_mov_b32 m0, s27
	s_nop 0
	global_load_lds_dwordx4 v[212:213], off
	s_mov_b32 m0, s44
	s_nop 0
	global_load_lds_dwordx4 v[218:219], off
	s_waitcnt lgkmcnt(0)
	s_barrier
	s_setprio 1
	s_waitcnt lgkmcnt(0)
	v_mfma_f32_16x16x32_bf16 v[60:63], v[112:115], v[178:181], 0
	v_mfma_f32_16x16x32_bf16 v[56:59], v[120:123], v[178:181], 0
	v_mfma_f32_16x16x32_bf16 v[44:47], v[112:115], v[186:189], 0
	v_mfma_f32_16x16x32_bf16 v[40:43], v[120:123], v[186:189], 0
	v_mfma_f32_16x16x32_bf16 v[28:31], v[112:115], v[194:197], 0
	v_mfma_f32_16x16x32_bf16 v[24:27], v[120:123], v[194:197], 0
	v_mfma_f32_16x16x32_bf16 v[12:15], v[112:115], v[202:205], 0
	v_mfma_f32_16x16x32_bf16 v[8:11], v[120:123], v[202:205], 0
	v_mfma_f32_16x16x32_bf16 v[60:63], v[116:119], v[182:185], v[60:63]
	v_mfma_f32_16x16x32_bf16 v[56:59], v[124:127], v[182:185], v[56:59]
	v_mfma_f32_16x16x32_bf16 v[44:47], v[116:119], v[190:193], v[44:47]
	v_mfma_f32_16x16x32_bf16 v[40:43], v[124:127], v[190:193], v[40:43]
	v_mfma_f32_16x16x32_bf16 v[28:31], v[116:119], v[198:201], v[28:31]
	v_mfma_f32_16x16x32_bf16 v[24:27], v[124:127], v[198:201], v[24:27]
	v_mfma_f32_16x16x32_bf16 v[12:15], v[116:119], v[214:217], v[12:15]
	v_mfma_f32_16x16x32_bf16 v[8:11], v[124:127], v[214:217], v[8:11]
	s_setprio 0
	s_setprio 1
	v_mfma_f32_16x16x32_bf16 v[52:55], v[162:165], v[178:181], 0
	v_mfma_f32_16x16x32_bf16 v[48:51], v[170:173], v[178:181], 0
	v_mfma_f32_16x16x32_bf16 v[36:39], v[162:165], v[186:189], 0
	v_mfma_f32_16x16x32_bf16 v[32:35], v[170:173], v[186:189], 0
	v_mfma_f32_16x16x32_bf16 v[20:23], v[162:165], v[194:197], 0
	v_mfma_f32_16x16x32_bf16 v[16:19], v[170:173], v[194:197], 0
	v_mfma_f32_16x16x32_bf16 v[4:7], v[162:165], v[202:205], 0
	v_mfma_f32_16x16x32_bf16 v[0:3], v[170:173], v[202:205], 0
	v_mfma_f32_16x16x32_bf16 v[52:55], v[166:169], v[182:185], v[52:55]
	v_mfma_f32_16x16x32_bf16 v[48:51], v[174:177], v[182:185], v[48:51]
	v_mfma_f32_16x16x32_bf16 v[36:39], v[166:169], v[190:193], v[36:39]
	v_mfma_f32_16x16x32_bf16 v[32:35], v[174:177], v[190:193], v[32:35]
	v_mfma_f32_16x16x32_bf16 v[20:23], v[166:169], v[198:201], v[20:23]
	v_mfma_f32_16x16x32_bf16 v[16:19], v[174:177], v[198:201], v[16:19]
	v_mfma_f32_16x16x32_bf16 v[4:7], v[166:169], v[214:217], v[4:7]
	v_mfma_f32_16x16x32_bf16 v[0:3], v[174:177], v[214:217], v[0:3]
	s_setprio 0
	s_barrier
	s_mov_b32 s101, 0
	s_branch .Lmy_mid_1479

; __device__ __forceinline__ unsigned pk2(float lo, float hi) { const f32x2 v = {lo, hi}; return __builtin_bit_cast(unsigned, __builtin_convertvector(v, bf16x2_t)); }
; #define EPI_LOOP _Pragma("unroll") for (int ai = 0; ai < 2; ++ai) _Pragma("unroll") for (int m = 0; m < 4; ++m) _Pragma("unroll") for (int bj = 0; bj < 2; ++bj)
;     __device__ __forceinline__ void operator()(const f32x4 (&acc)[2][2][4][2], const Unit& un, int wr, int wc, int fr, int fq) const {
;     ...
;         EPI_LOOP { const int row = rbase + ai * 128 + m * 16, col = cw + bj * 128; const float r = rr[ai][m];
;             f32x4 v0 = acc[ai][bj][m][0] * r + s0[bj], v1 = acc[ai][bj][m][1] * r + s1[bj];
;             v0 = __builtin_elementwise_max(v0, (f32x4){0.f, 0.f, 0.f, 0.f}); v1 = __builtin_elementwise_max(v1, (f32x4){0.f, 0.f, 0.f, 0.f}); v0 = v0 * v0; v1 = v1 * v1;
;             u32x4 w; w.x = pk2(v0.x, v0.y); w.y = pk2(v0.z, v0.w); w.z = pk2(v1.x, v1.y); w.w = pk2(v1.z, v1.w);
;             *(u32x4*)(o + (size_t)row * DFF + col) = w; }
.LBB0_1482:
	v_lshlrev_b64 v[176:177], 14, v[176:177]
	s_mov_b64 s[24:25], 0x200000
	v_readlane_b32 s58, v254, 51
	s_waitcnt vmcnt(0)
	v_pk_fma_f32 v[142:143], v[142:143], v[180:181], v[126:127] op_sel_hi:[1,0,1]
	v_pk_fma_f32 v[140:141], v[140:141], v[180:181], v[124:125] op_sel_hi:[1,0,1]
	v_pk_fma_f32 v[138:139], v[138:139], v[180:181], v[122:123] op_sel_hi:[1,0,1]
	v_pk_fma_f32 v[136:137], v[136:137], v[180:181], v[120:121] op_sel_hi:[1,0,1]
	v_max_f32_e32 v143, 0, v143
	v_max_f32_e32 v142, 0, v142
	v_max_f32_e32 v141, 0, v141
	v_max_f32_e32 v140, 0, v140
	v_max_f32_e32 v139, 0, v139
	v_max_f32_e32 v138, 0, v138
	v_max_f32_e32 v137, 0, v137
	v_max_f32_e32 v136, 0, v136
	v_pk_mul_f32 v[142:143], v[142:143], v[142:143]
	v_pk_mul_f32 v[140:141], v[140:141], v[140:141]
	v_pk_mul_f32 v[138:139], v[138:139], v[138:139]
	v_pk_mul_f32 v[136:137], v[136:137], v[136:137]
	v_cvt_pk_bf16_f32 v140, v140, v141
	v_cvt_pk_bf16_f32 v141, v142, v143
	v_cvt_pk_bf16_f32 v142, v136, v137
	v_cvt_pk_bf16_f32 v143, v138, v139
	v_lshl_add_u64 v[136:137], s[10:11], 0, v[176:177]
	v_lshlrev_b64 v[138:139], 1, v[174:175]
	v_pk_fma_f32 v[134:135], v[134:135], v[180:181], v[118:119] op_sel_hi:[1,0,1]
	v_pk_fma_f32 v[132:133], v[132:133], v[180:181], v[116:117] op_sel_hi:[1,0,1]
	v_pk_fma_f32 v[130:131], v[130:131], v[180:181], v[114:115] op_sel_hi:[1,0,1]
	v_pk_fma_f32 v[128:129], v[128:129], v[180:181], v[112:113] op_sel_hi:[1,0,1]
	v_lshl_add_u64 v[136:137], v[136:137], 0, v[138:139]
	v_max_f32_e32 v135, 0, v135
	v_max_f32_e32 v134, 0, v134
	v_max_f32_e32 v133, 0, v133
	v_max_f32_e32 v132, 0, v132
	v_max_f32_e32 v131, 0, v131
	v_max_f32_e32 v130, 0, v130
	v_max_f32_e32 v129, 0, v129
	v_max_f32_e32 v128, 0, v128
	global_store_dwordx4 v[136:137], v[140:143], off
	v_pk_mul_f32 v[134:135], v[134:135], v[134:135]
	v_pk_mul_f32 v[132:133], v[132:133], v[132:133]
	v_pk_mul_f32 v[140:141], v[130:131], v[130:131]
	v_pk_mul_f32 v[130:131], v[128:129], v[128:129]
	v_pk_fma_f32 v[108:109], v[108:109], v[170:171], v[124:125] op_sel_hi:[1,0,1]
	v_cvt_pk_bf16_f32 v128, v132, v133
	v_cvt_pk_bf16_f32 v129, v134, v135
	v_cvt_pk_bf16_f32 v130, v130, v131
	v_cvt_pk_bf16_f32 v131, v140, v141
	v_pk_fma_f32 v[110:111], v[110:111], v[170:171], v[126:127] op_sel_hi:[1,0,1]
	v_pk_fma_f32 v[106:107], v[106:107], v[170:171], v[122:123] op_sel_hi:[1,0,1]
	v_pk_fma_f32 v[104:105], v[104:105], v[170:171], v[120:121] op_sel_hi:[1,0,1]
	v_max_f32_e32 v109, 0, v109
	v_max_f32_e32 v108, 0, v108
	global_store_dwordx4 v[136:137], v[128:131], off offset:256
	v_max_f32_e32 v111, 0, v111
	v_max_f32_e32 v110, 0, v110
	v_lshlrev_b64 v[128:129], 14, v[172:173]
	v_max_f32_e32 v107, 0, v107
	v_max_f32_e32 v106, 0, v106
	v_max_f32_e32 v105, 0, v105
	v_max_f32_e32 v104, 0, v104
	v_pk_mul_f32 v[108:109], v[108:109], v[108:109]
	v_pk_mul_f32 v[110:111], v[110:111], v[110:111]
	v_pk_mul_f32 v[130:131], v[106:107], v[106:107]
	v_pk_mul_f32 v[106:107], v[104:105], v[104:105]
	v_cvt_pk_bf16_f32 v104, v108, v109
	v_lshl_add_u64 v[108:109], s[10:11], 0, v[128:129]
	v_pk_fma_f32 v[102:103], v[102:103], v[170:171], v[118:119] op_sel_hi:[1,0,1]
	v_pk_fma_f32 v[100:101], v[100:101], v[170:171], v[116:117] op_sel_hi:[1,0,1]
	v_pk_fma_f32 v[98:99], v[98:99], v[170:171], v[114:115] op_sel_hi:[1,0,1]
	v_pk_fma_f32 v[96:97], v[96:97], v[170:171], v[112:113] op_sel_hi:[1,0,1]
	v_cvt_pk_bf16_f32 v105, v110, v111
	v_cvt_pk_bf16_f32 v106, v106, v107
	v_cvt_pk_bf16_f32 v107, v130, v131
	v_lshl_add_u64 v[108:109], v[108:109], 0, v[138:139]
	v_max_f32_e32 v103, 0, v103
	v_max_f32_e32 v102, 0, v102
	v_max_f32_e32 v101, 0, v101
	v_max_f32_e32 v100, 0, v100
	v_max_f32_e32 v99, 0, v99
	v_max_f32_e32 v98, 0, v98
	v_max_f32_e32 v97, 0, v97
	v_max_f32_e32 v96, 0, v96
	global_store_dwordx4 v[108:109], v[104:107], off
	v_pk_mul_f32 v[102:103], v[102:103], v[102:103]
	v_pk_mul_f32 v[100:101], v[100:101], v[100:101]
	v_pk_mul_f32 v[104:105], v[98:99], v[98:99]
	v_pk_mul_f32 v[98:99], v[96:97], v[96:97]
	v_pk_fma_f32 v[92:93], v[92:93], v[166:167], v[124:125] op_sel_hi:[1,0,1]
	v_cvt_pk_bf16_f32 v96, v100, v101
	v_cvt_pk_bf16_f32 v97, v102, v103
	v_cvt_pk_bf16_f32 v98, v98, v99
	v_cvt_pk_bf16_f32 v99, v104, v105
	v_pk_fma_f32 v[94:95], v[94:95], v[166:167], v[126:127] op_sel_hi:[1,0,1]
	v_pk_fma_f32 v[90:91], v[90:91], v[166:167], v[122:123] op_sel_hi:[1,0,1]
	v_pk_fma_f32 v[88:89], v[88:89], v[166:167], v[120:121] op_sel_hi:[1,0,1]
	v_max_f32_e32 v93, 0, v93
	v_max_f32_e32 v92, 0, v92
	global_store_dwordx4 v[108:109], v[96:99], off offset:256
	v_max_f32_e32 v95, 0, v95
	v_max_f32_e32 v94, 0, v94
	v_lshlrev_b64 v[96:97], 14, v[168:169]
	v_max_f32_e32 v91, 0, v91
	v_max_f32_e32 v90, 0, v90
	v_max_f32_e32 v89, 0, v89
	v_max_f32_e32 v88, 0, v88
	v_pk_mul_f32 v[92:93], v[92:93], v[92:93]
	v_pk_mul_f32 v[94:95], v[94:95], v[94:95]
	v_pk_mul_f32 v[98:99], v[90:91], v[90:91]
	v_pk_mul_f32 v[90:91], v[88:89], v[88:89]
	v_cvt_pk_bf16_f32 v88, v92, v93
	v_lshl_add_u64 v[92:93], s[10:11], 0, v[96:97]
	v_pk_fma_f32 v[86:87], v[86:87], v[166:167], v[118:119] op_sel_hi:[1,0,1]
	v_pk_fma_f32 v[84:85], v[84:85], v[166:167], v[116:117] op_sel_hi:[1,0,1]
	v_pk_fma_f32 v[82:83], v[82:83], v[166:167], v[114:115] op_sel_hi:[1,0,1]
	v_pk_fma_f32 v[80:81], v[80:81], v[166:167], v[112:113] op_sel_hi:[1,0,1]
	v_cvt_pk_bf16_f32 v89, v94, v95
	v_cvt_pk_bf16_f32 v90, v90, v91
	v_cvt_pk_bf16_f32 v91, v98, v99
	v_lshl_add_u64 v[92:93], v[92:93], 0, v[138:139]
	v_max_f32_e32 v87, 0, v87
	v_max_f32_e32 v86, 0, v86
	v_max_f32_e32 v85, 0, v85
	v_max_f32_e32 v84, 0, v84
	v_max_f32_e32 v83, 0, v83
	v_max_f32_e32 v82, 0, v82
	v_max_f32_e32 v81, 0, v81
	v_max_f32_e32 v80, 0, v80
; __device__ __forceinline__ unsigned pk2(float lo, float hi) { const f32x2 v = {lo, hi}; return __builtin_bit_cast(unsigned, __builtin_convertvector(v, bf16x2_t)); }
; #define EPI_LOOP _Pragma("unroll") for (int ai = 0; ai < 2; ++ai) _Pragma("unroll") for (int m = 0; m < 4; ++m) _Pragma("unroll") for (int bj = 0; bj < 2; ++bj)
;     __device__ __forceinline__ void operator()(const f32x4 (&acc)[2][2][4][2], const Unit& un, int wr, int wc, int fr, int fq) const {
;     ...
;         EPI_LOOP { const int row = rbase + ai * 128 + m * 16, col = cw + bj * 128; const float r = rr[ai][m];
;             f32x4 v0 = acc[ai][bj][m][0] * r + s0[bj], v1 = acc[ai][bj][m][1] * r + s1[bj];
;             v0 = __builtin_elementwise_max(v0, (f32x4){0.f, 0.f, 0.f, 0.f}); v1 = __builtin_elementwise_max(v1, (f32x4){0.f, 0.f, 0.f, 0.f}); v0 = v0 * v0; v1 = v1 * v1;
;             u32x4 w; w.x = pk2(v0.x, v0.y); w.y = pk2(v0.z, v0.w); w.z = pk2(v1.x, v1.y); w.w = pk2(v1.z, v1.w);
;             *(u32x4*)(o + (size_t)row * DFF + col) = w; }
	global_store_dwordx4 v[92:93], v[88:91], off
	v_pk_mul_f32 v[86:87], v[86:87], v[86:87]
	v_pk_mul_f32 v[84:85], v[84:85], v[84:85]
	v_pk_mul_f32 v[88:89], v[82:83], v[82:83]
	v_pk_mul_f32 v[82:83], v[80:81], v[80:81]
	v_pk_fma_f32 v[76:77], v[76:77], v[162:163], v[124:125] op_sel_hi:[1,0,1]
	v_cvt_pk_bf16_f32 v80, v84, v85
	v_cvt_pk_bf16_f32 v81, v86, v87
	v_cvt_pk_bf16_f32 v82, v82, v83
	v_cvt_pk_bf16_f32 v83, v88, v89
	v_pk_fma_f32 v[78:79], v[78:79], v[162:163], v[126:127] op_sel_hi:[1,0,1]
	v_pk_fma_f32 v[74:75], v[74:75], v[162:163], v[122:123] op_sel_hi:[1,0,1]
	v_pk_fma_f32 v[72:73], v[72:73], v[162:163], v[120:121] op_sel_hi:[1,0,1]
	v_max_f32_e32 v77, 0, v77
	v_max_f32_e32 v76, 0, v76
	global_store_dwordx4 v[92:93], v[80:83], off offset:256
	v_max_f32_e32 v79, 0, v79
	v_max_f32_e32 v78, 0, v78
	v_lshlrev_b64 v[80:81], 14, v[164:165]
	v_max_f32_e32 v75, 0, v75
	v_max_f32_e32 v74, 0, v74
	v_max_f32_e32 v73, 0, v73
	v_max_f32_e32 v72, 0, v72
	v_pk_mul_f32 v[76:77], v[76:77], v[76:77]
	v_pk_mul_f32 v[78:79], v[78:79], v[78:79]
	v_pk_mul_f32 v[82:83], v[74:75], v[74:75]
	v_pk_mul_f32 v[74:75], v[72:73], v[72:73]
	v_cvt_pk_bf16_f32 v72, v76, v77
	v_lshl_add_u64 v[76:77], s[10:11], 0, v[80:81]
	v_pk_fma_f32 v[70:71], v[70:71], v[162:163], v[118:119] op_sel_hi:[1,0,1]
	v_pk_fma_f32 v[68:69], v[68:69], v[162:163], v[116:117] op_sel_hi:[1,0,1]
	v_pk_fma_f32 v[66:67], v[66:67], v[162:163], v[114:115] op_sel_hi:[1,0,1]
	v_pk_fma_f32 v[64:65], v[64:65], v[162:163], v[112:113] op_sel_hi:[1,0,1]
	v_cvt_pk_bf16_f32 v73, v78, v79
	v_cvt_pk_bf16_f32 v74, v74, v75
	v_cvt_pk_bf16_f32 v75, v82, v83
	v_lshl_add_u64 v[76:77], v[76:77], 0, v[138:139]
	v_max_f32_e32 v71, 0, v71
	v_max_f32_e32 v70, 0, v70
	v_max_f32_e32 v69, 0, v69
	v_max_f32_e32 v68, 0, v68
	v_max_f32_e32 v67, 0, v67
	v_max_f32_e32 v66, 0, v66
	v_max_f32_e32 v65, 0, v65
	v_max_f32_e32 v64, 0, v64
	v_pk_fma_f32 v[62:63], v[62:63], v[160:161], v[126:127] op_sel_hi:[1,0,1]
	global_store_dwordx4 v[76:77], v[72:75], off
	v_pk_mul_f32 v[70:71], v[70:71], v[70:71]
	v_pk_mul_f32 v[68:69], v[68:69], v[68:69]
	v_pk_mul_f32 v[72:73], v[66:67], v[66:67]
	v_pk_mul_f32 v[66:67], v[64:65], v[64:65]
	v_pk_fma_f32 v[60:61], v[60:61], v[160:161], v[124:125] op_sel_hi:[1,0,1]
	v_pk_fma_f32 v[58:59], v[58:59], v[160:161], v[122:123] op_sel_hi:[1,0,1]
	v_pk_fma_f32 v[56:57], v[56:57], v[160:161], v[120:121] op_sel_hi:[1,0,1]
	v_max_f32_e32 v63, 0, v63
	v_max_f32_e32 v62, 0, v62
	v_cvt_pk_bf16_f32 v64, v68, v69
	v_cvt_pk_bf16_f32 v65, v70, v71
	v_cvt_pk_bf16_f32 v66, v66, v67
	v_cvt_pk_bf16_f32 v67, v72, v73
	v_max_f32_e32 v61, 0, v61
	v_max_f32_e32 v60, 0, v60
	v_max_f32_e32 v59, 0, v59
	v_max_f32_e32 v58, 0, v58
	v_max_f32_e32 v57, 0, v57
	v_max_f32_e32 v56, 0, v56
	v_pk_mul_f32 v[62:63], v[62:63], v[62:63]
	global_store_dwordx4 v[76:77], v[64:67], off offset:256
	v_pk_mul_f32 v[60:61], v[60:61], v[60:61]
	v_pk_fma_f32 v[54:55], v[54:55], v[160:161], v[118:119] op_sel_hi:[1,0,1]
	v_pk_mul_f32 v[64:65], v[58:59], v[58:59]
	v_pk_mul_f32 v[58:59], v[56:57], v[56:57]
	v_cvt_pk_bf16_f32 v57, v62, v63
	v_add_co_u32_e32 v62, vcc, s78, v136
	v_pk_fma_f32 v[52:53], v[52:53], v[160:161], v[116:117] op_sel_hi:[1,0,1]
	v_pk_fma_f32 v[50:51], v[50:51], v[160:161], v[114:115] op_sel_hi:[1,0,1]
	v_pk_fma_f32 v[48:49], v[48:49], v[160:161], v[112:113] op_sel_hi:[1,0,1]
	v_cvt_pk_bf16_f32 v56, v60, v61
	v_cvt_pk_bf16_f32 v58, v58, v59
	v_cvt_pk_bf16_f32 v59, v64, v65
	v_addc_co_u32_e32 v63, vcc, 0, v137, vcc
	v_max_f32_e32 v55, 0, v55
	v_max_f32_e32 v54, 0, v54
	v_max_f32_e32 v53, 0, v53
	v_max_f32_e32 v52, 0, v52
	v_max_f32_e32 v51, 0, v51
	v_max_f32_e32 v50, 0, v50
	v_max_f32_e32 v49, 0, v49
	v_max_f32_e32 v48, 0, v48
	v_pk_fma_f32 v[46:47], v[46:47], v[158:159], v[126:127] op_sel_hi:[1,0,1]
	global_store_dwordx4 v[62:63], v[56:59], off
	v_pk_mul_f32 v[54:55], v[54:55], v[54:55]
	v_pk_mul_f32 v[52:53], v[52:53], v[52:53]
	v_pk_mul_f32 v[56:57], v[50:51], v[50:51]
	v_pk_mul_f32 v[50:51], v[48:49], v[48:49]
	v_pk_fma_f32 v[44:45], v[44:45], v[158:159], v[124:125] op_sel_hi:[1,0,1]
	v_pk_fma_f32 v[42:43], v[42:43], v[158:159], v[122:123] op_sel_hi:[1,0,1]
	v_pk_fma_f32 v[40:41], v[40:41], v[158:159], v[120:121] op_sel_hi:[1,0,1]
	v_max_f32_e32 v47, 0, v47
	v_max_f32_e32 v46, 0, v46
	v_lshl_add_u64 v[60:61], v[136:137], 0, s[24:25]
	v_cvt_pk_bf16_f32 v48, v52, v53
	v_cvt_pk_bf16_f32 v49, v54, v55
	v_cvt_pk_bf16_f32 v50, v50, v51
	v_cvt_pk_bf16_f32 v51, v56, v57
	v_max_f32_e32 v45, 0, v45
	v_max_f32_e32 v44, 0, v44
	v_max_f32_e32 v43, 0, v43
	v_max_f32_e32 v42, 0, v42
	v_max_f32_e32 v41, 0, v41
	v_max_f32_e32 v40, 0, v40
	v_pk_mul_f32 v[46:47], v[46:47], v[46:47]
	global_store_dwordx4 v[60:61], v[48:51], off offset:256
	v_pk_mul_f32 v[44:45], v[44:45], v[44:45]
	v_pk_fma_f32 v[38:39], v[38:39], v[158:159], v[118:119] op_sel_hi:[1,0,1]
	v_pk_mul_f32 v[48:49], v[42:43], v[42:43]
	v_pk_mul_f32 v[42:43], v[40:41], v[40:41]
	v_cvt_pk_bf16_f32 v41, v46, v47
	v_add_co_u32_e32 v46, vcc, s74, v136
; __device__ __forceinline__ unsigned pk2(float lo, float hi) { const f32x2 v = {lo, hi}; return __builtin_bit_cast(unsigned, __builtin_convertvector(v, bf16x2_t)); }
; #define EPI_LOOP _Pragma("unroll") for (int ai = 0; ai < 2; ++ai) _Pragma("unroll") for (int m = 0; m < 4; ++m) _Pragma("unroll") for (int bj = 0; bj < 2; ++bj)
; template <class Epi, class Sched, bool ALIGN_EPI = false, bool SP2 = false>
; __device__ __forceinline__ void gemm_phase(PG8_LAS unsigned char* lds, const Gemm g, const Sched& S, const Epi& E, const int tid) {
;     ...
;         if constexpr (!Epi::AFTER_DRAIN) { E(acc, cur, wr, wc, fr, fq); S.done(cur); }
;         if (!has_next) break;
; #pragma unroll
;         for (int a = 0; a < 2; ++a)
; #pragma unroll
;             for (int b = 0; b < 2; ++b)
; #pragma unroll
;                 for (int m = 0; m < 4; ++m)
; #pragma unroll
;                     for (int n = 0; n < 2; ++n) acc[a][b][m][n] = (f32x4){0.f, 0.f, 0.f, 0.f};
;         cur = nxt; cA = nA; cB = nB; ++ui;
;     __device__ __forceinline__ void operator()(const f32x4 (&acc)[2][2][4][2], const Unit& un, int wr, int wc, int fr, int fq) const {
;     ...
;         EPI_LOOP { const int row = rbase + ai * 128 + m * 16, col = cw + bj * 128; const float r = rr[ai][m];
;             f32x4 v0 = acc[ai][bj][m][0] * r + s0[bj], v1 = acc[ai][bj][m][1] * r + s1[bj];
;             v0 = __builtin_elementwise_max(v0, (f32x4){0.f, 0.f, 0.f, 0.f}); v1 = __builtin_elementwise_max(v1, (f32x4){0.f, 0.f, 0.f, 0.f}); v0 = v0 * v0; v1 = v1 * v1;
;             u32x4 w; w.x = pk2(v0.x, v0.y); w.y = pk2(v0.z, v0.w); w.z = pk2(v1.x, v1.y); w.w = pk2(v1.z, v1.w);
;             *(u32x4*)(o + (size_t)row * DFF + col) = w; }
	v_pk_fma_f32 v[36:37], v[36:37], v[158:159], v[116:117] op_sel_hi:[1,0,1]
	v_pk_fma_f32 v[34:35], v[34:35], v[158:159], v[114:115] op_sel_hi:[1,0,1]
	v_pk_fma_f32 v[32:33], v[32:33], v[158:159], v[112:113] op_sel_hi:[1,0,1]
	v_cvt_pk_bf16_f32 v40, v44, v45
	v_cvt_pk_bf16_f32 v42, v42, v43
	v_cvt_pk_bf16_f32 v43, v48, v49
	v_addc_co_u32_e32 v47, vcc, 0, v137, vcc
	v_max_f32_e32 v39, 0, v39
	v_max_f32_e32 v38, 0, v38
	v_max_f32_e32 v37, 0, v37
	v_max_f32_e32 v36, 0, v36
	v_max_f32_e32 v35, 0, v35
	v_max_f32_e32 v34, 0, v34
	v_max_f32_e32 v33, 0, v33
	v_max_f32_e32 v32, 0, v32
	v_pk_fma_f32 v[30:31], v[30:31], v[156:157], v[126:127] op_sel_hi:[1,0,1]
	s_mov_b64 s[24:25], 0x240000
	global_store_dwordx4 v[46:47], v[40:43], off
	v_pk_mul_f32 v[38:39], v[38:39], v[38:39]
	v_pk_mul_f32 v[36:37], v[36:37], v[36:37]
	v_pk_mul_f32 v[40:41], v[34:35], v[34:35]
	v_pk_mul_f32 v[34:35], v[32:33], v[32:33]
	v_pk_fma_f32 v[28:29], v[28:29], v[156:157], v[124:125] op_sel_hi:[1,0,1]
	v_pk_fma_f32 v[26:27], v[26:27], v[156:157], v[122:123] op_sel_hi:[1,0,1]
	v_pk_fma_f32 v[24:25], v[24:25], v[156:157], v[120:121] op_sel_hi:[1,0,1]
	v_max_f32_e32 v31, 0, v31
	v_max_f32_e32 v30, 0, v30
	v_lshl_add_u64 v[44:45], v[136:137], 0, s[24:25]
	v_cvt_pk_bf16_f32 v32, v36, v37
	v_cvt_pk_bf16_f32 v33, v38, v39
	v_cvt_pk_bf16_f32 v34, v34, v35
	v_cvt_pk_bf16_f32 v35, v40, v41
	v_max_f32_e32 v29, 0, v29
	v_max_f32_e32 v28, 0, v28
	v_max_f32_e32 v27, 0, v27
	v_max_f32_e32 v26, 0, v26
	v_max_f32_e32 v25, 0, v25
	v_max_f32_e32 v24, 0, v24
	v_pk_mul_f32 v[30:31], v[30:31], v[30:31]
	global_store_dwordx4 v[44:45], v[32:35], off offset:256
	v_pk_mul_f32 v[28:29], v[28:29], v[28:29]
	v_pk_fma_f32 v[22:23], v[22:23], v[156:157], v[118:119] op_sel_hi:[1,0,1]
	v_pk_mul_f32 v[32:33], v[26:27], v[26:27]
	v_pk_mul_f32 v[26:27], v[24:25], v[24:25]
	v_cvt_pk_bf16_f32 v25, v30, v31
	v_add_co_u32_e32 v30, vcc, s71, v136
	v_pk_fma_f32 v[20:21], v[20:21], v[156:157], v[116:117] op_sel_hi:[1,0,1]
	v_pk_fma_f32 v[18:19], v[18:19], v[156:157], v[114:115] op_sel_hi:[1,0,1]
	v_pk_fma_f32 v[16:17], v[16:17], v[156:157], v[112:113] op_sel_hi:[1,0,1]
	v_cvt_pk_bf16_f32 v24, v28, v29
	v_cvt_pk_bf16_f32 v26, v26, v27
	v_cvt_pk_bf16_f32 v27, v32, v33
	v_addc_co_u32_e32 v31, vcc, 0, v137, vcc
	v_max_f32_e32 v23, 0, v23
	v_max_f32_e32 v22, 0, v22
	v_max_f32_e32 v21, 0, v21
	v_max_f32_e32 v20, 0, v20
	v_max_f32_e32 v19, 0, v19
	v_max_f32_e32 v18, 0, v18
	v_max_f32_e32 v17, 0, v17
	v_max_f32_e32 v16, 0, v16
	v_pk_fma_f32 v[14:15], v[14:15], v[154:155], v[126:127] op_sel_hi:[1,0,1]
	s_mov_b64 s[24:25], 0x280000
	global_store_dwordx4 v[30:31], v[24:27], off
	v_pk_mul_f32 v[22:23], v[22:23], v[22:23]
	v_pk_mul_f32 v[20:21], v[20:21], v[20:21]
	v_pk_mul_f32 v[24:25], v[18:19], v[18:19]
	v_pk_mul_f32 v[18:19], v[16:17], v[16:17]
	v_pk_fma_f32 v[12:13], v[12:13], v[154:155], v[124:125] op_sel_hi:[1,0,1]
	v_pk_fma_f32 v[10:11], v[10:11], v[154:155], v[122:123] op_sel_hi:[1,0,1]
	v_pk_fma_f32 v[8:9], v[8:9], v[154:155], v[120:121] op_sel_hi:[1,0,1]
	v_max_f32_e32 v15, 0, v15
	v_max_f32_e32 v14, 0, v14
	v_lshl_add_u64 v[28:29], v[136:137], 0, s[24:25]
	v_cvt_pk_bf16_f32 v16, v20, v21
	v_cvt_pk_bf16_f32 v17, v22, v23
	v_cvt_pk_bf16_f32 v18, v18, v19
	v_cvt_pk_bf16_f32 v19, v24, v25
	v_max_f32_e32 v13, 0, v13
	v_max_f32_e32 v12, 0, v12
	v_max_f32_e32 v11, 0, v11
	v_max_f32_e32 v10, 0, v10
	v_max_f32_e32 v9, 0, v9
	v_max_f32_e32 v8, 0, v8
	v_pk_mul_f32 v[14:15], v[14:15], v[14:15]
	global_store_dwordx4 v[28:29], v[16:19], off offset:256
	v_pk_mul_f32 v[12:13], v[12:13], v[12:13]
	v_pk_fma_f32 v[6:7], v[6:7], v[154:155], v[118:119] op_sel_hi:[1,0,1]
	v_pk_mul_f32 v[16:17], v[10:11], v[10:11]
	v_pk_mul_f32 v[10:11], v[8:9], v[8:9]
	v_cvt_pk_bf16_f32 v9, v14, v15
	v_add_co_u32_e32 v14, vcc, s72, v136
	v_pk_fma_f32 v[4:5], v[4:5], v[154:155], v[116:117] op_sel_hi:[1,0,1]
	v_pk_fma_f32 v[2:3], v[2:3], v[154:155], v[114:115] op_sel_hi:[1,0,1]
	v_pk_fma_f32 v[0:1], v[0:1], v[154:155], v[112:113] op_sel_hi:[1,0,1]
	v_cvt_pk_bf16_f32 v8, v12, v13
	v_cvt_pk_bf16_f32 v10, v10, v11
	v_cvt_pk_bf16_f32 v11, v16, v17
	v_addc_co_u32_e32 v15, vcc, 0, v137, vcc
	v_max_f32_e32 v7, 0, v7
	v_max_f32_e32 v6, 0, v6
	v_max_f32_e32 v5, 0, v5
	v_max_f32_e32 v4, 0, v4
	v_max_f32_e32 v3, 0, v3
	v_max_f32_e32 v2, 0, v2
	v_max_f32_e32 v1, 0, v1
	v_max_f32_e32 v0, 0, v0
	s_mov_b64 s[24:25], 0x2c0000
	global_store_dwordx4 v[14:15], v[8:11], off
	v_pk_mul_f32 v[6:7], v[6:7], v[6:7]
	v_pk_mul_f32 v[4:5], v[4:5], v[4:5]
	v_pk_mul_f32 v[8:9], v[2:3], v[2:3]
	v_pk_mul_f32 v[2:3], v[0:1], v[0:1]
	v_lshl_add_u64 v[12:13], v[136:137], 0, s[24:25]
	v_cvt_pk_bf16_f32 v0, v4, v5
	v_cvt_pk_bf16_f32 v1, v6, v7
	v_cvt_pk_bf16_f32 v2, v2, v3
	v_cvt_pk_bf16_f32 v3, v8, v9
	s_mov_b64 s[24:25], -1
	s_andn2_b64 vcc, exec, s[0:1]
	global_store_dwordx4 v[12:13], v[0:3], off offset:256
	s_cbranch_vccnz .LBB0_1475
	s_mov_b32 s101, 1
	s_andn2_b64 vcc, exec, s[6:7]
	s_cbranch_vccnz .LBB0_1474
	s_mov_b32 s100, 1
	s_branch .LBB0_1474

; #define PG8_STAGE(bufoff, gbase, voff) do { _Pragma("unroll") for (int _i = 0; _i < 2; ++_i) \
;         __builtin_amdgcn_global_load_lds((const unsigned*)((const char*)(gbase) + (voff)[_i]), (PG8_LAS unsigned*)(lds + (bufoff) + ldsw + _i * 8192), 16, 0, 0); } while (0)
; #define PG8_LDA(dst, b, h) do { _Pragma("unroll") for (int m = 0; m < 4; ++m) _Pragma("unroll") for (int k = 0; k < 2; ++k) dst[m][k] = *(const PG8_LAS bf16x8*)(lds + PG8_SA(b, h) + aoff + m * 2048 + k * 1024); } while (0)
; #define PG8_LDB(dst, b, h) do { _Pragma("unroll") for (int n = 0; n < 2; ++n) _Pragma("unroll") for (int k = 0; k < 2; ++k) dst[n][k] = *(const PG8_LAS bf16x8*)(lds + PG8_SB(b, h) + boff + n * 2048 + k * 1024); } while (0)
; #define PG8_MMA(ai, bj, At, Bt) do { __builtin_amdgcn_s_setprio(1); _Pragma("unroll") for (int m = 0; m < 4; ++m) _Pragma("unroll") for (int n = 0; n < 2; ++n) _Pragma("unroll") for (int k = 0; k < 2; ++k) \
;         acc[ai][bj][m][n] = __builtin_amdgcn_mfma_f32_16x16x32_bf16(Bt[n][k], At[m][k], acc[ai][bj][m][n], 0, 0, 0); __builtin_amdgcn_s_setprio(0); } while (0)
; #define PG8_WAIT_V(n) asm volatile("s_waitcnt vmcnt(" #n ")" ::: "memory")
; #define PG8_WAIT_L(n) asm volatile("s_waitcnt lgkmcnt(" #n ")" ::: "memory")
; #define PG8_BAR __builtin_amdgcn_s_barrier()
; #define PG8_SCHED __builtin_amdgcn_sched_barrier(0)
; template <class Epi, class Sched, bool ALIGN_EPI = false, bool SP2 = false>
; __device__ __forceinline__ void gemm_phase(PG8_LAS unsigned char* lds, const Gemm g, const Sched& S, const Epi& E, const int tid) {
;     ...
;             PG8_LDB(B0, 0, 0); PG8_LDB(B1, 0, 1); PG8_SCHED; PG8_LDA(At, 0, 0); PG8_STAGE(PG8_SA(1, 1), a1 + hstep, voffA);
;             PG8_WAIT_V(8); PG8_WAIT_L(0); PG8_BAR; PG8_MMA(0, 0, At, B0); PG8_MMA(0, 1, At, B1); PG8_BAR; PG8_SCHED;
;             PG8_LDA(At, 0, 1); PG8_STAGE(PG8_SB(0, 0), b2, voffB); PG8_STAGE(PG8_SB(0, 1), b2 + hstep, voffB); PG8_STAGE(PG8_SA(0, 0), a2, voffA);
;             PG8_WAIT_V(8); PG8_WAIT_L(0); PG8_BAR; PG8_MMA(1, 0, At, B0); PG8_MMA(1, 1, At, B1); PG8_BAR; PG8_SCHED;
.Lmy_nobar_1559:
	s_cmp_eq_u32 s101, 0
	s_cbranch_scc1 .Lmy_strict_1559
	s_add_u32 s44, s42, 0xffe00080
	s_addc_u32 s45, s43, -1
	s_add_i32 s74, 0, 0x10000
	v_add_u32_e32 v132, s74, v252
	v_add_u32_e32 v156, s33, v252
	ds_read_b128 v[116:119], v132
	ds_read_b128 v[124:127], v132 offset:1024
	ds_read_b128 v[128:131], v132 offset:2048
	ds_read_b128 v[132:135], v132 offset:3072
	ds_read_b128 v[144:147], v156
	ds_read_b128 v[148:151], v156 offset:1024
	ds_read_b128 v[152:155], v156 offset:2048
	ds_read_b128 v[156:159], v156 offset:3072
	s_cmpk_eq_i32 s73, 0x7c
	s_cselect_b32 s47, s31, s45
	s_cselect_b32 s46, s39, s44
	s_cselect_b32 s45, s29, s72
	s_cselect_b32 s44, s41, s71
	v_lshl_add_u64 v[192:193], s[42:43], 0, v[220:221]
	s_add_i32 m0, s55, 0xc000
	ds_read_b128 v[160:163], v210
	ds_read_b128 v[164:167], v210 offset:1024
	ds_read_b128 v[168:171], v210 offset:2048
	ds_read_b128 v[172:175], v210 offset:3072
	ds_read_b128 v[176:179], v210 offset:4096
	ds_read_b128 v[180:183], v210 offset:5120
	ds_read_b128 v[184:187], v210 offset:6144
	ds_read_b128 v[188:191], v210 offset:7168
	global_load_lds_dwordx4 v[192:193], off
	v_lshl_add_u64 v[192:193], s[42:43], 0, v[222:223]
	s_add_i32 m0, s55, 0xe000
	s_nop 0
	global_load_lds_dwordx4 v[192:193], off
	s_waitcnt lgkmcnt(0)
	s_barrier
	s_setprio 1
	s_waitcnt lgkmcnt(0)
	v_mfma_f32_16x16x32_bf16 v[140:143], v[116:119], v[160:163], 0
	v_mfma_f32_16x16x32_bf16 v[136:139], v[128:131], v[160:163], 0
	v_mfma_f32_16x16x32_bf16 v[108:111], v[116:119], v[168:171], 0
	v_mfma_f32_16x16x32_bf16 v[104:107], v[128:131], v[168:171], 0
	v_mfma_f32_16x16x32_bf16 v[92:95], v[116:119], v[176:179], 0
	v_mfma_f32_16x16x32_bf16 v[88:91], v[128:131], v[176:179], 0
	v_mfma_f32_16x16x32_bf16 v[76:79], v[116:119], v[184:187], 0
	v_mfma_f32_16x16x32_bf16 v[72:75], v[128:131], v[184:187], 0
	v_mfma_f32_16x16x32_bf16 v[140:143], v[124:127], v[164:167], v[140:143]
	v_mfma_f32_16x16x32_bf16 v[136:139], v[132:135], v[164:167], v[136:139]
	v_mfma_f32_16x16x32_bf16 v[108:111], v[124:127], v[172:175], v[108:111]
	v_mfma_f32_16x16x32_bf16 v[104:107], v[132:135], v[172:175], v[104:107]
	v_mfma_f32_16x16x32_bf16 v[92:95], v[124:127], v[180:183], v[92:95]
	v_mfma_f32_16x16x32_bf16 v[88:91], v[132:135], v[180:183], v[88:91]
	v_mfma_f32_16x16x32_bf16 v[76:79], v[124:127], v[188:191], v[76:79]
	v_mfma_f32_16x16x32_bf16 v[72:75], v[132:135], v[188:191], v[72:75]
	s_setprio 0
	s_setprio 1
	v_mfma_f32_16x16x32_bf16 v[120:123], v[144:147], v[160:163], 0
	v_mfma_f32_16x16x32_bf16 v[112:115], v[152:155], v[160:163], 0
	v_mfma_f32_16x16x32_bf16 v[100:103], v[144:147], v[168:171], 0
	v_mfma_f32_16x16x32_bf16 v[96:99], v[152:155], v[168:171], 0
	v_mfma_f32_16x16x32_bf16 v[84:87], v[144:147], v[176:179], 0
	v_mfma_f32_16x16x32_bf16 v[80:83], v[152:155], v[176:179], 0
	v_mfma_f32_16x16x32_bf16 v[68:71], v[144:147], v[184:187], 0
	v_mfma_f32_16x16x32_bf16 v[64:67], v[152:155], v[184:187], 0
	v_mfma_f32_16x16x32_bf16 v[120:123], v[148:151], v[164:167], v[120:123]
	v_mfma_f32_16x16x32_bf16 v[112:115], v[156:159], v[164:167], v[112:115]
	v_mfma_f32_16x16x32_bf16 v[100:103], v[148:151], v[172:175], v[100:103]
	v_mfma_f32_16x16x32_bf16 v[96:99], v[156:159], v[172:175], v[96:99]
	v_mfma_f32_16x16x32_bf16 v[84:87], v[148:151], v[180:183], v[84:87]
	v_mfma_f32_16x16x32_bf16 v[80:83], v[156:159], v[180:183], v[80:83]
	v_mfma_f32_16x16x32_bf16 v[68:71], v[148:151], v[188:191], v[68:71]
	v_mfma_f32_16x16x32_bf16 v[64:67], v[156:159], v[188:191], v[64:67]
	s_setprio 0
	s_barrier
	s_add_i32 s74, s74, s54
	v_lshl_add_u64 v[192:193], s[44:45], 0, v[208:209]
	s_mov_b32 m0, s74
	ds_read_b128 v[160:163], v210 offset:16384
	ds_read_b128 v[164:167], v210 offset:17408
	ds_read_b128 v[168:171], v210 offset:18432
	ds_read_b128 v[172:175], v210 offset:19456
	ds_read_b128 v[176:179], v210 offset:20480
	ds_read_b128 v[180:183], v210 offset:21504
	ds_read_b128 v[184:187], v210 offset:22528
	ds_read_b128 v[188:191], v210 offset:23552
	global_load_lds_dwordx4 v[192:193], off
	s_add_i32 m0, s74, 0x2000
	s_add_u32 s74, s44, 0x200000
	v_lshl_add_u64 v[194:195], s[44:45], 0, v[218:219]
	s_addc_u32 s75, s45, 0
	s_add_i32 s76, s33, s54
	global_load_lds_dwordx4 v[194:195], off
	v_lshl_add_u64 v[196:197], s[74:75], 0, v[208:209]
	s_mov_b32 m0, s76
	v_lshl_add_u64 v[198:199], s[46:47], 0, v[216:217]
	global_load_lds_dwordx4 v[196:197], off
	v_lshl_add_u64 v[196:197], s[74:75], 0, v[218:219]
	s_add_i32 m0, s76, 0x2000
	s_nop 0
	global_load_lds_dwordx4 v[196:197], off
	v_lshl_add_u64 v[196:197], s[46:47], 0, v[214:215]
	s_mov_b32 m0, s55
	s_nop 0
	global_load_lds_dwordx4 v[196:197], off
	s_mov_b32 m0, s56
	s_nop 0
	global_load_lds_dwordx4 v[198:199], off
	s_waitcnt lgkmcnt(0)
	s_barrier
	s_setprio 1
	s_waitcnt lgkmcnt(0)
	v_mfma_f32_16x16x32_bf16 v[60:63], v[116:119], v[160:163], 0
	v_mfma_f32_16x16x32_bf16 v[56:59], v[128:131], v[160:163], 0
	v_mfma_f32_16x16x32_bf16 v[44:47], v[116:119], v[168:171], 0
	v_mfma_f32_16x16x32_bf16 v[40:43], v[128:131], v[168:171], 0
	v_mfma_f32_16x16x32_bf16 v[28:31], v[116:119], v[176:179], 0
	v_mfma_f32_16x16x32_bf16 v[24:27], v[128:131], v[176:179], 0
	v_mfma_f32_16x16x32_bf16 v[12:15], v[116:119], v[184:187], 0
	v_mfma_f32_16x16x32_bf16 v[8:11], v[128:131], v[184:187], 0
	v_mfma_f32_16x16x32_bf16 v[60:63], v[124:127], v[164:167], v[60:63]
	v_mfma_f32_16x16x32_bf16 v[56:59], v[132:135], v[164:167], v[56:59]
	v_mfma_f32_16x16x32_bf16 v[44:47], v[124:127], v[172:175], v[44:47]
	v_mfma_f32_16x16x32_bf16 v[40:43], v[132:135], v[172:175], v[40:43]
	v_mfma_f32_16x16x32_bf16 v[28:31], v[124:127], v[180:183], v[28:31]
	v_mfma_f32_16x16x32_bf16 v[24:27], v[132:135], v[180:183], v[24:27]
	v_mfma_f32_16x16x32_bf16 v[12:15], v[124:127], v[188:191], v[12:15]
	v_mfma_f32_16x16x32_bf16 v[8:11], v[132:135], v[188:191], v[8:11]
	s_setprio 0
	s_setprio 1
	v_mfma_f32_16x16x32_bf16 v[52:55], v[144:147], v[160:163], 0
	v_mfma_f32_16x16x32_bf16 v[48:51], v[152:155], v[160:163], 0
	v_mfma_f32_16x16x32_bf16 v[36:39], v[144:147], v[168:171], 0
	v_mfma_f32_16x16x32_bf16 v[32:35], v[152:155], v[168:171], 0
	v_mfma_f32_16x16x32_bf16 v[20:23], v[144:147], v[176:179], 0
	v_mfma_f32_16x16x32_bf16 v[16:19], v[152:155], v[176:179], 0
	v_mfma_f32_16x16x32_bf16 v[4:7], v[144:147], v[184:187], 0
	v_mfma_f32_16x16x32_bf16 v[0:3], v[152:155], v[184:187], 0
	v_mfma_f32_16x16x32_bf16 v[52:55], v[148:151], v[164:167], v[52:55]
	v_mfma_f32_16x16x32_bf16 v[48:51], v[156:159], v[164:167], v[48:51]
	v_mfma_f32_16x16x32_bf16 v[36:39], v[148:151], v[172:175], v[36:39]
	v_mfma_f32_16x16x32_bf16 v[32:35], v[156:159], v[172:175], v[32:35]
	v_mfma_f32_16x16x32_bf16 v[20:23], v[148:151], v[180:183], v[20:23]
	v_mfma_f32_16x16x32_bf16 v[16:19], v[156:159], v[180:183], v[16:19]
	v_mfma_f32_16x16x32_bf16 v[4:7], v[148:151], v[188:191], v[4:7]
	v_mfma_f32_16x16x32_bf16 v[0:3], v[156:159], v[188:191], v[0:3]
	s_setprio 0
	s_barrier
	s_mov_b32 s101, 0
	s_branch .Lmy_mid_1559

; #define PG8_STAGE(bufoff, gbase, voff) do { _Pragma("unroll") for (int _i = 0; _i < 2; ++_i) \
;         __builtin_amdgcn_global_load_lds((const unsigned*)((const char*)(gbase) + (voff)[_i]), (PG8_LAS unsigned*)(lds + (bufoff) + ldsw + _i * 8192), 16, 0, 0); } while (0)
; #define PG8_LDA(dst, b, h) do { _Pragma("unroll") for (int m = 0; m < 4; ++m) _Pragma("unroll") for (int k = 0; k < 2; ++k) dst[m][k] = *(const PG8_LAS bf16x8*)(lds + PG8_SA(b, h) + aoff + m * 2048 + k * 1024); } while (0)
; #define PG8_LDB(dst, b, h) do { _Pragma("unroll") for (int n = 0; n < 2; ++n) _Pragma("unroll") for (int k = 0; k < 2; ++k) dst[n][k] = *(const PG8_LAS bf16x8*)(lds + PG8_SB(b, h) + boff + n * 2048 + k * 1024); } while (0)
; #define PG8_MMA(ai, bj, At, Bt) do { __builtin_amdgcn_s_setprio(1); _Pragma("unroll") for (int m = 0; m < 4; ++m) _Pragma("unroll") for (int n = 0; n < 2; ++n) _Pragma("unroll") for (int k = 0; k < 2; ++k) \
;         acc[ai][bj][m][n] = __builtin_amdgcn_mfma_f32_16x16x32_bf16(Bt[n][k], At[m][k], acc[ai][bj][m][n], 0, 0, 0); __builtin_amdgcn_s_setprio(0); } while (0)
; #define PG8_WAIT_V(n) asm volatile("s_waitcnt vmcnt(" #n ")" ::: "memory")
; #define PG8_WAIT_L(n) asm volatile("s_waitcnt lgkmcnt(" #n ")" ::: "memory")
; #define PG8_BAR __builtin_amdgcn_s_barrier()
; #define PG8_SCHED __builtin_amdgcn_sched_barrier(0)
; template <class Epi, class Sched, bool ALIGN_EPI = false, bool SP2 = false>
; __device__ __forceinline__ void gemm_phase(PG8_LAS unsigned char* lds, const Gemm g, const Sched& S, const Epi& E, const int tid) {
;     ...
;             PG8_LDB(B0, 0, 0); PG8_LDB(B1, 0, 1); PG8_SCHED; PG8_LDA(At, 0, 0); PG8_STAGE(PG8_SA(1, 1), a1 + hstep, voffA);
;             PG8_WAIT_V(8); PG8_WAIT_L(0); PG8_BAR; PG8_MMA(0, 0, At, B0); PG8_MMA(0, 1, At, B1); PG8_BAR; PG8_SCHED;
;             PG8_LDA(At, 0, 1); PG8_STAGE(PG8_SB(0, 0), b2, voffB); PG8_STAGE(PG8_SB(0, 1), b2 + hstep, voffB); PG8_STAGE(PG8_SA(0, 0), a2, voffA);
;             PG8_WAIT_V(8); PG8_WAIT_L(0); PG8_BAR; PG8_MMA(1, 0, At, B0); PG8_MMA(1, 1, At, B1); PG8_BAR; PG8_SCHED;
.Lmy_nobar_1604:
	s_cmp_eq_u32 s101, 0
	s_cbranch_scc1 .Lmy_strict_1604
	s_add_u32 s34, s30, 0xffe00080
	s_addc_u32 s35, s31, -1
	s_add_i32 s61, 0, 0x10000
	v_add_u32_e32 v140, s61, v161
	v_add_u32_e32 v158, s33, v161
	ds_read_b128 v[128:131], v140
	ds_read_b128 v[132:135], v140 offset:1024
	ds_read_b128 v[136:139], v140 offset:2048
	ds_read_b128 v[140:143], v140 offset:3072
	ds_read_b128 v[154:157], v158
	ds_read_b128 v[164:167], v158 offset:1024
	ds_read_b128 v[168:171], v158 offset:2048
	ds_read_b128 v[172:175], v158 offset:3072
	s_cmpk_eq_i32 s60, 0x7c
	s_cselect_b32 s37, s23, s35
	s_cselect_b32 s36, s56, s34
	s_cselect_b32 s35, s21, s59
	s_cselect_b32 s34, s57, s58
	v_lshl_add_u64 v[158:159], s[30:31], 0, v[150:151]
	s_add_i32 m0, s29, 0xc000
	ds_read_b128 v[176:179], v163
	ds_read_b128 v[180:183], v163 offset:1024
	ds_read_b128 v[184:187], v163 offset:2048
	ds_read_b128 v[188:191], v163 offset:3072
	ds_read_b128 v[192:195], v163 offset:4096
	ds_read_b128 v[196:199], v163 offset:5120
	ds_read_b128 v[200:203], v163 offset:6144
	ds_read_b128 v[204:207], v163 offset:7168
	global_load_lds_dwordx4 v[158:159], off
	v_lshl_add_u64 v[158:159], s[30:31], 0, v[152:153]
	s_add_i32 m0, s29, 0xe000
	s_nop 0
	global_load_lds_dwordx4 v[158:159], off
	s_waitcnt lgkmcnt(0)
	s_barrier
	s_setprio 1
	s_waitcnt lgkmcnt(0)
	v_mfma_f32_16x16x32_bf16 v[124:127], v[128:131], v[176:179], 0
	v_mfma_f32_16x16x32_bf16 v[120:123], v[136:139], v[176:179], 0
	v_mfma_f32_16x16x32_bf16 v[116:119], v[128:131], v[184:187], 0
	v_mfma_f32_16x16x32_bf16 v[112:115], v[136:139], v[184:187], 0
	v_mfma_f32_16x16x32_bf16 v[108:111], v[128:131], v[192:195], 0
	v_mfma_f32_16x16x32_bf16 v[100:103], v[136:139], v[192:195], 0
	v_mfma_f32_16x16x32_bf16 v[92:95], v[128:131], v[200:203], 0
	v_mfma_f32_16x16x32_bf16 v[72:75], v[136:139], v[200:203], 0
	v_mfma_f32_16x16x32_bf16 v[124:127], v[132:135], v[180:183], v[124:127]
	v_mfma_f32_16x16x32_bf16 v[120:123], v[140:143], v[180:183], v[120:123]
	v_mfma_f32_16x16x32_bf16 v[116:119], v[132:135], v[188:191], v[116:119]
	v_mfma_f32_16x16x32_bf16 v[112:115], v[140:143], v[188:191], v[112:115]
	v_mfma_f32_16x16x32_bf16 v[108:111], v[132:135], v[196:199], v[108:111]
	v_mfma_f32_16x16x32_bf16 v[100:103], v[140:143], v[196:199], v[100:103]
	v_mfma_f32_16x16x32_bf16 v[92:95], v[132:135], v[204:207], v[92:95]
	v_mfma_f32_16x16x32_bf16 v[72:75], v[140:143], v[204:207], v[72:75]
	s_setprio 0
	s_setprio 1
	v_mfma_f32_16x16x32_bf16 v[104:107], v[154:157], v[176:179], 0
	v_mfma_f32_16x16x32_bf16 v[96:99], v[168:171], v[176:179], 0
	v_mfma_f32_16x16x32_bf16 v[88:91], v[154:157], v[184:187], 0
	v_mfma_f32_16x16x32_bf16 v[84:87], v[168:171], v[184:187], 0
	v_mfma_f32_16x16x32_bf16 v[80:83], v[154:157], v[192:195], 0
	v_mfma_f32_16x16x32_bf16 v[76:79], v[168:171], v[192:195], 0
	v_mfma_f32_16x16x32_bf16 v[68:71], v[154:157], v[200:203], 0
	v_mfma_f32_16x16x32_bf16 v[64:67], v[168:171], v[200:203], 0
	v_mfma_f32_16x16x32_bf16 v[104:107], v[164:167], v[180:183], v[104:107]
	v_mfma_f32_16x16x32_bf16 v[96:99], v[172:175], v[180:183], v[96:99]
	v_mfma_f32_16x16x32_bf16 v[88:91], v[164:167], v[188:191], v[88:91]
	v_mfma_f32_16x16x32_bf16 v[84:87], v[172:175], v[188:191], v[84:87]
	v_mfma_f32_16x16x32_bf16 v[80:83], v[164:167], v[196:199], v[80:83]
	v_mfma_f32_16x16x32_bf16 v[76:79], v[172:175], v[196:199], v[76:79]
	v_mfma_f32_16x16x32_bf16 v[68:71], v[164:167], v[204:207], v[68:71]
	v_mfma_f32_16x16x32_bf16 v[64:67], v[172:175], v[204:207], v[64:67]
	s_setprio 0
	s_barrier
	s_add_i32 s61, s61, s45
	v_lshl_add_u64 v[158:159], s[34:35], 0, v[208:209]
	s_mov_b32 m0, s61
	ds_read_b128 v[176:179], v163 offset:16384
	ds_read_b128 v[180:183], v163 offset:17408
	ds_read_b128 v[184:187], v163 offset:18432
	ds_read_b128 v[188:191], v163 offset:19456
	ds_read_b128 v[192:195], v163 offset:20480
	ds_read_b128 v[196:199], v163 offset:21504
	ds_read_b128 v[200:203], v163 offset:22528
	ds_read_b128 v[204:207], v163 offset:23552
	global_load_lds_dwordx4 v[158:159], off
	s_add_i32 m0, s61, 0x2000
	s_add_u32 s62, s34, 0x200000
	v_lshl_add_u64 v[210:211], s[34:35], 0, v[148:149]
	s_addc_u32 s63, s35, 0
	s_add_i32 s61, s33, s45
	global_load_lds_dwordx4 v[210:211], off
	v_lshl_add_u64 v[212:213], s[62:63], 0, v[208:209]
	s_mov_b32 m0, s61
	v_lshl_add_u64 v[214:215], s[36:37], 0, v[146:147]
	global_load_lds_dwordx4 v[212:213], off
	v_lshl_add_u64 v[212:213], s[62:63], 0, v[148:149]
	s_add_i32 m0, s61, 0x2000
	s_nop 0
	global_load_lds_dwordx4 v[212:213], off
	v_lshl_add_u64 v[212:213], s[36:37], 0, v[144:145]
	s_mov_b32 m0, s29
	s_nop 0
	global_load_lds_dwordx4 v[212:213], off
	s_mov_b32 m0, s46
	s_nop 0
	global_load_lds_dwordx4 v[214:215], off
	s_waitcnt lgkmcnt(0)
	s_barrier
	s_setprio 1
	s_waitcnt lgkmcnt(0)
	v_mfma_f32_16x16x32_bf16 v[60:63], v[128:131], v[176:179], 0
	v_mfma_f32_16x16x32_bf16 v[56:59], v[136:139], v[176:179], 0
	v_mfma_f32_16x16x32_bf16 v[52:55], v[128:131], v[184:187], 0
	v_mfma_f32_16x16x32_bf16 v[48:51], v[136:139], v[184:187], 0
	v_mfma_f32_16x16x32_bf16 v[44:47], v[128:131], v[192:195], 0
	v_mfma_f32_16x16x32_bf16 v[36:39], v[136:139], v[192:195], 0
	v_mfma_f32_16x16x32_bf16 v[20:23], v[128:131], v[200:203], 0
	v_mfma_f32_16x16x32_bf16 v[8:11], v[136:139], v[200:203], 0
	v_mfma_f32_16x16x32_bf16 v[60:63], v[132:135], v[180:183], v[60:63]
	v_mfma_f32_16x16x32_bf16 v[56:59], v[140:143], v[180:183], v[56:59]
	v_mfma_f32_16x16x32_bf16 v[52:55], v[132:135], v[188:191], v[52:55]
	v_mfma_f32_16x16x32_bf16 v[48:51], v[140:143], v[188:191], v[48:51]
	v_mfma_f32_16x16x32_bf16 v[44:47], v[132:135], v[196:199], v[44:47]
	v_mfma_f32_16x16x32_bf16 v[36:39], v[140:143], v[196:199], v[36:39]
	v_mfma_f32_16x16x32_bf16 v[20:23], v[132:135], v[204:207], v[20:23]
	v_mfma_f32_16x16x32_bf16 v[8:11], v[140:143], v[204:207], v[8:11]
	s_setprio 0
	s_setprio 1
	v_mfma_f32_16x16x32_bf16 v[40:43], v[154:157], v[176:179], 0
	v_mfma_f32_16x16x32_bf16 v[32:35], v[168:171], v[176:179], 0
	v_mfma_f32_16x16x32_bf16 v[28:31], v[154:157], v[184:187], 0
	v_mfma_f32_16x16x32_bf16 v[24:27], v[168:171], v[184:187], 0
	v_mfma_f32_16x16x32_bf16 v[16:19], v[154:157], v[192:195], 0
	v_mfma_f32_16x16x32_bf16 v[12:15], v[168:171], v[192:195], 0
	v_mfma_f32_16x16x32_bf16 v[4:7], v[154:157], v[200:203], 0
	v_mfma_f32_16x16x32_bf16 v[0:3], v[168:171], v[200:203], 0
	v_mfma_f32_16x16x32_bf16 v[40:43], v[164:167], v[180:183], v[40:43]
	v_mfma_f32_16x16x32_bf16 v[32:35], v[172:175], v[180:183], v[32:35]
	v_mfma_f32_16x16x32_bf16 v[28:31], v[164:167], v[188:191], v[28:31]
	v_mfma_f32_16x16x32_bf16 v[24:27], v[172:175], v[188:191], v[24:27]
	v_mfma_f32_16x16x32_bf16 v[16:19], v[164:167], v[196:199], v[16:19]
	v_mfma_f32_16x16x32_bf16 v[12:15], v[172:175], v[196:199], v[12:15]
	v_mfma_f32_16x16x32_bf16 v[4:7], v[164:167], v[204:207], v[4:7]
	v_mfma_f32_16x16x32_bf16 v[0:3], v[172:175], v[204:207], v[0:3]
	s_setprio 0
	s_barrier
	s_mov_b32 s101, 0
	s_branch .Lmy_mid_1604

;     __device__ __forceinline__ void operator()(const f32x4 (&acc)[2][2][4][2], const Unit& un, int wr, int wc, int fr, int fq) const {
;     ...
;         for (int ai = 0; ai < 2; ++ai) {
;             f32x4 xa[4][2][2];
; #pragma unroll
;             for (int m = 0; m < 4; ++m)
; #pragma unroll
;                 for (int bj = 0; bj < 2; ++bj) { const float* sp = src + (size_t)(rbase + ai * 128 + m * 16 - radj) * D + cw + bj * 128; xa[m][bj][0] = *(const f32x4*)sp; xa[m][bj][1] = *(const f32x4*)(sp + 4); }
; #pragma unroll
;             for (int m = 0; m < 4; ++m)
; #pragma unroll
;                 for (int bj = 0; bj < 2; ++bj) { float* dp = dst + (size_t)(rbase + ai * 128 + m * 16 - radj) * D + cw + bj * 128;
;                     *(f32x4*)dp = xa[m][bj][0] + g0[bj] * acc[ai][bj][m][0]; *(f32x4*)(dp + 4) = xa[m][bj][1] + g1[bj] * acc[ai][bj][m][1]; } }
.LBB0_1610:
	s_lshl_b32 s23, s28, 8
	s_lshl_b64 s[36:37], s[36:37], 2
	s_add_u32 s36, s49, s36
	v_lshl_or_b32 v128, s55, 8, v162
	s_addc_u32 s37, s50, s37
	s_add_i32 s21, s21, s23
	v_ashrrev_i32_e32 v129, 31, v128
	v_add_u32_e32 v158, s21, v160
	v_lshlrev_b64 v[154:155], 2, v[128:129]
	v_ashrrev_i32_e32 v159, 31, v158
	v_or_b32_e32 v180, 16, v158
	v_or_b32_e32 v196, 32, v158
	v_or_b32_e32 v218, 48, v158
	v_lshl_add_u64 v[156:157], s[34:35], 0, v[154:155]
	v_lshlrev_b64 v[210:211], 13, v[158:159]
	v_ashrrev_i32_e32 v181, 31, v180
	v_ashrrev_i32_e32 v197, 31, v196
	v_ashrrev_i32_e32 v219, 31, v218
	v_lshl_add_u64 v[128:129], s[36:37], 0, v[154:155]
	v_lshl_add_u64 v[176:177], v[156:157], 0, v[210:211]
	v_lshlrev_b64 v[212:213], 13, v[180:181]
	v_lshlrev_b64 v[234:235], 13, v[196:197]
	v_lshlrev_b64 v[236:237], 13, v[218:219]
	global_load_dwordx4 v[164:167], v[176:177], off
	global_load_dwordx4 v[140:143], v[128:129], off
	global_load_dwordx4 v[136:139], v[128:129], off offset:16
	global_load_dwordx4 v[168:171], v[176:177], off offset:16
	global_load_dwordx4 v[172:175], v[176:177], off offset:512
	global_load_dwordx4 v[132:135], v[128:129], off offset:512
	s_nop 0
	global_load_dwordx4 v[128:131], v[128:129], off offset:528
	s_nop 0
	global_load_dwordx4 v[176:179], v[176:177], off offset:528
	v_lshl_add_u64 v[192:193], v[156:157], 0, v[212:213]
	v_lshl_add_u64 v[214:215], v[156:157], 0, v[234:235]
	v_lshl_add_u64 v[230:231], v[156:157], 0, v[236:237]
	global_load_dwordx4 v[180:183], v[192:193], off
	global_load_dwordx4 v[184:187], v[192:193], off offset:16
	global_load_dwordx4 v[188:191], v[192:193], off offset:528
	s_nop 0
	global_load_dwordx4 v[192:195], v[192:193], off offset:512
	s_nop 0
	global_load_dwordx4 v[196:199], v[214:215], off
	global_load_dwordx4 v[200:203], v[214:215], off offset:16
	global_load_dwordx4 v[204:207], v[214:215], off offset:528
	s_nop 0
	global_load_dwordx4 v[214:217], v[214:215], off offset:512
	s_nop 0
	global_load_dwordx4 v[218:221], v[230:231], off
	global_load_dwordx4 v[222:225], v[230:231], off offset:16
	global_load_dwordx4 v[226:229], v[230:231], off offset:512
	s_nop 0
	global_load_dwordx4 v[230:233], v[230:231], off offset:528
	v_lshl_add_u64 v[154:155], s[30:31], 0, v[154:155]
	v_lshl_add_u64 v[210:211], v[154:155], 0, v[210:211]
	v_lshl_add_u64 v[212:213], v[154:155], 0, v[212:213]
	v_lshl_add_u64 v[236:237], v[154:155], 0, v[236:237]
	v_lshl_add_u64 v[234:235], v[154:155], 0, v[234:235]
	s_andn2_b64 vcc, exec, s[0:1]
	s_mov_b64 s[0:1], -1
	s_waitcnt vmcnt(0)
	v_pk_fma_f32 v[126:127], v[126:127], v[142:143], v[166:167]
	v_pk_fma_f32 v[124:125], v[124:125], v[140:141], v[164:165]
	v_pk_fma_f32 v[122:123], v[122:123], v[138:139], v[170:171]
	v_pk_fma_f32 v[120:121], v[120:121], v[136:137], v[168:169]
	v_pk_fma_f32 v[106:107], v[106:107], v[134:135], v[174:175]
	v_pk_fma_f32 v[104:105], v[104:105], v[132:133], v[172:173]
	v_pk_fma_f32 v[98:99], v[98:99], v[130:131], v[178:179]
	v_pk_fma_f32 v[96:97], v[96:97], v[128:129], v[176:177]
	global_store_dwordx4 v[210:211], v[124:127], off
	global_store_dwordx4 v[210:211], v[120:123], off offset:16
	global_store_dwordx4 v[210:211], v[104:107], off offset:512
	global_store_dwordx4 v[210:211], v[96:99], off offset:528
	v_pk_fma_f32 v[86:87], v[86:87], v[130:131], v[190:191]
	v_pk_fma_f32 v[106:107], v[114:115], v[138:139], v[186:187]
	v_pk_fma_f32 v[98:99], v[118:119], v[142:143], v[182:183]
	v_pk_fma_f32 v[96:97], v[116:117], v[140:141], v[180:181]
	v_pk_fma_f32 v[80:81], v[80:81], v[132:133], v[214:215]
	v_pk_fma_f32 v[66:67], v[66:67], v[130:131], v[232:233]
	v_pk_fma_f32 v[64:65], v[64:65], v[128:129], v[230:231]
	v_pk_fma_f32 v[104:105], v[112:113], v[136:137], v[184:185]
	v_pk_fma_f32 v[90:91], v[90:91], v[134:135], v[194:195]
	v_pk_fma_f32 v[88:89], v[88:89], v[132:133], v[192:193]
	v_pk_fma_f32 v[84:85], v[84:85], v[128:129], v[188:189]
	v_pk_fma_f32 v[110:111], v[110:111], v[142:143], v[198:199]
	v_pk_fma_f32 v[108:109], v[108:109], v[140:141], v[196:197]
	v_pk_fma_f32 v[102:103], v[102:103], v[138:139], v[202:203]
	v_pk_fma_f32 v[100:101], v[100:101], v[136:137], v[200:201]
	v_pk_fma_f32 v[82:83], v[82:83], v[134:135], v[216:217]
	v_pk_fma_f32 v[78:79], v[78:79], v[130:131], v[206:207]
	v_pk_fma_f32 v[76:77], v[76:77], v[128:129], v[204:205]
	v_pk_fma_f32 v[94:95], v[94:95], v[142:143], v[220:221]
	v_pk_fma_f32 v[92:93], v[92:93], v[140:141], v[218:219]
	global_store_dwordx4 v[212:213], v[96:99], off
	global_store_dwordx4 v[212:213], v[104:107], off offset:16
	global_store_dwordx4 v[212:213], v[88:91], off offset:512
	global_store_dwordx4 v[212:213], v[84:87], off offset:528
	global_store_dwordx4 v[234:235], v[108:111], off
	global_store_dwordx4 v[234:235], v[100:103], off offset:16
	global_store_dwordx4 v[234:235], v[80:83], off offset:512
	global_store_dwordx4 v[234:235], v[76:79], off offset:528
	global_store_dwordx4 v[236:237], v[92:95], off
	global_store_dwordx4 v[236:237], v[64:67], off offset:528
	v_add_u32_e32 v80, 0x90, v158
; template <class Epi, class Sched, bool ALIGN_EPI = false, bool SP2 = false>
; __device__ __forceinline__ void gemm_phase(PG8_LAS unsigned char* lds, const Gemm g, const Sched& S, const Epi& E, const int tid) {
;     ...
;         if constexpr (!Epi::AFTER_DRAIN) { E(acc, cur, wr, wc, fr, fq); S.done(cur); }
;         if (!has_next) break;
; #pragma unroll
;         for (int a = 0; a < 2; ++a)
; #pragma unroll
;             for (int b = 0; b < 2; ++b)
; #pragma unroll
;                 for (int m = 0; m < 4; ++m)
; #pragma unroll
;                     for (int n = 0; n < 2; ++n) acc[a][b][m][n] = (f32x4){0.f, 0.f, 0.f, 0.f};
;         cur = nxt; cA = nA; cB = nB; ++ui;
;     __device__ __forceinline__ void operator()(const f32x4 (&acc)[2][2][4][2], const Unit& un, int wr, int wc, int fr, int fq) const {
;     ...
; #pragma unroll
;             for (int m = 0; m < 4; ++m)
; #pragma unroll
;                 for (int bj = 0; bj < 2; ++bj) { float* dp = dst + (size_t)(rbase + ai * 128 + m * 16 - radj) * D + cw + bj * 128;
;                     *(f32x4*)dp = xa[m][bj][0] + g0[bj] * acc[ai][bj][m][0]; *(f32x4*)(dp + 4) = xa[m][bj][1] + g1[bj] * acc[ai][bj][m][1]; } }
	v_add_u32_e32 v96, 0xa0, v158
	v_add_u32_e32 v64, 0x80, v158
	v_add_u32_e32 v112, 0xb0, v158
	v_ashrrev_i32_e32 v65, 31, v64
	v_ashrrev_i32_e32 v81, 31, v80
	v_ashrrev_i32_e32 v97, 31, v96
	v_ashrrev_i32_e32 v113, 31, v112
	v_pk_fma_f32 v[74:75], v[74:75], v[138:139], v[224:225]
	v_pk_fma_f32 v[72:73], v[72:73], v[136:137], v[222:223]
	v_pk_fma_f32 v[70:71], v[70:71], v[134:135], v[228:229]
	v_pk_fma_f32 v[68:69], v[68:69], v[132:133], v[226:227]
	v_lshlrev_b64 v[164:165], 13, v[64:65]
	v_lshlrev_b64 v[166:167], 13, v[80:81]
	v_lshlrev_b64 v[168:169], 13, v[96:97]
	v_lshlrev_b64 v[158:159], 13, v[112:113]
	global_store_dwordx4 v[236:237], v[72:75], off offset:16
	global_store_dwordx4 v[236:237], v[68:71], off offset:512
	v_lshl_add_u64 v[76:77], v[156:157], 0, v[164:165]
	v_lshl_add_u64 v[92:93], v[156:157], 0, v[166:167]
	v_lshl_add_u64 v[108:109], v[156:157], 0, v[168:169]
	v_lshl_add_u64 v[124:125], v[156:157], 0, v[158:159]
	global_load_dwordx4 v[64:67], v[76:77], off
	global_load_dwordx4 v[68:71], v[76:77], off offset:16
	global_load_dwordx4 v[72:75], v[76:77], off offset:528
	s_nop 0
	global_load_dwordx4 v[76:79], v[76:77], off offset:512
	s_nop 0
	global_load_dwordx4 v[80:83], v[92:93], off
	global_load_dwordx4 v[84:87], v[92:93], off offset:16
	global_load_dwordx4 v[88:91], v[92:93], off offset:528
	s_nop 0
	global_load_dwordx4 v[92:95], v[92:93], off offset:512
	s_nop 0
	global_load_dwordx4 v[96:99], v[108:109], off
	global_load_dwordx4 v[100:103], v[108:109], off offset:16
	global_load_dwordx4 v[104:107], v[108:109], off offset:528
	s_nop 0
	global_load_dwordx4 v[108:111], v[108:109], off offset:512
	s_nop 0
	global_load_dwordx4 v[112:115], v[124:125], off
	global_load_dwordx4 v[116:119], v[124:125], off offset:16
	global_load_dwordx4 v[120:123], v[124:125], off offset:512
	s_nop 0
	global_load_dwordx4 v[124:127], v[124:125], off offset:528
	v_lshl_add_u64 v[156:157], v[154:155], 0, v[164:165]
	v_lshl_add_u64 v[164:165], v[154:155], 0, v[166:167]
	v_lshl_add_u64 v[166:167], v[154:155], 0, v[168:169]
	v_lshl_add_u64 v[154:155], v[154:155], 0, v[158:159]
	s_waitcnt vmcnt(15)
	v_pk_fma_f32 v[62:63], v[62:63], v[142:143], v[66:67]
	v_pk_fma_f32 v[60:61], v[60:61], v[140:141], v[64:65]
	s_waitcnt vmcnt(14)
	v_pk_fma_f32 v[58:59], v[58:59], v[138:139], v[70:71]
	s_waitcnt vmcnt(3)
	v_pk_fma_f32 v[22:23], v[22:23], v[142:143], v[114:115]
	v_pk_fma_f32 v[20:21], v[20:21], v[140:141], v[112:113]
	s_waitcnt vmcnt(2)
	v_pk_fma_f32 v[10:11], v[10:11], v[138:139], v[118:119]
	v_pk_fma_f32 v[8:9], v[8:9], v[136:137], v[116:117]
	s_waitcnt vmcnt(1)
	v_pk_fma_f32 v[6:7], v[6:7], v[134:135], v[122:123]
	v_pk_fma_f32 v[4:5], v[4:5], v[132:133], v[120:121]
	s_waitcnt vmcnt(0)
	v_pk_fma_f32 v[2:3], v[2:3], v[130:131], v[126:127]
	v_pk_fma_f32 v[0:1], v[0:1], v[128:129], v[124:125]
	v_pk_fma_f32 v[56:57], v[56:57], v[136:137], v[68:69]
	v_pk_fma_f32 v[42:43], v[42:43], v[134:135], v[78:79]
	v_pk_fma_f32 v[40:41], v[40:41], v[132:133], v[76:77]
	v_pk_fma_f32 v[34:35], v[34:35], v[130:131], v[74:75]
	v_pk_fma_f32 v[32:33], v[32:33], v[128:129], v[72:73]
	v_pk_fma_f32 v[54:55], v[54:55], v[142:143], v[82:83]
	v_pk_fma_f32 v[52:53], v[52:53], v[140:141], v[80:81]
	v_pk_fma_f32 v[50:51], v[50:51], v[138:139], v[86:87]
	v_pk_fma_f32 v[48:49], v[48:49], v[136:137], v[84:85]
	v_pk_fma_f32 v[30:31], v[30:31], v[134:135], v[94:95]
	v_pk_fma_f32 v[28:29], v[28:29], v[132:133], v[92:93]
	v_pk_fma_f32 v[26:27], v[26:27], v[130:131], v[90:91]
	v_pk_fma_f32 v[24:25], v[24:25], v[128:129], v[88:89]
	v_pk_fma_f32 v[46:47], v[46:47], v[142:143], v[98:99]
	v_pk_fma_f32 v[44:45], v[44:45], v[140:141], v[96:97]
	v_pk_fma_f32 v[38:39], v[38:39], v[138:139], v[102:103]
	v_pk_fma_f32 v[36:37], v[36:37], v[136:137], v[100:101]
	v_pk_fma_f32 v[18:19], v[18:19], v[134:135], v[110:111]
	v_pk_fma_f32 v[16:17], v[16:17], v[132:133], v[108:109]
	v_pk_fma_f32 v[14:15], v[14:15], v[130:131], v[106:107]
	v_pk_fma_f32 v[12:13], v[12:13], v[128:129], v[104:105]
	global_store_dwordx4 v[156:157], v[60:63], off
	global_store_dwordx4 v[156:157], v[56:59], off offset:16
	global_store_dwordx4 v[156:157], v[40:43], off offset:512
	global_store_dwordx4 v[156:157], v[32:35], off offset:528
	global_store_dwordx4 v[164:165], v[52:55], off
	global_store_dwordx4 v[164:165], v[48:51], off offset:16
	global_store_dwordx4 v[164:165], v[28:31], off offset:512
	global_store_dwordx4 v[164:165], v[24:27], off offset:528
	global_store_dwordx4 v[166:167], v[44:47], off
	global_store_dwordx4 v[166:167], v[36:39], off offset:16
	global_store_dwordx4 v[166:167], v[16:19], off offset:512
	global_store_dwordx4 v[166:167], v[12:15], off offset:528
	global_store_dwordx4 v[154:155], v[20:23], off
	global_store_dwordx4 v[154:155], v[8:11], off offset:16
	global_store_dwordx4 v[154:155], v[4:7], off offset:512
	global_store_dwordx4 v[154:155], v[0:3], off offset:528
	s_cbranch_vccnz .LBB0_1596
	s_mov_b32 s101, 1
	s_andn2_b64 vcc, exec, s[16:17]
	s_cbranch_vccnz .LBB0_1595
	s_mov_b32 s100, 1
	s_branch .LBB0_1595
